# GEMM epilogue output stores (in-proj Z/QFK, branch, out-proj residual, FFN-in) carry the nontemporal hint: streamed outputs stop displacing operands in L2
# baseline (speedup 1.0000x reference)
.LBB0_217:
	v_or_b32_e32 v173, s41, v165
	v_add_u32_e32 v172, 0xf00, v170
	v_add_lshl_u32 v172, v172, v173, 1
	v_lshlrev_b32_e32 v174, 11, v169
	v_lshl_add_u32 v174, v173, 1, v174
	s_andn2_b64 vcc, exec, s[38:39]
	s_mov_b64 s[10:11], -1
	global_load_dwordx4 v[132:135], v172, s[4:5]
	global_load_dwordx4 v[136:139], v172, s[4:5] offset:256
	v_add_u32_e32 v172, 0x26000, v172
	global_load_dwordx4 v[190:193], v172, s[4:5]
	global_load_dwordx4 v[194:197], v172, s[4:5] offset:256
	v_add_u32_e32 v172, 0x26000, v172
	global_load_dwordx4 v[198:201], v172, s[4:5]
	global_load_dwordx4 v[202:205], v172, s[4:5] offset:256
	v_add_u32_e32 v172, 0x26000, v172
	global_load_dwordx4 v[206:209], v172, s[4:5]
	global_load_dwordx4 v[210:213], v172, s[4:5] offset:256
	v_add_u32_e32 v172, 0xbe000, v172
	global_load_dwordx4 v[214:217], v172, s[4:5]
	global_load_dwordx4 v[218:221], v172, s[4:5] offset:256
	v_add_u32_e32 v172, 0x26000, v172
	global_load_dwordx4 v[222:225], v172, s[4:5]
	global_load_dwordx4 v[226:229], v172, s[4:5] offset:256
	v_add_u32_e32 v172, 0x26000, v172
	global_load_dwordx4 v[230:233], v172, s[4:5]
	global_load_dwordx4 v[234:237], v172, s[4:5] offset:256
	v_add_u32_e32 v172, 0x26000, v172
	global_load_dwordx4 v[238:241], v172, s[4:5]
	global_load_dwordx4 v[242:245], v172, s[4:5] offset:256
	s_waitcnt vmcnt(15)
	v_lshlrev_b32_e32 v246, 16, v132
	v_and_b32_e32 v247, 0xffff0000, v132
	v_lshlrev_b32_e32 v248, 16, v133
	v_and_b32_e32 v249, 0xffff0000, v133
	v_lshlrev_b32_e32 v250, 16, v134
	v_and_b32_e32 v251, 0xffff0000, v134
	v_lshlrev_b32_e32 v152, 16, v135
	v_and_b32_e32 v153, 0xffff0000, v135
	v_pk_mul_f32 v[128:129], v[128:129], v[246:247]
	v_pk_mul_f32 v[130:131], v[130:131], v[248:249]
	v_pk_mul_f32 v[124:125], v[124:125], v[250:251]
	v_pk_mul_f32 v[126:127], v[126:127], v[152:153]
	v_cvt_pk_bf16_f32 v128, v128, v129
	v_cvt_pk_bf16_f32 v129, v130, v131
	v_cvt_pk_bf16_f32 v130, v124, v125
	v_cvt_pk_bf16_f32 v131, v126, v127
	global_store_dwordx4 v174, v[128:131], s[2:3] nt
	s_waitcnt vmcnt(15)
	v_lshlrev_b32_e32 v246, 16, v136
	v_and_b32_e32 v247, 0xffff0000, v136
	v_lshlrev_b32_e32 v248, 16, v137
	v_and_b32_e32 v249, 0xffff0000, v137
	v_lshlrev_b32_e32 v250, 16, v138
	v_and_b32_e32 v251, 0xffff0000, v138
	v_lshlrev_b32_e32 v152, 16, v139
	v_and_b32_e32 v153, 0xffff0000, v139
	v_pk_mul_f32 v[120:121], v[120:121], v[246:247]
	v_pk_mul_f32 v[122:123], v[122:123], v[248:249]
	v_pk_mul_f32 v[116:117], v[116:117], v[250:251]
	v_pk_mul_f32 v[118:119], v[118:119], v[152:153]
	v_cvt_pk_bf16_f32 v120, v120, v121
	v_cvt_pk_bf16_f32 v121, v122, v123
	v_cvt_pk_bf16_f32 v122, v116, v117
	v_cvt_pk_bf16_f32 v123, v118, v119
	global_store_dwordx4 v174, v[120:123], s[2:3] offset:256 nt
	v_add_u32_e32 v174, 0x8000, v174
	s_waitcnt vmcnt(15)
	v_lshlrev_b32_e32 v246, 16, v190
	v_and_b32_e32 v247, 0xffff0000, v190
	v_lshlrev_b32_e32 v248, 16, v191
	v_and_b32_e32 v249, 0xffff0000, v191
	v_lshlrev_b32_e32 v250, 16, v192
	v_and_b32_e32 v251, 0xffff0000, v192
	v_lshlrev_b32_e32 v152, 16, v193
	v_and_b32_e32 v153, 0xffff0000, v193
	v_pk_mul_f32 v[112:113], v[112:113], v[246:247]
	v_pk_mul_f32 v[114:115], v[114:115], v[248:249]
	v_pk_mul_f32 v[108:109], v[108:109], v[250:251]
	v_pk_mul_f32 v[110:111], v[110:111], v[152:153]
	v_cvt_pk_bf16_f32 v112, v112, v113
	v_cvt_pk_bf16_f32 v113, v114, v115
	v_cvt_pk_bf16_f32 v114, v108, v109
	v_cvt_pk_bf16_f32 v115, v110, v111
	global_store_dwordx4 v174, v[112:115], s[2:3] nt
	s_waitcnt vmcnt(15)
	v_lshlrev_b32_e32 v246, 16, v194
	v_and_b32_e32 v247, 0xffff0000, v194
	v_lshlrev_b32_e32 v248, 16, v195
	v_and_b32_e32 v249, 0xffff0000, v195
	v_lshlrev_b32_e32 v250, 16, v196
	v_and_b32_e32 v251, 0xffff0000, v196
	v_lshlrev_b32_e32 v152, 16, v197
	v_and_b32_e32 v153, 0xffff0000, v197
	v_pk_mul_f32 v[104:105], v[104:105], v[246:247]
	v_pk_mul_f32 v[106:107], v[106:107], v[248:249]
	v_pk_mul_f32 v[100:101], v[100:101], v[250:251]
	v_pk_mul_f32 v[102:103], v[102:103], v[152:153]
	v_cvt_pk_bf16_f32 v104, v104, v105
	v_cvt_pk_bf16_f32 v105, v106, v107
	v_cvt_pk_bf16_f32 v106, v100, v101
	v_cvt_pk_bf16_f32 v107, v102, v103
	global_store_dwordx4 v174, v[104:107], s[2:3] offset:256 nt
	v_add_u32_e32 v174, 0x8000, v174
	s_waitcnt vmcnt(15)
	v_lshlrev_b32_e32 v246, 16, v198
	v_and_b32_e32 v247, 0xffff0000, v198
	v_lshlrev_b32_e32 v248, 16, v199
	v_and_b32_e32 v249, 0xffff0000, v199
	v_lshlrev_b32_e32 v250, 16, v200
	v_and_b32_e32 v251, 0xffff0000, v200
	v_lshlrev_b32_e32 v152, 16, v201
	v_and_b32_e32 v153, 0xffff0000, v201
	v_pk_mul_f32 v[96:97], v[96:97], v[246:247]
	v_pk_mul_f32 v[98:99], v[98:99], v[248:249]
	v_pk_mul_f32 v[92:93], v[92:93], v[250:251]
	v_pk_mul_f32 v[94:95], v[94:95], v[152:153]
	v_cvt_pk_bf16_f32 v96, v96, v97
	v_cvt_pk_bf16_f32 v97, v98, v99
	v_cvt_pk_bf16_f32 v98, v92, v93
	v_cvt_pk_bf16_f32 v99, v94, v95
	global_store_dwordx4 v174, v[96:99], s[2:3] nt
	s_waitcnt vmcnt(15)
	v_lshlrev_b32_e32 v246, 16, v202
	v_and_b32_e32 v247, 0xffff0000, v202
	v_lshlrev_b32_e32 v248, 16, v203
	v_and_b32_e32 v249, 0xffff0000, v203
	v_lshlrev_b32_e32 v250, 16, v204
	v_and_b32_e32 v251, 0xffff0000, v204
	v_lshlrev_b32_e32 v152, 16, v205
	v_and_b32_e32 v153, 0xffff0000, v205
	v_pk_mul_f32 v[88:89], v[88:89], v[246:247]
	v_pk_mul_f32 v[90:91], v[90:91], v[248:249]
	v_pk_mul_f32 v[84:85], v[84:85], v[250:251]
	v_pk_mul_f32 v[86:87], v[86:87], v[152:153]
	v_cvt_pk_bf16_f32 v88, v88, v89
	v_cvt_pk_bf16_f32 v89, v90, v91
	v_cvt_pk_bf16_f32 v90, v84, v85
	v_cvt_pk_bf16_f32 v91, v86, v87
	global_store_dwordx4 v174, v[88:91], s[2:3] offset:256 nt
	v_add_u32_e32 v174, 0x8000, v174
	s_waitcnt vmcnt(15)
	v_lshlrev_b32_e32 v246, 16, v206
	v_and_b32_e32 v247, 0xffff0000, v206
	v_lshlrev_b32_e32 v248, 16, v207
	v_and_b32_e32 v249, 0xffff0000, v207
	v_lshlrev_b32_e32 v250, 16, v208
	v_and_b32_e32 v251, 0xffff0000, v208
	v_lshlrev_b32_e32 v152, 16, v209
	v_and_b32_e32 v153, 0xffff0000, v209
	v_pk_mul_f32 v[80:81], v[80:81], v[246:247]
	v_pk_mul_f32 v[82:83], v[82:83], v[248:249]
	v_pk_mul_f32 v[76:77], v[76:77], v[250:251]
	v_pk_mul_f32 v[78:79], v[78:79], v[152:153]
	v_cvt_pk_bf16_f32 v80, v80, v81
	v_cvt_pk_bf16_f32 v81, v82, v83
	v_cvt_pk_bf16_f32 v82, v76, v77
	v_cvt_pk_bf16_f32 v83, v78, v79
	global_store_dwordx4 v174, v[80:83], s[2:3] nt
	s_waitcnt vmcnt(15)
	v_lshlrev_b32_e32 v246, 16, v210
	v_and_b32_e32 v247, 0xffff0000, v210
	v_lshlrev_b32_e32 v248, 16, v211
	v_and_b32_e32 v249, 0xffff0000, v211
	v_lshlrev_b32_e32 v250, 16, v212
	v_and_b32_e32 v251, 0xffff0000, v212
	v_lshlrev_b32_e32 v152, 16, v213
	v_and_b32_e32 v153, 0xffff0000, v213
	v_pk_mul_f32 v[72:73], v[72:73], v[246:247]
	v_pk_mul_f32 v[74:75], v[74:75], v[248:249]
	v_pk_mul_f32 v[68:69], v[68:69], v[250:251]
	v_pk_mul_f32 v[70:71], v[70:71], v[152:153]
	v_cvt_pk_bf16_f32 v72, v72, v73
	v_cvt_pk_bf16_f32 v73, v74, v75
	v_cvt_pk_bf16_f32 v74, v68, v69
	v_cvt_pk_bf16_f32 v75, v70, v71
	global_store_dwordx4 v174, v[72:75], s[2:3] offset:256 nt
	v_add_u32_e32 v174, 0x28000, v174
	s_waitcnt vmcnt(15)
	v_lshlrev_b32_e32 v246, 16, v214
	v_and_b32_e32 v247, 0xffff0000, v214
	v_lshlrev_b32_e32 v248, 16, v215
	v_and_b32_e32 v249, 0xffff0000, v215
	v_lshlrev_b32_e32 v250, 16, v216
	v_and_b32_e32 v251, 0xffff0000, v216
	v_lshlrev_b32_e32 v152, 16, v217
	v_and_b32_e32 v153, 0xffff0000, v217
	v_pk_mul_f32 v[64:65], v[64:65], v[246:247]
	v_pk_mul_f32 v[66:67], v[66:67], v[248:249]
	v_pk_mul_f32 v[60:61], v[60:61], v[250:251]
	v_pk_mul_f32 v[62:63], v[62:63], v[152:153]
	v_cvt_pk_bf16_f32 v64, v64, v65
	v_cvt_pk_bf16_f32 v65, v66, v67
	v_cvt_pk_bf16_f32 v66, v60, v61
	v_cvt_pk_bf16_f32 v67, v62, v63
	global_store_dwordx4 v174, v[64:67], s[2:3] nt
	s_waitcnt vmcnt(15)
	v_lshlrev_b32_e32 v246, 16, v218
	v_and_b32_e32 v247, 0xffff0000, v218
	v_lshlrev_b32_e32 v248, 16, v219
	v_and_b32_e32 v249, 0xffff0000, v219
	v_lshlrev_b32_e32 v250, 16, v220
	v_and_b32_e32 v251, 0xffff0000, v220
	v_lshlrev_b32_e32 v152, 16, v221
	v_and_b32_e32 v153, 0xffff0000, v221
	v_pk_mul_f32 v[56:57], v[56:57], v[246:247]
	v_pk_mul_f32 v[58:59], v[58:59], v[248:249]
	v_pk_mul_f32 v[52:53], v[52:53], v[250:251]
	v_pk_mul_f32 v[54:55], v[54:55], v[152:153]
	v_cvt_pk_bf16_f32 v56, v56, v57
	v_cvt_pk_bf16_f32 v57, v58, v59
	v_cvt_pk_bf16_f32 v58, v52, v53
	v_cvt_pk_bf16_f32 v59, v54, v55
	global_store_dwordx4 v174, v[56:59], s[2:3] offset:256 nt
	v_add_u32_e32 v174, 0x8000, v174
	s_waitcnt vmcnt(15)
	v_lshlrev_b32_e32 v246, 16, v222
	v_and_b32_e32 v247, 0xffff0000, v222
	v_lshlrev_b32_e32 v248, 16, v223
	v_and_b32_e32 v249, 0xffff0000, v223
	v_lshlrev_b32_e32 v250, 16, v224
	v_and_b32_e32 v251, 0xffff0000, v224
	v_lshlrev_b32_e32 v152, 16, v225
	v_and_b32_e32 v153, 0xffff0000, v225
	v_pk_mul_f32 v[48:49], v[48:49], v[246:247]
	v_pk_mul_f32 v[50:51], v[50:51], v[248:249]
	v_pk_mul_f32 v[44:45], v[44:45], v[250:251]
	v_pk_mul_f32 v[46:47], v[46:47], v[152:153]
	v_cvt_pk_bf16_f32 v48, v48, v49
	v_cvt_pk_bf16_f32 v49, v50, v51
	v_cvt_pk_bf16_f32 v50, v44, v45
	v_cvt_pk_bf16_f32 v51, v46, v47
	global_store_dwordx4 v174, v[48:51], s[2:3] nt
	s_waitcnt vmcnt(15)
	v_lshlrev_b32_e32 v246, 16, v226
	v_and_b32_e32 v247, 0xffff0000, v226
	v_lshlrev_b32_e32 v248, 16, v227
	v_and_b32_e32 v249, 0xffff0000, v227
	v_lshlrev_b32_e32 v250, 16, v228
	v_and_b32_e32 v251, 0xffff0000, v228
	v_lshlrev_b32_e32 v152, 16, v229
	v_and_b32_e32 v153, 0xffff0000, v229
	v_pk_mul_f32 v[40:41], v[40:41], v[246:247]
	v_pk_mul_f32 v[42:43], v[42:43], v[248:249]
	v_pk_mul_f32 v[36:37], v[36:37], v[250:251]
	v_pk_mul_f32 v[38:39], v[38:39], v[152:153]
	v_cvt_pk_bf16_f32 v40, v40, v41
	v_cvt_pk_bf16_f32 v41, v42, v43
	v_cvt_pk_bf16_f32 v42, v36, v37
	v_cvt_pk_bf16_f32 v43, v38, v39
	global_store_dwordx4 v174, v[40:43], s[2:3] offset:256 nt
	v_add_u32_e32 v174, 0x8000, v174
	s_waitcnt vmcnt(15)
	v_lshlrev_b32_e32 v246, 16, v230
	v_and_b32_e32 v247, 0xffff0000, v230
	v_lshlrev_b32_e32 v248, 16, v231
	v_and_b32_e32 v249, 0xffff0000, v231
	v_lshlrev_b32_e32 v250, 16, v232
	v_and_b32_e32 v251, 0xffff0000, v232
	v_lshlrev_b32_e32 v152, 16, v233
	v_and_b32_e32 v153, 0xffff0000, v233
	v_pk_mul_f32 v[32:33], v[32:33], v[246:247]
	v_pk_mul_f32 v[34:35], v[34:35], v[248:249]
	v_pk_mul_f32 v[28:29], v[28:29], v[250:251]
	v_pk_mul_f32 v[30:31], v[30:31], v[152:153]
	v_cvt_pk_bf16_f32 v32, v32, v33
	v_cvt_pk_bf16_f32 v33, v34, v35
	v_cvt_pk_bf16_f32 v34, v28, v29
	v_cvt_pk_bf16_f32 v35, v30, v31
	global_store_dwordx4 v174, v[32:35], s[2:3] nt
	s_waitcnt vmcnt(15)
	v_lshlrev_b32_e32 v246, 16, v234
	v_and_b32_e32 v247, 0xffff0000, v234
	v_lshlrev_b32_e32 v248, 16, v235
	v_and_b32_e32 v249, 0xffff0000, v235
	v_lshlrev_b32_e32 v250, 16, v236
	v_and_b32_e32 v251, 0xffff0000, v236
	v_lshlrev_b32_e32 v152, 16, v237
	v_and_b32_e32 v153, 0xffff0000, v237
	v_pk_mul_f32 v[24:25], v[24:25], v[246:247]
	v_pk_mul_f32 v[26:27], v[26:27], v[248:249]
	v_pk_mul_f32 v[20:21], v[20:21], v[250:251]
	v_pk_mul_f32 v[22:23], v[22:23], v[152:153]
	v_cvt_pk_bf16_f32 v24, v24, v25
	v_cvt_pk_bf16_f32 v25, v26, v27
	v_cvt_pk_bf16_f32 v26, v20, v21
	v_cvt_pk_bf16_f32 v27, v22, v23
	global_store_dwordx4 v174, v[24:27], s[2:3] offset:256 nt
	v_add_u32_e32 v174, 0x8000, v174
	s_waitcnt vmcnt(15)
	v_lshlrev_b32_e32 v246, 16, v238
	v_and_b32_e32 v247, 0xffff0000, v238
	v_lshlrev_b32_e32 v248, 16, v239
	v_and_b32_e32 v249, 0xffff0000, v239
	v_lshlrev_b32_e32 v250, 16, v240
	v_and_b32_e32 v251, 0xffff0000, v240
	v_lshlrev_b32_e32 v152, 16, v241
	v_and_b32_e32 v153, 0xffff0000, v241
	v_pk_mul_f32 v[16:17], v[16:17], v[246:247]
	v_pk_mul_f32 v[18:19], v[18:19], v[248:249]
	v_pk_mul_f32 v[12:13], v[12:13], v[250:251]
	v_pk_mul_f32 v[14:15], v[14:15], v[152:153]
	v_cvt_pk_bf16_f32 v16, v16, v17
	v_cvt_pk_bf16_f32 v17, v18, v19
	v_cvt_pk_bf16_f32 v18, v12, v13
	v_cvt_pk_bf16_f32 v19, v14, v15
	global_store_dwordx4 v174, v[16:19], s[2:3] nt
	s_waitcnt vmcnt(15)
	v_lshlrev_b32_e32 v246, 16, v242
	v_and_b32_e32 v247, 0xffff0000, v242
	v_lshlrev_b32_e32 v248, 16, v243
	v_and_b32_e32 v249, 0xffff0000, v243
	v_lshlrev_b32_e32 v250, 16, v244
	v_and_b32_e32 v251, 0xffff0000, v244
	v_lshlrev_b32_e32 v152, 16, v245
	v_and_b32_e32 v153, 0xffff0000, v245
	v_pk_mul_f32 v[8:9], v[8:9], v[246:247]
	v_pk_mul_f32 v[10:11], v[10:11], v[248:249]
	v_pk_mul_f32 v[4:5], v[4:5], v[250:251]
	v_pk_mul_f32 v[6:7], v[6:7], v[152:153]
	v_cvt_pk_bf16_f32 v8, v8, v9
	v_cvt_pk_bf16_f32 v9, v10, v11
	v_cvt_pk_bf16_f32 v10, v4, v5
	v_cvt_pk_bf16_f32 v11, v6, v7
	global_store_dwordx4 v174, v[8:11], s[2:3] offset:256 nt
	s_cbranch_vccnz .LBB0_198
	s_andn2_b64 vcc, exec, s[36:37]
	s_cbranch_vccnz .LBB0_197
	s_barrier
	s_branch .LBB0_197

.Lepi_none:
	v_mul_lo_u32 v152, v195, s30
	v_add_u32_e32 v153, s9, v191
	v_lshl_add_u32 v152, v153, 1, v152
	v_cvt_pk_bf16_f32 v128, v128, v129
	v_cvt_pk_bf16_f32 v129, v130, v131
	v_cvt_pk_bf16_f32 v130, v124, v125
	v_cvt_pk_bf16_f32 v131, v126, v127
	global_store_dwordx4 v152, v[128:131], s[44:45] nt
	v_cvt_pk_bf16_f32 v120, v120, v121
	v_cvt_pk_bf16_f32 v121, v122, v123
	v_cvt_pk_bf16_f32 v122, v116, v117
	v_cvt_pk_bf16_f32 v123, v118, v119
	global_store_dwordx4 v152, v[120:123], s[44:45] offset:256 nt
	v_add_u32_e32 v152, 0x26000, v152
	v_cvt_pk_bf16_f32 v112, v112, v113
	v_cvt_pk_bf16_f32 v113, v114, v115
	v_cvt_pk_bf16_f32 v114, v108, v109
	v_cvt_pk_bf16_f32 v115, v110, v111
	global_store_dwordx4 v152, v[112:115], s[44:45] nt
	v_cvt_pk_bf16_f32 v104, v104, v105
	v_cvt_pk_bf16_f32 v105, v106, v107
	v_cvt_pk_bf16_f32 v106, v100, v101
	v_cvt_pk_bf16_f32 v107, v102, v103
	global_store_dwordx4 v152, v[104:107], s[44:45] offset:256 nt
	v_add_u32_e32 v152, 0x26000, v152
	v_cvt_pk_bf16_f32 v96, v96, v97
	v_cvt_pk_bf16_f32 v97, v98, v99
	v_cvt_pk_bf16_f32 v98, v92, v93
	v_cvt_pk_bf16_f32 v99, v94, v95
	global_store_dwordx4 v152, v[96:99], s[44:45] nt
	v_cvt_pk_bf16_f32 v88, v88, v89
	v_cvt_pk_bf16_f32 v89, v90, v91
	v_cvt_pk_bf16_f32 v90, v84, v85
	v_cvt_pk_bf16_f32 v91, v86, v87
	global_store_dwordx4 v152, v[88:91], s[44:45] offset:256 nt
	v_add_u32_e32 v152, 0x26000, v152
	v_cvt_pk_bf16_f32 v80, v80, v81
	v_cvt_pk_bf16_f32 v81, v82, v83
	v_cvt_pk_bf16_f32 v82, v76, v77
	v_cvt_pk_bf16_f32 v83, v78, v79
	global_store_dwordx4 v152, v[80:83], s[44:45] nt
	v_cvt_pk_bf16_f32 v72, v72, v73
	v_cvt_pk_bf16_f32 v73, v74, v75
	v_cvt_pk_bf16_f32 v74, v68, v69
	v_cvt_pk_bf16_f32 v75, v70, v71
	global_store_dwordx4 v152, v[72:75], s[44:45] offset:256 nt
	v_add_u32_e32 v152, 0xbe000, v152
	v_cvt_pk_bf16_f32 v64, v64, v65
	v_cvt_pk_bf16_f32 v65, v66, v67
	v_cvt_pk_bf16_f32 v66, v60, v61
	v_cvt_pk_bf16_f32 v67, v62, v63
	global_store_dwordx4 v152, v[64:67], s[44:45] nt
	v_cvt_pk_bf16_f32 v56, v56, v57
	v_cvt_pk_bf16_f32 v57, v58, v59
	v_cvt_pk_bf16_f32 v58, v52, v53
	v_cvt_pk_bf16_f32 v59, v54, v55
	global_store_dwordx4 v152, v[56:59], s[44:45] offset:256 nt
	v_add_u32_e32 v152, 0x26000, v152
	v_cvt_pk_bf16_f32 v48, v48, v49
	v_cvt_pk_bf16_f32 v49, v50, v51
	v_cvt_pk_bf16_f32 v50, v44, v45
	v_cvt_pk_bf16_f32 v51, v46, v47
	global_store_dwordx4 v152, v[48:51], s[44:45] nt
	v_cvt_pk_bf16_f32 v40, v40, v41
	v_cvt_pk_bf16_f32 v41, v42, v43
	v_cvt_pk_bf16_f32 v42, v36, v37
	v_cvt_pk_bf16_f32 v43, v38, v39
	global_store_dwordx4 v152, v[40:43], s[44:45] offset:256 nt
	v_add_u32_e32 v152, 0x26000, v152
	v_cvt_pk_bf16_f32 v32, v32, v33
	v_cvt_pk_bf16_f32 v33, v34, v35
	v_cvt_pk_bf16_f32 v34, v28, v29
	v_cvt_pk_bf16_f32 v35, v30, v31
	global_store_dwordx4 v152, v[32:35], s[44:45] nt
	v_cvt_pk_bf16_f32 v24, v24, v25
	v_cvt_pk_bf16_f32 v25, v26, v27
	v_cvt_pk_bf16_f32 v26, v20, v21
	v_cvt_pk_bf16_f32 v27, v22, v23
	global_store_dwordx4 v152, v[24:27], s[44:45] offset:256 nt
	v_add_u32_e32 v152, 0x26000, v152
	v_cvt_pk_bf16_f32 v16, v16, v17
	v_cvt_pk_bf16_f32 v17, v18, v19
	v_cvt_pk_bf16_f32 v18, v12, v13
	v_cvt_pk_bf16_f32 v19, v14, v15
	global_store_dwordx4 v152, v[16:19], s[44:45] nt
	v_cvt_pk_bf16_f32 v8, v8, v9
	v_cvt_pk_bf16_f32 v9, v10, v11
	v_cvt_pk_bf16_f32 v10, v4, v5
	v_cvt_pk_bf16_f32 v11, v6, v7
	global_store_dwordx4 v152, v[8:11], s[44:45] offset:256 nt
	s_branch .LBB0_590
.Lepi_silu:
	v_mul_lo_u32 v152, v195, s30
	v_add_u32_e32 v153, s9, v191
	v_lshl_add_u32 v152, v153, 1, v152
	v_mul_f32_e32 v164, 0xbfb8aa3b, v128
	v_mul_f32_e32 v165, 0xbfb8aa3b, v129
	v_mul_f32_e32 v166, 0xbfb8aa3b, v130
	v_mul_f32_e32 v167, 0xbfb8aa3b, v131
	v_mul_f32_e32 v168, 0xbfb8aa3b, v124
	v_mul_f32_e32 v169, 0xbfb8aa3b, v125
	v_mul_f32_e32 v170, 0xbfb8aa3b, v126
	v_mul_f32_e32 v171, 0xbfb8aa3b, v127
	v_exp_f32_e32 v164, v164
	v_exp_f32_e32 v165, v165
	v_exp_f32_e32 v166, v166
	v_exp_f32_e32 v167, v167
	v_exp_f32_e32 v168, v168
	v_exp_f32_e32 v169, v169
	v_exp_f32_e32 v170, v170
	v_exp_f32_e32 v171, v171
	v_add_f32_e32 v164, 1.0, v164
	v_add_f32_e32 v165, 1.0, v165
	v_add_f32_e32 v166, 1.0, v166
	v_add_f32_e32 v167, 1.0, v167
	v_add_f32_e32 v168, 1.0, v168
	v_add_f32_e32 v169, 1.0, v169
	v_add_f32_e32 v170, 1.0, v170
	v_add_f32_e32 v171, 1.0, v171
	v_rcp_f32_e32 v164, v164
	v_rcp_f32_e32 v165, v165
	v_rcp_f32_e32 v166, v166
	v_rcp_f32_e32 v167, v167
	v_rcp_f32_e32 v168, v168
	v_rcp_f32_e32 v169, v169
	v_rcp_f32_e32 v170, v170
	v_rcp_f32_e32 v171, v171
	v_mul_f32_e32 v128, v128, v164
	v_mul_f32_e32 v129, v129, v165
	v_mul_f32_e32 v130, v130, v166
	v_mul_f32_e32 v131, v131, v167
	v_mul_f32_e32 v124, v124, v168
	v_mul_f32_e32 v125, v125, v169
	v_mul_f32_e32 v126, v126, v170
	v_mul_f32_e32 v127, v127, v171
	v_cvt_pk_bf16_f32 v128, v128, v129
	v_cvt_pk_bf16_f32 v129, v130, v131
	v_cvt_pk_bf16_f32 v130, v124, v125
	v_cvt_pk_bf16_f32 v131, v126, v127
	global_store_dwordx4 v152, v[128:131], s[44:45] nt
	v_mul_f32_e32 v164, 0xbfb8aa3b, v120
	v_mul_f32_e32 v165, 0xbfb8aa3b, v121
	v_mul_f32_e32 v166, 0xbfb8aa3b, v122
	v_mul_f32_e32 v167, 0xbfb8aa3b, v123
	v_mul_f32_e32 v168, 0xbfb8aa3b, v116
	v_mul_f32_e32 v169, 0xbfb8aa3b, v117
	v_mul_f32_e32 v170, 0xbfb8aa3b, v118
	v_mul_f32_e32 v171, 0xbfb8aa3b, v119
	v_exp_f32_e32 v164, v164
	v_exp_f32_e32 v165, v165
	v_exp_f32_e32 v166, v166
	v_exp_f32_e32 v167, v167
	v_exp_f32_e32 v168, v168
	v_exp_f32_e32 v169, v169
	v_exp_f32_e32 v170, v170
	v_exp_f32_e32 v171, v171
	v_add_f32_e32 v164, 1.0, v164
	v_add_f32_e32 v165, 1.0, v165
	v_add_f32_e32 v166, 1.0, v166
	v_add_f32_e32 v167, 1.0, v167
	v_add_f32_e32 v168, 1.0, v168
	v_add_f32_e32 v169, 1.0, v169
	v_add_f32_e32 v170, 1.0, v170
	v_add_f32_e32 v171, 1.0, v171
	v_rcp_f32_e32 v164, v164
	v_rcp_f32_e32 v165, v165
	v_rcp_f32_e32 v166, v166
	v_rcp_f32_e32 v167, v167
	v_rcp_f32_e32 v168, v168
	v_rcp_f32_e32 v169, v169
	v_rcp_f32_e32 v170, v170
	v_rcp_f32_e32 v171, v171
	v_mul_f32_e32 v120, v120, v164
	v_mul_f32_e32 v121, v121, v165
	v_mul_f32_e32 v122, v122, v166
	v_mul_f32_e32 v123, v123, v167
	v_mul_f32_e32 v116, v116, v168
	v_mul_f32_e32 v117, v117, v169
	v_mul_f32_e32 v118, v118, v170
	v_mul_f32_e32 v119, v119, v171
	v_cvt_pk_bf16_f32 v120, v120, v121
	v_cvt_pk_bf16_f32 v121, v122, v123
	v_cvt_pk_bf16_f32 v122, v116, v117
	v_cvt_pk_bf16_f32 v123, v118, v119
	global_store_dwordx4 v152, v[120:123], s[44:45] offset:256 nt
	v_add_u32_e32 v152, 0x26000, v152
	v_mul_f32_e32 v164, 0xbfb8aa3b, v112
	v_mul_f32_e32 v165, 0xbfb8aa3b, v113
	v_mul_f32_e32 v166, 0xbfb8aa3b, v114
	v_mul_f32_e32 v167, 0xbfb8aa3b, v115
	v_mul_f32_e32 v168, 0xbfb8aa3b, v108
	v_mul_f32_e32 v169, 0xbfb8aa3b, v109
	v_mul_f32_e32 v170, 0xbfb8aa3b, v110
	v_mul_f32_e32 v171, 0xbfb8aa3b, v111
	v_exp_f32_e32 v164, v164
	v_exp_f32_e32 v165, v165
	v_exp_f32_e32 v166, v166
	v_exp_f32_e32 v167, v167
	v_exp_f32_e32 v168, v168
	v_exp_f32_e32 v169, v169
	v_exp_f32_e32 v170, v170
	v_exp_f32_e32 v171, v171
	v_add_f32_e32 v164, 1.0, v164
	v_add_f32_e32 v165, 1.0, v165
	v_add_f32_e32 v166, 1.0, v166
	v_add_f32_e32 v167, 1.0, v167
	v_add_f32_e32 v168, 1.0, v168
	v_add_f32_e32 v169, 1.0, v169
	v_add_f32_e32 v170, 1.0, v170
	v_add_f32_e32 v171, 1.0, v171
	v_rcp_f32_e32 v164, v164
	v_rcp_f32_e32 v165, v165
	v_rcp_f32_e32 v166, v166
	v_rcp_f32_e32 v167, v167
	v_rcp_f32_e32 v168, v168
	v_rcp_f32_e32 v169, v169
	v_rcp_f32_e32 v170, v170
	v_rcp_f32_e32 v171, v171
	v_mul_f32_e32 v112, v112, v164
	v_mul_f32_e32 v113, v113, v165
	v_mul_f32_e32 v114, v114, v166
	v_mul_f32_e32 v115, v115, v167
	v_mul_f32_e32 v108, v108, v168
	v_mul_f32_e32 v109, v109, v169
	v_mul_f32_e32 v110, v110, v170
	v_mul_f32_e32 v111, v111, v171
	v_cvt_pk_bf16_f32 v112, v112, v113
	v_cvt_pk_bf16_f32 v113, v114, v115
	v_cvt_pk_bf16_f32 v114, v108, v109
	v_cvt_pk_bf16_f32 v115, v110, v111
	global_store_dwordx4 v152, v[112:115], s[44:45] nt
	v_mul_f32_e32 v164, 0xbfb8aa3b, v104
	v_mul_f32_e32 v165, 0xbfb8aa3b, v105
	v_mul_f32_e32 v166, 0xbfb8aa3b, v106
	v_mul_f32_e32 v167, 0xbfb8aa3b, v107
	v_mul_f32_e32 v168, 0xbfb8aa3b, v100
	v_mul_f32_e32 v169, 0xbfb8aa3b, v101
	v_mul_f32_e32 v170, 0xbfb8aa3b, v102
	v_mul_f32_e32 v171, 0xbfb8aa3b, v103
	v_exp_f32_e32 v164, v164
	v_exp_f32_e32 v165, v165
	v_exp_f32_e32 v166, v166
	v_exp_f32_e32 v167, v167
	v_exp_f32_e32 v168, v168
	v_exp_f32_e32 v169, v169
	v_exp_f32_e32 v170, v170
	v_exp_f32_e32 v171, v171
	v_add_f32_e32 v164, 1.0, v164
	v_add_f32_e32 v165, 1.0, v165
	v_add_f32_e32 v166, 1.0, v166
	v_add_f32_e32 v167, 1.0, v167
	v_add_f32_e32 v168, 1.0, v168
	v_add_f32_e32 v169, 1.0, v169
	v_add_f32_e32 v170, 1.0, v170
	v_add_f32_e32 v171, 1.0, v171
	v_rcp_f32_e32 v164, v164
	v_rcp_f32_e32 v165, v165
	v_rcp_f32_e32 v166, v166
	v_rcp_f32_e32 v167, v167
	v_rcp_f32_e32 v168, v168
	v_rcp_f32_e32 v169, v169
	v_rcp_f32_e32 v170, v170
	v_rcp_f32_e32 v171, v171
	v_mul_f32_e32 v104, v104, v164
	v_mul_f32_e32 v105, v105, v165
	v_mul_f32_e32 v106, v106, v166
	v_mul_f32_e32 v107, v107, v167
	v_mul_f32_e32 v100, v100, v168
	v_mul_f32_e32 v101, v101, v169
	v_mul_f32_e32 v102, v102, v170
	v_mul_f32_e32 v103, v103, v171
	v_cvt_pk_bf16_f32 v104, v104, v105
	v_cvt_pk_bf16_f32 v105, v106, v107
	v_cvt_pk_bf16_f32 v106, v100, v101
	v_cvt_pk_bf16_f32 v107, v102, v103
	global_store_dwordx4 v152, v[104:107], s[44:45] offset:256 nt
	v_add_u32_e32 v152, 0x26000, v152
	v_mul_f32_e32 v164, 0xbfb8aa3b, v96
	v_mul_f32_e32 v165, 0xbfb8aa3b, v97
	v_mul_f32_e32 v166, 0xbfb8aa3b, v98
	v_mul_f32_e32 v167, 0xbfb8aa3b, v99
	v_mul_f32_e32 v168, 0xbfb8aa3b, v92
	v_mul_f32_e32 v169, 0xbfb8aa3b, v93
	v_mul_f32_e32 v170, 0xbfb8aa3b, v94
	v_mul_f32_e32 v171, 0xbfb8aa3b, v95
	v_exp_f32_e32 v164, v164
	v_exp_f32_e32 v165, v165
	v_exp_f32_e32 v166, v166
	v_exp_f32_e32 v167, v167
	v_exp_f32_e32 v168, v168
	v_exp_f32_e32 v169, v169
	v_exp_f32_e32 v170, v170
	v_exp_f32_e32 v171, v171
	v_add_f32_e32 v164, 1.0, v164
	v_add_f32_e32 v165, 1.0, v165
	v_add_f32_e32 v166, 1.0, v166
	v_add_f32_e32 v167, 1.0, v167
	v_add_f32_e32 v168, 1.0, v168
	v_add_f32_e32 v169, 1.0, v169
	v_add_f32_e32 v170, 1.0, v170
	v_add_f32_e32 v171, 1.0, v171
	v_rcp_f32_e32 v164, v164
	v_rcp_f32_e32 v165, v165
	v_rcp_f32_e32 v166, v166
	v_rcp_f32_e32 v167, v167
	v_rcp_f32_e32 v168, v168
	v_rcp_f32_e32 v169, v169
	v_rcp_f32_e32 v170, v170
	v_rcp_f32_e32 v171, v171
	v_mul_f32_e32 v96, v96, v164
	v_mul_f32_e32 v97, v97, v165
	v_mul_f32_e32 v98, v98, v166
	v_mul_f32_e32 v99, v99, v167
	v_mul_f32_e32 v92, v92, v168
	v_mul_f32_e32 v93, v93, v169
	v_mul_f32_e32 v94, v94, v170
	v_mul_f32_e32 v95, v95, v171
	v_cvt_pk_bf16_f32 v96, v96, v97
	v_cvt_pk_bf16_f32 v97, v98, v99
	v_cvt_pk_bf16_f32 v98, v92, v93
	v_cvt_pk_bf16_f32 v99, v94, v95
	global_store_dwordx4 v152, v[96:99], s[44:45] nt
	v_mul_f32_e32 v164, 0xbfb8aa3b, v88
	v_mul_f32_e32 v165, 0xbfb8aa3b, v89
	v_mul_f32_e32 v166, 0xbfb8aa3b, v90
	v_mul_f32_e32 v167, 0xbfb8aa3b, v91
	v_mul_f32_e32 v168, 0xbfb8aa3b, v84
	v_mul_f32_e32 v169, 0xbfb8aa3b, v85
	v_mul_f32_e32 v170, 0xbfb8aa3b, v86
	v_mul_f32_e32 v171, 0xbfb8aa3b, v87
	v_exp_f32_e32 v164, v164
	v_exp_f32_e32 v165, v165
	v_exp_f32_e32 v166, v166
	v_exp_f32_e32 v167, v167
	v_exp_f32_e32 v168, v168
	v_exp_f32_e32 v169, v169
	v_exp_f32_e32 v170, v170
	v_exp_f32_e32 v171, v171
	v_add_f32_e32 v164, 1.0, v164
	v_add_f32_e32 v165, 1.0, v165
	v_add_f32_e32 v166, 1.0, v166
	v_add_f32_e32 v167, 1.0, v167
	v_add_f32_e32 v168, 1.0, v168
	v_add_f32_e32 v169, 1.0, v169
	v_add_f32_e32 v170, 1.0, v170
	v_add_f32_e32 v171, 1.0, v171
	v_rcp_f32_e32 v164, v164
	v_rcp_f32_e32 v165, v165
	v_rcp_f32_e32 v166, v166
	v_rcp_f32_e32 v167, v167
	v_rcp_f32_e32 v168, v168
	v_rcp_f32_e32 v169, v169
	v_rcp_f32_e32 v170, v170
	v_rcp_f32_e32 v171, v171
	v_mul_f32_e32 v88, v88, v164
	v_mul_f32_e32 v89, v89, v165
	v_mul_f32_e32 v90, v90, v166
	v_mul_f32_e32 v91, v91, v167
	v_mul_f32_e32 v84, v84, v168
	v_mul_f32_e32 v85, v85, v169
	v_mul_f32_e32 v86, v86, v170
	v_mul_f32_e32 v87, v87, v171
	v_cvt_pk_bf16_f32 v88, v88, v89
	v_cvt_pk_bf16_f32 v89, v90, v91
	v_cvt_pk_bf16_f32 v90, v84, v85
	v_cvt_pk_bf16_f32 v91, v86, v87
	global_store_dwordx4 v152, v[88:91], s[44:45] offset:256 nt
	v_add_u32_e32 v152, 0x26000, v152
	v_mul_f32_e32 v164, 0xbfb8aa3b, v80
	v_mul_f32_e32 v165, 0xbfb8aa3b, v81
	v_mul_f32_e32 v166, 0xbfb8aa3b, v82
	v_mul_f32_e32 v167, 0xbfb8aa3b, v83
	v_mul_f32_e32 v168, 0xbfb8aa3b, v76
	v_mul_f32_e32 v169, 0xbfb8aa3b, v77
	v_mul_f32_e32 v170, 0xbfb8aa3b, v78
	v_mul_f32_e32 v171, 0xbfb8aa3b, v79
	v_exp_f32_e32 v164, v164
	v_exp_f32_e32 v165, v165
	v_exp_f32_e32 v166, v166
	v_exp_f32_e32 v167, v167
	v_exp_f32_e32 v168, v168
	v_exp_f32_e32 v169, v169
	v_exp_f32_e32 v170, v170
	v_exp_f32_e32 v171, v171
	v_add_f32_e32 v164, 1.0, v164
	v_add_f32_e32 v165, 1.0, v165
	v_add_f32_e32 v166, 1.0, v166
	v_add_f32_e32 v167, 1.0, v167
	v_add_f32_e32 v168, 1.0, v168
	v_add_f32_e32 v169, 1.0, v169
	v_add_f32_e32 v170, 1.0, v170
	v_add_f32_e32 v171, 1.0, v171
	v_rcp_f32_e32 v164, v164
	v_rcp_f32_e32 v165, v165
	v_rcp_f32_e32 v166, v166
	v_rcp_f32_e32 v167, v167
	v_rcp_f32_e32 v168, v168
	v_rcp_f32_e32 v169, v169
	v_rcp_f32_e32 v170, v170
	v_rcp_f32_e32 v171, v171
	v_mul_f32_e32 v80, v80, v164
	v_mul_f32_e32 v81, v81, v165
	v_mul_f32_e32 v82, v82, v166
	v_mul_f32_e32 v83, v83, v167
	v_mul_f32_e32 v76, v76, v168
	v_mul_f32_e32 v77, v77, v169
	v_mul_f32_e32 v78, v78, v170
	v_mul_f32_e32 v79, v79, v171
	v_cvt_pk_bf16_f32 v80, v80, v81
	v_cvt_pk_bf16_f32 v81, v82, v83
	v_cvt_pk_bf16_f32 v82, v76, v77
	v_cvt_pk_bf16_f32 v83, v78, v79
	global_store_dwordx4 v152, v[80:83], s[44:45] nt
	v_mul_f32_e32 v164, 0xbfb8aa3b, v72
	v_mul_f32_e32 v165, 0xbfb8aa3b, v73
	v_mul_f32_e32 v166, 0xbfb8aa3b, v74
	v_mul_f32_e32 v167, 0xbfb8aa3b, v75
	v_mul_f32_e32 v168, 0xbfb8aa3b, v68
	v_mul_f32_e32 v169, 0xbfb8aa3b, v69
	v_mul_f32_e32 v170, 0xbfb8aa3b, v70
	v_mul_f32_e32 v171, 0xbfb8aa3b, v71
	v_exp_f32_e32 v164, v164
	v_exp_f32_e32 v165, v165
	v_exp_f32_e32 v166, v166
	v_exp_f32_e32 v167, v167
	v_exp_f32_e32 v168, v168
	v_exp_f32_e32 v169, v169
	v_exp_f32_e32 v170, v170
	v_exp_f32_e32 v171, v171
	v_add_f32_e32 v164, 1.0, v164
	v_add_f32_e32 v165, 1.0, v165
	v_add_f32_e32 v166, 1.0, v166
	v_add_f32_e32 v167, 1.0, v167
	v_add_f32_e32 v168, 1.0, v168
	v_add_f32_e32 v169, 1.0, v169
	v_add_f32_e32 v170, 1.0, v170
	v_add_f32_e32 v171, 1.0, v171
	v_rcp_f32_e32 v164, v164
	v_rcp_f32_e32 v165, v165
	v_rcp_f32_e32 v166, v166
	v_rcp_f32_e32 v167, v167
	v_rcp_f32_e32 v168, v168
	v_rcp_f32_e32 v169, v169
	v_rcp_f32_e32 v170, v170
	v_rcp_f32_e32 v171, v171
	v_mul_f32_e32 v72, v72, v164
	v_mul_f32_e32 v73, v73, v165
	v_mul_f32_e32 v74, v74, v166
	v_mul_f32_e32 v75, v75, v167
	v_mul_f32_e32 v68, v68, v168
	v_mul_f32_e32 v69, v69, v169
	v_mul_f32_e32 v70, v70, v170
	v_mul_f32_e32 v71, v71, v171
	v_cvt_pk_bf16_f32 v72, v72, v73
	v_cvt_pk_bf16_f32 v73, v74, v75
	v_cvt_pk_bf16_f32 v74, v68, v69
	v_cvt_pk_bf16_f32 v75, v70, v71
	global_store_dwordx4 v152, v[72:75], s[44:45] offset:256 nt
	v_add_u32_e32 v152, 0xbe000, v152
	v_mul_f32_e32 v164, 0xbfb8aa3b, v64
	v_mul_f32_e32 v165, 0xbfb8aa3b, v65
	v_mul_f32_e32 v166, 0xbfb8aa3b, v66
	v_mul_f32_e32 v167, 0xbfb8aa3b, v67
	v_mul_f32_e32 v168, 0xbfb8aa3b, v60
	v_mul_f32_e32 v169, 0xbfb8aa3b, v61
	v_mul_f32_e32 v170, 0xbfb8aa3b, v62
	v_mul_f32_e32 v171, 0xbfb8aa3b, v63
	v_exp_f32_e32 v164, v164
	v_exp_f32_e32 v165, v165
	v_exp_f32_e32 v166, v166
	v_exp_f32_e32 v167, v167
	v_exp_f32_e32 v168, v168
	v_exp_f32_e32 v169, v169
	v_exp_f32_e32 v170, v170
	v_exp_f32_e32 v171, v171
	v_add_f32_e32 v164, 1.0, v164
	v_add_f32_e32 v165, 1.0, v165
	v_add_f32_e32 v166, 1.0, v166
	v_add_f32_e32 v167, 1.0, v167
	v_add_f32_e32 v168, 1.0, v168
	v_add_f32_e32 v169, 1.0, v169
	v_add_f32_e32 v170, 1.0, v170
	v_add_f32_e32 v171, 1.0, v171
	v_rcp_f32_e32 v164, v164
	v_rcp_f32_e32 v165, v165
	v_rcp_f32_e32 v166, v166
	v_rcp_f32_e32 v167, v167
	v_rcp_f32_e32 v168, v168
	v_rcp_f32_e32 v169, v169
	v_rcp_f32_e32 v170, v170
	v_rcp_f32_e32 v171, v171
	v_mul_f32_e32 v64, v64, v164
	v_mul_f32_e32 v65, v65, v165
	v_mul_f32_e32 v66, v66, v166
	v_mul_f32_e32 v67, v67, v167
	v_mul_f32_e32 v60, v60, v168
	v_mul_f32_e32 v61, v61, v169
	v_mul_f32_e32 v62, v62, v170
	v_mul_f32_e32 v63, v63, v171
	v_cvt_pk_bf16_f32 v64, v64, v65
	v_cvt_pk_bf16_f32 v65, v66, v67
	v_cvt_pk_bf16_f32 v66, v60, v61
	v_cvt_pk_bf16_f32 v67, v62, v63
	global_store_dwordx4 v152, v[64:67], s[44:45] nt
	v_mul_f32_e32 v164, 0xbfb8aa3b, v56
	v_mul_f32_e32 v165, 0xbfb8aa3b, v57
	v_mul_f32_e32 v166, 0xbfb8aa3b, v58
	v_mul_f32_e32 v167, 0xbfb8aa3b, v59
	v_mul_f32_e32 v168, 0xbfb8aa3b, v52
	v_mul_f32_e32 v169, 0xbfb8aa3b, v53
	v_mul_f32_e32 v170, 0xbfb8aa3b, v54
	v_mul_f32_e32 v171, 0xbfb8aa3b, v55
	v_exp_f32_e32 v164, v164
	v_exp_f32_e32 v165, v165
	v_exp_f32_e32 v166, v166
	v_exp_f32_e32 v167, v167
	v_exp_f32_e32 v168, v168
	v_exp_f32_e32 v169, v169
	v_exp_f32_e32 v170, v170
	v_exp_f32_e32 v171, v171
	v_add_f32_e32 v164, 1.0, v164
	v_add_f32_e32 v165, 1.0, v165
	v_add_f32_e32 v166, 1.0, v166
	v_add_f32_e32 v167, 1.0, v167
	v_add_f32_e32 v168, 1.0, v168
	v_add_f32_e32 v169, 1.0, v169
	v_add_f32_e32 v170, 1.0, v170
	v_add_f32_e32 v171, 1.0, v171
	v_rcp_f32_e32 v164, v164
	v_rcp_f32_e32 v165, v165
	v_rcp_f32_e32 v166, v166
	v_rcp_f32_e32 v167, v167
	v_rcp_f32_e32 v168, v168
	v_rcp_f32_e32 v169, v169
	v_rcp_f32_e32 v170, v170
	v_rcp_f32_e32 v171, v171
	v_mul_f32_e32 v56, v56, v164
	v_mul_f32_e32 v57, v57, v165
	v_mul_f32_e32 v58, v58, v166
	v_mul_f32_e32 v59, v59, v167
	v_mul_f32_e32 v52, v52, v168
	v_mul_f32_e32 v53, v53, v169
	v_mul_f32_e32 v54, v54, v170
	v_mul_f32_e32 v55, v55, v171
	v_cvt_pk_bf16_f32 v56, v56, v57
	v_cvt_pk_bf16_f32 v57, v58, v59
	v_cvt_pk_bf16_f32 v58, v52, v53
	v_cvt_pk_bf16_f32 v59, v54, v55
	global_store_dwordx4 v152, v[56:59], s[44:45] offset:256 nt
	v_add_u32_e32 v152, 0x26000, v152
	v_mul_f32_e32 v164, 0xbfb8aa3b, v48
	v_mul_f32_e32 v165, 0xbfb8aa3b, v49
	v_mul_f32_e32 v166, 0xbfb8aa3b, v50
	v_mul_f32_e32 v167, 0xbfb8aa3b, v51
	v_mul_f32_e32 v168, 0xbfb8aa3b, v44
	v_mul_f32_e32 v169, 0xbfb8aa3b, v45
	v_mul_f32_e32 v170, 0xbfb8aa3b, v46
	v_mul_f32_e32 v171, 0xbfb8aa3b, v47
	v_exp_f32_e32 v164, v164
	v_exp_f32_e32 v165, v165
	v_exp_f32_e32 v166, v166
	v_exp_f32_e32 v167, v167
	v_exp_f32_e32 v168, v168
	v_exp_f32_e32 v169, v169
	v_exp_f32_e32 v170, v170
	v_exp_f32_e32 v171, v171
	v_add_f32_e32 v164, 1.0, v164
	v_add_f32_e32 v165, 1.0, v165
	v_add_f32_e32 v166, 1.0, v166
	v_add_f32_e32 v167, 1.0, v167
	v_add_f32_e32 v168, 1.0, v168
	v_add_f32_e32 v169, 1.0, v169
	v_add_f32_e32 v170, 1.0, v170
	v_add_f32_e32 v171, 1.0, v171
	v_rcp_f32_e32 v164, v164
	v_rcp_f32_e32 v165, v165
	v_rcp_f32_e32 v166, v166
	v_rcp_f32_e32 v167, v167
	v_rcp_f32_e32 v168, v168
	v_rcp_f32_e32 v169, v169
	v_rcp_f32_e32 v170, v170
	v_rcp_f32_e32 v171, v171
	v_mul_f32_e32 v48, v48, v164
	v_mul_f32_e32 v49, v49, v165
	v_mul_f32_e32 v50, v50, v166
	v_mul_f32_e32 v51, v51, v167
	v_mul_f32_e32 v44, v44, v168
	v_mul_f32_e32 v45, v45, v169
	v_mul_f32_e32 v46, v46, v170
	v_mul_f32_e32 v47, v47, v171
	v_cvt_pk_bf16_f32 v48, v48, v49
	v_cvt_pk_bf16_f32 v49, v50, v51
	v_cvt_pk_bf16_f32 v50, v44, v45
	v_cvt_pk_bf16_f32 v51, v46, v47
	global_store_dwordx4 v152, v[48:51], s[44:45] nt
	v_mul_f32_e32 v164, 0xbfb8aa3b, v40
	v_mul_f32_e32 v165, 0xbfb8aa3b, v41
	v_mul_f32_e32 v166, 0xbfb8aa3b, v42
	v_mul_f32_e32 v167, 0xbfb8aa3b, v43
	v_mul_f32_e32 v168, 0xbfb8aa3b, v36
	v_mul_f32_e32 v169, 0xbfb8aa3b, v37
	v_mul_f32_e32 v170, 0xbfb8aa3b, v38
	v_mul_f32_e32 v171, 0xbfb8aa3b, v39
	v_exp_f32_e32 v164, v164
	v_exp_f32_e32 v165, v165
	v_exp_f32_e32 v166, v166
	v_exp_f32_e32 v167, v167
	v_exp_f32_e32 v168, v168
	v_exp_f32_e32 v169, v169
	v_exp_f32_e32 v170, v170
	v_exp_f32_e32 v171, v171
	v_add_f32_e32 v164, 1.0, v164
	v_add_f32_e32 v165, 1.0, v165
	v_add_f32_e32 v166, 1.0, v166
	v_add_f32_e32 v167, 1.0, v167
	v_add_f32_e32 v168, 1.0, v168
	v_add_f32_e32 v169, 1.0, v169
	v_add_f32_e32 v170, 1.0, v170
	v_add_f32_e32 v171, 1.0, v171
	v_rcp_f32_e32 v164, v164
	v_rcp_f32_e32 v165, v165
	v_rcp_f32_e32 v166, v166
	v_rcp_f32_e32 v167, v167
	v_rcp_f32_e32 v168, v168
	v_rcp_f32_e32 v169, v169
	v_rcp_f32_e32 v170, v170
	v_rcp_f32_e32 v171, v171
	v_mul_f32_e32 v40, v40, v164
	v_mul_f32_e32 v41, v41, v165
	v_mul_f32_e32 v42, v42, v166
	v_mul_f32_e32 v43, v43, v167
	v_mul_f32_e32 v36, v36, v168
	v_mul_f32_e32 v37, v37, v169
	v_mul_f32_e32 v38, v38, v170
	v_mul_f32_e32 v39, v39, v171
	v_cvt_pk_bf16_f32 v40, v40, v41
	v_cvt_pk_bf16_f32 v41, v42, v43
	v_cvt_pk_bf16_f32 v42, v36, v37
	v_cvt_pk_bf16_f32 v43, v38, v39
	global_store_dwordx4 v152, v[40:43], s[44:45] offset:256 nt
	v_add_u32_e32 v152, 0x26000, v152
	v_mul_f32_e32 v164, 0xbfb8aa3b, v32
	v_mul_f32_e32 v165, 0xbfb8aa3b, v33
	v_mul_f32_e32 v166, 0xbfb8aa3b, v34
	v_mul_f32_e32 v167, 0xbfb8aa3b, v35
	v_mul_f32_e32 v168, 0xbfb8aa3b, v28
	v_mul_f32_e32 v169, 0xbfb8aa3b, v29
	v_mul_f32_e32 v170, 0xbfb8aa3b, v30
	v_mul_f32_e32 v171, 0xbfb8aa3b, v31
	v_exp_f32_e32 v164, v164
	v_exp_f32_e32 v165, v165
	v_exp_f32_e32 v166, v166
	v_exp_f32_e32 v167, v167
	v_exp_f32_e32 v168, v168
	v_exp_f32_e32 v169, v169
	v_exp_f32_e32 v170, v170
	v_exp_f32_e32 v171, v171
	v_add_f32_e32 v164, 1.0, v164
	v_add_f32_e32 v165, 1.0, v165
	v_add_f32_e32 v166, 1.0, v166
	v_add_f32_e32 v167, 1.0, v167
	v_add_f32_e32 v168, 1.0, v168
	v_add_f32_e32 v169, 1.0, v169
	v_add_f32_e32 v170, 1.0, v170
	v_add_f32_e32 v171, 1.0, v171
	v_rcp_f32_e32 v164, v164
	v_rcp_f32_e32 v165, v165
	v_rcp_f32_e32 v166, v166
	v_rcp_f32_e32 v167, v167
	v_rcp_f32_e32 v168, v168
	v_rcp_f32_e32 v169, v169
	v_rcp_f32_e32 v170, v170
	v_rcp_f32_e32 v171, v171
	v_mul_f32_e32 v32, v32, v164
	v_mul_f32_e32 v33, v33, v165
	v_mul_f32_e32 v34, v34, v166
	v_mul_f32_e32 v35, v35, v167
	v_mul_f32_e32 v28, v28, v168
	v_mul_f32_e32 v29, v29, v169
	v_mul_f32_e32 v30, v30, v170
	v_mul_f32_e32 v31, v31, v171
	v_cvt_pk_bf16_f32 v32, v32, v33
	v_cvt_pk_bf16_f32 v33, v34, v35
	v_cvt_pk_bf16_f32 v34, v28, v29
	v_cvt_pk_bf16_f32 v35, v30, v31
	global_store_dwordx4 v152, v[32:35], s[44:45] nt
	v_mul_f32_e32 v164, 0xbfb8aa3b, v24
	v_mul_f32_e32 v165, 0xbfb8aa3b, v25
	v_mul_f32_e32 v166, 0xbfb8aa3b, v26
	v_mul_f32_e32 v167, 0xbfb8aa3b, v27
	v_mul_f32_e32 v168, 0xbfb8aa3b, v20
	v_mul_f32_e32 v169, 0xbfb8aa3b, v21
	v_mul_f32_e32 v170, 0xbfb8aa3b, v22
	v_mul_f32_e32 v171, 0xbfb8aa3b, v23
	v_exp_f32_e32 v164, v164
	v_exp_f32_e32 v165, v165
	v_exp_f32_e32 v166, v166
	v_exp_f32_e32 v167, v167
	v_exp_f32_e32 v168, v168
	v_exp_f32_e32 v169, v169
	v_exp_f32_e32 v170, v170
	v_exp_f32_e32 v171, v171
	v_add_f32_e32 v164, 1.0, v164
	v_add_f32_e32 v165, 1.0, v165
	v_add_f32_e32 v166, 1.0, v166
	v_add_f32_e32 v167, 1.0, v167
	v_add_f32_e32 v168, 1.0, v168
	v_add_f32_e32 v169, 1.0, v169
	v_add_f32_e32 v170, 1.0, v170
	v_add_f32_e32 v171, 1.0, v171
	v_rcp_f32_e32 v164, v164
	v_rcp_f32_e32 v165, v165
	v_rcp_f32_e32 v166, v166
	v_rcp_f32_e32 v167, v167
	v_rcp_f32_e32 v168, v168
	v_rcp_f32_e32 v169, v169
	v_rcp_f32_e32 v170, v170
	v_rcp_f32_e32 v171, v171
	v_mul_f32_e32 v24, v24, v164
	v_mul_f32_e32 v25, v25, v165
	v_mul_f32_e32 v26, v26, v166
	v_mul_f32_e32 v27, v27, v167
	v_mul_f32_e32 v20, v20, v168
	v_mul_f32_e32 v21, v21, v169
	v_mul_f32_e32 v22, v22, v170
	v_mul_f32_e32 v23, v23, v171
	v_cvt_pk_bf16_f32 v24, v24, v25
	v_cvt_pk_bf16_f32 v25, v26, v27
	v_cvt_pk_bf16_f32 v26, v20, v21
	v_cvt_pk_bf16_f32 v27, v22, v23
	global_store_dwordx4 v152, v[24:27], s[44:45] offset:256 nt
	v_add_u32_e32 v152, 0x26000, v152
	v_mul_f32_e32 v164, 0xbfb8aa3b, v16
	v_mul_f32_e32 v165, 0xbfb8aa3b, v17
	v_mul_f32_e32 v166, 0xbfb8aa3b, v18
	v_mul_f32_e32 v167, 0xbfb8aa3b, v19
	v_mul_f32_e32 v168, 0xbfb8aa3b, v12
	v_mul_f32_e32 v169, 0xbfb8aa3b, v13
	v_mul_f32_e32 v170, 0xbfb8aa3b, v14
	v_mul_f32_e32 v171, 0xbfb8aa3b, v15
	v_exp_f32_e32 v164, v164
	v_exp_f32_e32 v165, v165
	v_exp_f32_e32 v166, v166
	v_exp_f32_e32 v167, v167
	v_exp_f32_e32 v168, v168
	v_exp_f32_e32 v169, v169
	v_exp_f32_e32 v170, v170
	v_exp_f32_e32 v171, v171
	v_add_f32_e32 v164, 1.0, v164
	v_add_f32_e32 v165, 1.0, v165
	v_add_f32_e32 v166, 1.0, v166
	v_add_f32_e32 v167, 1.0, v167
	v_add_f32_e32 v168, 1.0, v168
	v_add_f32_e32 v169, 1.0, v169
	v_add_f32_e32 v170, 1.0, v170
	v_add_f32_e32 v171, 1.0, v171
	v_rcp_f32_e32 v164, v164
	v_rcp_f32_e32 v165, v165
	v_rcp_f32_e32 v166, v166
	v_rcp_f32_e32 v167, v167
	v_rcp_f32_e32 v168, v168
	v_rcp_f32_e32 v169, v169
	v_rcp_f32_e32 v170, v170
	v_rcp_f32_e32 v171, v171
	v_mul_f32_e32 v16, v16, v164
	v_mul_f32_e32 v17, v17, v165
	v_mul_f32_e32 v18, v18, v166
	v_mul_f32_e32 v19, v19, v167
	v_mul_f32_e32 v12, v12, v168
	v_mul_f32_e32 v13, v13, v169
	v_mul_f32_e32 v14, v14, v170
	v_mul_f32_e32 v15, v15, v171
	v_cvt_pk_bf16_f32 v16, v16, v17
	v_cvt_pk_bf16_f32 v17, v18, v19
	v_cvt_pk_bf16_f32 v18, v12, v13
	v_cvt_pk_bf16_f32 v19, v14, v15
	global_store_dwordx4 v152, v[16:19], s[44:45] nt
	v_mul_f32_e32 v164, 0xbfb8aa3b, v8
	v_mul_f32_e32 v165, 0xbfb8aa3b, v9
	v_mul_f32_e32 v166, 0xbfb8aa3b, v10
	v_mul_f32_e32 v167, 0xbfb8aa3b, v11
	v_mul_f32_e32 v168, 0xbfb8aa3b, v4
	v_mul_f32_e32 v169, 0xbfb8aa3b, v5
	v_mul_f32_e32 v170, 0xbfb8aa3b, v6
	v_mul_f32_e32 v171, 0xbfb8aa3b, v7
	v_exp_f32_e32 v164, v164
	v_exp_f32_e32 v165, v165
	v_exp_f32_e32 v166, v166
	v_exp_f32_e32 v167, v167
	v_exp_f32_e32 v168, v168
	v_exp_f32_e32 v169, v169
	v_exp_f32_e32 v170, v170
	v_exp_f32_e32 v171, v171
	v_add_f32_e32 v164, 1.0, v164
	v_add_f32_e32 v165, 1.0, v165
	v_add_f32_e32 v166, 1.0, v166
	v_add_f32_e32 v167, 1.0, v167
	v_add_f32_e32 v168, 1.0, v168
	v_add_f32_e32 v169, 1.0, v169
	v_add_f32_e32 v170, 1.0, v170
	v_add_f32_e32 v171, 1.0, v171
	v_rcp_f32_e32 v164, v164
	v_rcp_f32_e32 v165, v165
	v_rcp_f32_e32 v166, v166
	v_rcp_f32_e32 v167, v167
	v_rcp_f32_e32 v168, v168
	v_rcp_f32_e32 v169, v169
	v_rcp_f32_e32 v170, v170
	v_rcp_f32_e32 v171, v171
	v_mul_f32_e32 v8, v8, v164
	v_mul_f32_e32 v9, v9, v165
	v_mul_f32_e32 v10, v10, v166
	v_mul_f32_e32 v11, v11, v167
	v_mul_f32_e32 v4, v4, v168
	v_mul_f32_e32 v5, v5, v169
	v_mul_f32_e32 v6, v6, v170
	v_mul_f32_e32 v7, v7, v171
	v_cvt_pk_bf16_f32 v8, v8, v9
	v_cvt_pk_bf16_f32 v9, v10, v11
	v_cvt_pk_bf16_f32 v10, v4, v5
	v_cvt_pk_bf16_f32 v11, v6, v7
	global_store_dwordx4 v152, v[8:11], s[44:45] offset:256 nt
	s_branch .LBB0_590
.Lepi_gelu:
	v_mul_lo_u32 v152, v195, s30
	v_add_u32_e32 v153, s9, v191
	v_lshl_add_u32 v152, v153, 1, v152
	v_mul_f32_e32 v164, 0x3d372713, v128
	v_mul_f32_e32 v165, 0x3d372713, v129
	v_mul_f32_e32 v166, 0x3d372713, v130
	v_mul_f32_e32 v167, 0x3d372713, v131
	v_mul_f32_e32 v168, 0x3d372713, v124
	v_mul_f32_e32 v169, 0x3d372713, v125
	v_mul_f32_e32 v170, 0x3d372713, v126
	v_mul_f32_e32 v171, 0x3d372713, v127
	v_mul_f32_e32 v164, v128, v164
	v_mul_f32_e32 v165, v129, v165
	v_mul_f32_e32 v166, v130, v166
	v_mul_f32_e32 v167, v131, v167
	v_mul_f32_e32 v168, v124, v168
	v_mul_f32_e32 v169, v125, v169
	v_mul_f32_e32 v170, v126, v170
	v_mul_f32_e32 v171, v127, v171
	v_fma_f32 v164, v128, v164, v128
	v_fma_f32 v165, v129, v165, v129
	v_fma_f32 v166, v130, v166, v130
	v_fma_f32 v167, v131, v167, v131
	v_fma_f32 v168, v124, v168, v124
	v_fma_f32 v169, v125, v169, v125
	v_fma_f32 v170, v126, v170, v126
	v_fma_f32 v171, v127, v171, v127
	v_mul_f32_e32 v164, 0x3fcc422a, v164
	v_mul_f32_e32 v165, 0x3fcc422a, v165
	v_mul_f32_e32 v166, 0x3fcc422a, v166
	v_mul_f32_e32 v167, 0x3fcc422a, v167
	v_mul_f32_e32 v168, 0x3fcc422a, v168
	v_mul_f32_e32 v169, 0x3fcc422a, v169
	v_mul_f32_e32 v170, 0x3fcc422a, v170
	v_mul_f32_e32 v171, 0x3fcc422a, v171
	v_mul_f32_e32 v164, 0xbfb8aa3b, v164
	v_mul_f32_e32 v165, 0xbfb8aa3b, v165
	v_mul_f32_e32 v166, 0xbfb8aa3b, v166
	v_mul_f32_e32 v167, 0xbfb8aa3b, v167
	v_mul_f32_e32 v168, 0xbfb8aa3b, v168
	v_mul_f32_e32 v169, 0xbfb8aa3b, v169
	v_mul_f32_e32 v170, 0xbfb8aa3b, v170
	v_mul_f32_e32 v171, 0xbfb8aa3b, v171
	v_exp_f32_e32 v164, v164
	v_exp_f32_e32 v165, v165
	v_exp_f32_e32 v166, v166
	v_exp_f32_e32 v167, v167
	v_exp_f32_e32 v168, v168
	v_exp_f32_e32 v169, v169
	v_exp_f32_e32 v170, v170
	v_exp_f32_e32 v171, v171
	v_add_f32_e32 v164, 1.0, v164
	v_add_f32_e32 v165, 1.0, v165
	v_add_f32_e32 v166, 1.0, v166
	v_add_f32_e32 v167, 1.0, v167
	v_add_f32_e32 v168, 1.0, v168
	v_add_f32_e32 v169, 1.0, v169
	v_add_f32_e32 v170, 1.0, v170
	v_add_f32_e32 v171, 1.0, v171
	v_rcp_f32_e32 v164, v164
	v_rcp_f32_e32 v165, v165
	v_rcp_f32_e32 v166, v166
	v_rcp_f32_e32 v167, v167
	v_rcp_f32_e32 v168, v168
	v_rcp_f32_e32 v169, v169
	v_rcp_f32_e32 v170, v170
	v_rcp_f32_e32 v171, v171
	v_mul_f32_e32 v128, v128, v164
	v_mul_f32_e32 v129, v129, v165
	v_mul_f32_e32 v130, v130, v166
	v_mul_f32_e32 v131, v131, v167
	v_mul_f32_e32 v124, v124, v168
	v_mul_f32_e32 v125, v125, v169
	v_mul_f32_e32 v126, v126, v170
	v_mul_f32_e32 v127, v127, v171
	v_cvt_pk_bf16_f32 v128, v128, v129
	v_cvt_pk_bf16_f32 v129, v130, v131
	v_cvt_pk_bf16_f32 v130, v124, v125
	v_cvt_pk_bf16_f32 v131, v126, v127
	global_store_dwordx4 v152, v[128:131], s[44:45] nt
	v_mul_f32_e32 v164, 0x3d372713, v120
	v_mul_f32_e32 v165, 0x3d372713, v121
	v_mul_f32_e32 v166, 0x3d372713, v122
	v_mul_f32_e32 v167, 0x3d372713, v123
	v_mul_f32_e32 v168, 0x3d372713, v116
	v_mul_f32_e32 v169, 0x3d372713, v117
	v_mul_f32_e32 v170, 0x3d372713, v118
	v_mul_f32_e32 v171, 0x3d372713, v119
	v_mul_f32_e32 v164, v120, v164
	v_mul_f32_e32 v165, v121, v165
	v_mul_f32_e32 v166, v122, v166
	v_mul_f32_e32 v167, v123, v167
	v_mul_f32_e32 v168, v116, v168
	v_mul_f32_e32 v169, v117, v169
	v_mul_f32_e32 v170, v118, v170
	v_mul_f32_e32 v171, v119, v171
	v_fma_f32 v164, v120, v164, v120
	v_fma_f32 v165, v121, v165, v121
	v_fma_f32 v166, v122, v166, v122
	v_fma_f32 v167, v123, v167, v123
	v_fma_f32 v168, v116, v168, v116
	v_fma_f32 v169, v117, v169, v117
	v_fma_f32 v170, v118, v170, v118
	v_fma_f32 v171, v119, v171, v119
	v_mul_f32_e32 v164, 0x3fcc422a, v164
	v_mul_f32_e32 v165, 0x3fcc422a, v165
	v_mul_f32_e32 v166, 0x3fcc422a, v166
	v_mul_f32_e32 v167, 0x3fcc422a, v167
	v_mul_f32_e32 v168, 0x3fcc422a, v168
	v_mul_f32_e32 v169, 0x3fcc422a, v169
	v_mul_f32_e32 v170, 0x3fcc422a, v170
	v_mul_f32_e32 v171, 0x3fcc422a, v171
	v_mul_f32_e32 v164, 0xbfb8aa3b, v164
	v_mul_f32_e32 v165, 0xbfb8aa3b, v165
	v_mul_f32_e32 v166, 0xbfb8aa3b, v166
	v_mul_f32_e32 v167, 0xbfb8aa3b, v167
	v_mul_f32_e32 v168, 0xbfb8aa3b, v168
	v_mul_f32_e32 v169, 0xbfb8aa3b, v169
	v_mul_f32_e32 v170, 0xbfb8aa3b, v170
	v_mul_f32_e32 v171, 0xbfb8aa3b, v171
	v_exp_f32_e32 v164, v164
	v_exp_f32_e32 v165, v165
	v_exp_f32_e32 v166, v166
	v_exp_f32_e32 v167, v167
	v_exp_f32_e32 v168, v168
	v_exp_f32_e32 v169, v169
	v_exp_f32_e32 v170, v170
	v_exp_f32_e32 v171, v171
	v_add_f32_e32 v164, 1.0, v164
	v_add_f32_e32 v165, 1.0, v165
	v_add_f32_e32 v166, 1.0, v166
	v_add_f32_e32 v167, 1.0, v167
	v_add_f32_e32 v168, 1.0, v168
	v_add_f32_e32 v169, 1.0, v169
	v_add_f32_e32 v170, 1.0, v170
	v_add_f32_e32 v171, 1.0, v171
	v_rcp_f32_e32 v164, v164
	v_rcp_f32_e32 v165, v165
	v_rcp_f32_e32 v166, v166
	v_rcp_f32_e32 v167, v167
	v_rcp_f32_e32 v168, v168
	v_rcp_f32_e32 v169, v169
	v_rcp_f32_e32 v170, v170
	v_rcp_f32_e32 v171, v171
	v_mul_f32_e32 v120, v120, v164
	v_mul_f32_e32 v121, v121, v165
	v_mul_f32_e32 v122, v122, v166
	v_mul_f32_e32 v123, v123, v167
	v_mul_f32_e32 v116, v116, v168
	v_mul_f32_e32 v117, v117, v169
	v_mul_f32_e32 v118, v118, v170
	v_mul_f32_e32 v119, v119, v171
	v_cvt_pk_bf16_f32 v120, v120, v121
	v_cvt_pk_bf16_f32 v121, v122, v123
	v_cvt_pk_bf16_f32 v122, v116, v117
	v_cvt_pk_bf16_f32 v123, v118, v119
	global_store_dwordx4 v152, v[120:123], s[44:45] offset:256 nt
	v_add_u32_e32 v152, 0x26000, v152
	v_mul_f32_e32 v164, 0x3d372713, v112
	v_mul_f32_e32 v165, 0x3d372713, v113
	v_mul_f32_e32 v166, 0x3d372713, v114
	v_mul_f32_e32 v167, 0x3d372713, v115
	v_mul_f32_e32 v168, 0x3d372713, v108
	v_mul_f32_e32 v169, 0x3d372713, v109
	v_mul_f32_e32 v170, 0x3d372713, v110
	v_mul_f32_e32 v171, 0x3d372713, v111
	v_mul_f32_e32 v164, v112, v164
	v_mul_f32_e32 v165, v113, v165
	v_mul_f32_e32 v166, v114, v166
	v_mul_f32_e32 v167, v115, v167
	v_mul_f32_e32 v168, v108, v168
	v_mul_f32_e32 v169, v109, v169
	v_mul_f32_e32 v170, v110, v170
	v_mul_f32_e32 v171, v111, v171
	v_fma_f32 v164, v112, v164, v112
	v_fma_f32 v165, v113, v165, v113
	v_fma_f32 v166, v114, v166, v114
	v_fma_f32 v167, v115, v167, v115
	v_fma_f32 v168, v108, v168, v108
	v_fma_f32 v169, v109, v169, v109
	v_fma_f32 v170, v110, v170, v110
	v_fma_f32 v171, v111, v171, v111
	v_mul_f32_e32 v164, 0x3fcc422a, v164
	v_mul_f32_e32 v165, 0x3fcc422a, v165
	v_mul_f32_e32 v166, 0x3fcc422a, v166
	v_mul_f32_e32 v167, 0x3fcc422a, v167
	v_mul_f32_e32 v168, 0x3fcc422a, v168
	v_mul_f32_e32 v169, 0x3fcc422a, v169
	v_mul_f32_e32 v170, 0x3fcc422a, v170
	v_mul_f32_e32 v171, 0x3fcc422a, v171
	v_mul_f32_e32 v164, 0xbfb8aa3b, v164
	v_mul_f32_e32 v165, 0xbfb8aa3b, v165
	v_mul_f32_e32 v166, 0xbfb8aa3b, v166
	v_mul_f32_e32 v167, 0xbfb8aa3b, v167
	v_mul_f32_e32 v168, 0xbfb8aa3b, v168
	v_mul_f32_e32 v169, 0xbfb8aa3b, v169
	v_mul_f32_e32 v170, 0xbfb8aa3b, v170
	v_mul_f32_e32 v171, 0xbfb8aa3b, v171
	v_exp_f32_e32 v164, v164
	v_exp_f32_e32 v165, v165
	v_exp_f32_e32 v166, v166
	v_exp_f32_e32 v167, v167
	v_exp_f32_e32 v168, v168
	v_exp_f32_e32 v169, v169
	v_exp_f32_e32 v170, v170
	v_exp_f32_e32 v171, v171
	v_add_f32_e32 v164, 1.0, v164
	v_add_f32_e32 v165, 1.0, v165
	v_add_f32_e32 v166, 1.0, v166
	v_add_f32_e32 v167, 1.0, v167
	v_add_f32_e32 v168, 1.0, v168
	v_add_f32_e32 v169, 1.0, v169
	v_add_f32_e32 v170, 1.0, v170
	v_add_f32_e32 v171, 1.0, v171
	v_rcp_f32_e32 v164, v164
	v_rcp_f32_e32 v165, v165
	v_rcp_f32_e32 v166, v166
	v_rcp_f32_e32 v167, v167
	v_rcp_f32_e32 v168, v168
	v_rcp_f32_e32 v169, v169
	v_rcp_f32_e32 v170, v170
	v_rcp_f32_e32 v171, v171
	v_mul_f32_e32 v112, v112, v164
	v_mul_f32_e32 v113, v113, v165
	v_mul_f32_e32 v114, v114, v166
	v_mul_f32_e32 v115, v115, v167
	v_mul_f32_e32 v108, v108, v168
	v_mul_f32_e32 v109, v109, v169
	v_mul_f32_e32 v110, v110, v170
	v_mul_f32_e32 v111, v111, v171
	v_cvt_pk_bf16_f32 v112, v112, v113
	v_cvt_pk_bf16_f32 v113, v114, v115
	v_cvt_pk_bf16_f32 v114, v108, v109
	v_cvt_pk_bf16_f32 v115, v110, v111
	global_store_dwordx4 v152, v[112:115], s[44:45] nt
	v_mul_f32_e32 v164, 0x3d372713, v104
	v_mul_f32_e32 v165, 0x3d372713, v105
	v_mul_f32_e32 v166, 0x3d372713, v106
	v_mul_f32_e32 v167, 0x3d372713, v107
	v_mul_f32_e32 v168, 0x3d372713, v100
	v_mul_f32_e32 v169, 0x3d372713, v101
	v_mul_f32_e32 v170, 0x3d372713, v102
	v_mul_f32_e32 v171, 0x3d372713, v103
	v_mul_f32_e32 v164, v104, v164
	v_mul_f32_e32 v165, v105, v165
	v_mul_f32_e32 v166, v106, v166
	v_mul_f32_e32 v167, v107, v167
	v_mul_f32_e32 v168, v100, v168
	v_mul_f32_e32 v169, v101, v169
	v_mul_f32_e32 v170, v102, v170
	v_mul_f32_e32 v171, v103, v171
	v_fma_f32 v164, v104, v164, v104
	v_fma_f32 v165, v105, v165, v105
	v_fma_f32 v166, v106, v166, v106
	v_fma_f32 v167, v107, v167, v107
	v_fma_f32 v168, v100, v168, v100
	v_fma_f32 v169, v101, v169, v101
	v_fma_f32 v170, v102, v170, v102
	v_fma_f32 v171, v103, v171, v103
	v_mul_f32_e32 v164, 0x3fcc422a, v164
	v_mul_f32_e32 v165, 0x3fcc422a, v165
	v_mul_f32_e32 v166, 0x3fcc422a, v166
	v_mul_f32_e32 v167, 0x3fcc422a, v167
	v_mul_f32_e32 v168, 0x3fcc422a, v168
	v_mul_f32_e32 v169, 0x3fcc422a, v169
	v_mul_f32_e32 v170, 0x3fcc422a, v170
	v_mul_f32_e32 v171, 0x3fcc422a, v171
	v_mul_f32_e32 v164, 0xbfb8aa3b, v164
	v_mul_f32_e32 v165, 0xbfb8aa3b, v165
	v_mul_f32_e32 v166, 0xbfb8aa3b, v166
	v_mul_f32_e32 v167, 0xbfb8aa3b, v167
	v_mul_f32_e32 v168, 0xbfb8aa3b, v168
	v_mul_f32_e32 v169, 0xbfb8aa3b, v169
	v_mul_f32_e32 v170, 0xbfb8aa3b, v170
	v_mul_f32_e32 v171, 0xbfb8aa3b, v171
	v_exp_f32_e32 v164, v164
	v_exp_f32_e32 v165, v165
	v_exp_f32_e32 v166, v166
	v_exp_f32_e32 v167, v167
	v_exp_f32_e32 v168, v168
	v_exp_f32_e32 v169, v169
	v_exp_f32_e32 v170, v170
	v_exp_f32_e32 v171, v171
	v_add_f32_e32 v164, 1.0, v164
	v_add_f32_e32 v165, 1.0, v165
	v_add_f32_e32 v166, 1.0, v166
	v_add_f32_e32 v167, 1.0, v167
	v_add_f32_e32 v168, 1.0, v168
	v_add_f32_e32 v169, 1.0, v169
	v_add_f32_e32 v170, 1.0, v170
	v_add_f32_e32 v171, 1.0, v171
	v_rcp_f32_e32 v164, v164
	v_rcp_f32_e32 v165, v165
	v_rcp_f32_e32 v166, v166
	v_rcp_f32_e32 v167, v167
	v_rcp_f32_e32 v168, v168
	v_rcp_f32_e32 v169, v169
	v_rcp_f32_e32 v170, v170
	v_rcp_f32_e32 v171, v171
	v_mul_f32_e32 v104, v104, v164
	v_mul_f32_e32 v105, v105, v165
	v_mul_f32_e32 v106, v106, v166
	v_mul_f32_e32 v107, v107, v167
	v_mul_f32_e32 v100, v100, v168
	v_mul_f32_e32 v101, v101, v169
	v_mul_f32_e32 v102, v102, v170
	v_mul_f32_e32 v103, v103, v171
	v_cvt_pk_bf16_f32 v104, v104, v105
	v_cvt_pk_bf16_f32 v105, v106, v107
	v_cvt_pk_bf16_f32 v106, v100, v101
	v_cvt_pk_bf16_f32 v107, v102, v103
	global_store_dwordx4 v152, v[104:107], s[44:45] offset:256 nt
	v_add_u32_e32 v152, 0x26000, v152
	v_mul_f32_e32 v164, 0x3d372713, v96
	v_mul_f32_e32 v165, 0x3d372713, v97
	v_mul_f32_e32 v166, 0x3d372713, v98
	v_mul_f32_e32 v167, 0x3d372713, v99
	v_mul_f32_e32 v168, 0x3d372713, v92
	v_mul_f32_e32 v169, 0x3d372713, v93
	v_mul_f32_e32 v170, 0x3d372713, v94
	v_mul_f32_e32 v171, 0x3d372713, v95
	v_mul_f32_e32 v164, v96, v164
	v_mul_f32_e32 v165, v97, v165
	v_mul_f32_e32 v166, v98, v166
	v_mul_f32_e32 v167, v99, v167
	v_mul_f32_e32 v168, v92, v168
	v_mul_f32_e32 v169, v93, v169
	v_mul_f32_e32 v170, v94, v170
	v_mul_f32_e32 v171, v95, v171
	v_fma_f32 v164, v96, v164, v96
	v_fma_f32 v165, v97, v165, v97
	v_fma_f32 v166, v98, v166, v98
	v_fma_f32 v167, v99, v167, v99
	v_fma_f32 v168, v92, v168, v92
	v_fma_f32 v169, v93, v169, v93
	v_fma_f32 v170, v94, v170, v94
	v_fma_f32 v171, v95, v171, v95
	v_mul_f32_e32 v164, 0x3fcc422a, v164
	v_mul_f32_e32 v165, 0x3fcc422a, v165
	v_mul_f32_e32 v166, 0x3fcc422a, v166
	v_mul_f32_e32 v167, 0x3fcc422a, v167
	v_mul_f32_e32 v168, 0x3fcc422a, v168
	v_mul_f32_e32 v169, 0x3fcc422a, v169
	v_mul_f32_e32 v170, 0x3fcc422a, v170
	v_mul_f32_e32 v171, 0x3fcc422a, v171
	v_mul_f32_e32 v164, 0xbfb8aa3b, v164
	v_mul_f32_e32 v165, 0xbfb8aa3b, v165
	v_mul_f32_e32 v166, 0xbfb8aa3b, v166
	v_mul_f32_e32 v167, 0xbfb8aa3b, v167
	v_mul_f32_e32 v168, 0xbfb8aa3b, v168
	v_mul_f32_e32 v169, 0xbfb8aa3b, v169
	v_mul_f32_e32 v170, 0xbfb8aa3b, v170
	v_mul_f32_e32 v171, 0xbfb8aa3b, v171
	v_exp_f32_e32 v164, v164
	v_exp_f32_e32 v165, v165
	v_exp_f32_e32 v166, v166
	v_exp_f32_e32 v167, v167
	v_exp_f32_e32 v168, v168
	v_exp_f32_e32 v169, v169
	v_exp_f32_e32 v170, v170
	v_exp_f32_e32 v171, v171
	v_add_f32_e32 v164, 1.0, v164
	v_add_f32_e32 v165, 1.0, v165
	v_add_f32_e32 v166, 1.0, v166
	v_add_f32_e32 v167, 1.0, v167
	v_add_f32_e32 v168, 1.0, v168
	v_add_f32_e32 v169, 1.0, v169
	v_add_f32_e32 v170, 1.0, v170
	v_add_f32_e32 v171, 1.0, v171
	v_rcp_f32_e32 v164, v164
	v_rcp_f32_e32 v165, v165
	v_rcp_f32_e32 v166, v166
	v_rcp_f32_e32 v167, v167
	v_rcp_f32_e32 v168, v168
	v_rcp_f32_e32 v169, v169
	v_rcp_f32_e32 v170, v170
	v_rcp_f32_e32 v171, v171
	v_mul_f32_e32 v96, v96, v164
	v_mul_f32_e32 v97, v97, v165
	v_mul_f32_e32 v98, v98, v166
	v_mul_f32_e32 v99, v99, v167
	v_mul_f32_e32 v92, v92, v168
	v_mul_f32_e32 v93, v93, v169
	v_mul_f32_e32 v94, v94, v170
	v_mul_f32_e32 v95, v95, v171
	v_cvt_pk_bf16_f32 v96, v96, v97
	v_cvt_pk_bf16_f32 v97, v98, v99
	v_cvt_pk_bf16_f32 v98, v92, v93
	v_cvt_pk_bf16_f32 v99, v94, v95
	global_store_dwordx4 v152, v[96:99], s[44:45] nt
	v_mul_f32_e32 v164, 0x3d372713, v88
	v_mul_f32_e32 v165, 0x3d372713, v89
	v_mul_f32_e32 v166, 0x3d372713, v90
	v_mul_f32_e32 v167, 0x3d372713, v91
	v_mul_f32_e32 v168, 0x3d372713, v84
	v_mul_f32_e32 v169, 0x3d372713, v85
	v_mul_f32_e32 v170, 0x3d372713, v86
	v_mul_f32_e32 v171, 0x3d372713, v87
	v_mul_f32_e32 v164, v88, v164
	v_mul_f32_e32 v165, v89, v165
	v_mul_f32_e32 v166, v90, v166
	v_mul_f32_e32 v167, v91, v167
	v_mul_f32_e32 v168, v84, v168
	v_mul_f32_e32 v169, v85, v169
	v_mul_f32_e32 v170, v86, v170
	v_mul_f32_e32 v171, v87, v171
	v_fma_f32 v164, v88, v164, v88
	v_fma_f32 v165, v89, v165, v89
	v_fma_f32 v166, v90, v166, v90
	v_fma_f32 v167, v91, v167, v91
	v_fma_f32 v168, v84, v168, v84
	v_fma_f32 v169, v85, v169, v85
	v_fma_f32 v170, v86, v170, v86
	v_fma_f32 v171, v87, v171, v87
	v_mul_f32_e32 v164, 0x3fcc422a, v164
	v_mul_f32_e32 v165, 0x3fcc422a, v165
	v_mul_f32_e32 v166, 0x3fcc422a, v166
	v_mul_f32_e32 v167, 0x3fcc422a, v167
	v_mul_f32_e32 v168, 0x3fcc422a, v168
	v_mul_f32_e32 v169, 0x3fcc422a, v169
	v_mul_f32_e32 v170, 0x3fcc422a, v170
	v_mul_f32_e32 v171, 0x3fcc422a, v171
	v_mul_f32_e32 v164, 0xbfb8aa3b, v164
	v_mul_f32_e32 v165, 0xbfb8aa3b, v165
	v_mul_f32_e32 v166, 0xbfb8aa3b, v166
	v_mul_f32_e32 v167, 0xbfb8aa3b, v167
	v_mul_f32_e32 v168, 0xbfb8aa3b, v168
	v_mul_f32_e32 v169, 0xbfb8aa3b, v169
	v_mul_f32_e32 v170, 0xbfb8aa3b, v170
	v_mul_f32_e32 v171, 0xbfb8aa3b, v171
	v_exp_f32_e32 v164, v164
	v_exp_f32_e32 v165, v165
	v_exp_f32_e32 v166, v166
	v_exp_f32_e32 v167, v167
	v_exp_f32_e32 v168, v168
	v_exp_f32_e32 v169, v169
	v_exp_f32_e32 v170, v170
	v_exp_f32_e32 v171, v171
	v_add_f32_e32 v164, 1.0, v164
	v_add_f32_e32 v165, 1.0, v165
	v_add_f32_e32 v166, 1.0, v166
	v_add_f32_e32 v167, 1.0, v167
	v_add_f32_e32 v168, 1.0, v168
	v_add_f32_e32 v169, 1.0, v169
	v_add_f32_e32 v170, 1.0, v170
	v_add_f32_e32 v171, 1.0, v171
	v_rcp_f32_e32 v164, v164
	v_rcp_f32_e32 v165, v165
	v_rcp_f32_e32 v166, v166
	v_rcp_f32_e32 v167, v167
	v_rcp_f32_e32 v168, v168
	v_rcp_f32_e32 v169, v169
	v_rcp_f32_e32 v170, v170
	v_rcp_f32_e32 v171, v171
	v_mul_f32_e32 v88, v88, v164
	v_mul_f32_e32 v89, v89, v165
	v_mul_f32_e32 v90, v90, v166
	v_mul_f32_e32 v91, v91, v167
	v_mul_f32_e32 v84, v84, v168
	v_mul_f32_e32 v85, v85, v169
	v_mul_f32_e32 v86, v86, v170
	v_mul_f32_e32 v87, v87, v171
	v_cvt_pk_bf16_f32 v88, v88, v89
	v_cvt_pk_bf16_f32 v89, v90, v91
	v_cvt_pk_bf16_f32 v90, v84, v85
	v_cvt_pk_bf16_f32 v91, v86, v87
	global_store_dwordx4 v152, v[88:91], s[44:45] offset:256 nt
	v_add_u32_e32 v152, 0x26000, v152
	v_mul_f32_e32 v164, 0x3d372713, v80
	v_mul_f32_e32 v165, 0x3d372713, v81
	v_mul_f32_e32 v166, 0x3d372713, v82
	v_mul_f32_e32 v167, 0x3d372713, v83
	v_mul_f32_e32 v168, 0x3d372713, v76
	v_mul_f32_e32 v169, 0x3d372713, v77
	v_mul_f32_e32 v170, 0x3d372713, v78
	v_mul_f32_e32 v171, 0x3d372713, v79
	v_mul_f32_e32 v164, v80, v164
	v_mul_f32_e32 v165, v81, v165
	v_mul_f32_e32 v166, v82, v166
	v_mul_f32_e32 v167, v83, v167
	v_mul_f32_e32 v168, v76, v168
	v_mul_f32_e32 v169, v77, v169
	v_mul_f32_e32 v170, v78, v170
	v_mul_f32_e32 v171, v79, v171
	v_fma_f32 v164, v80, v164, v80
	v_fma_f32 v165, v81, v165, v81
	v_fma_f32 v166, v82, v166, v82
	v_fma_f32 v167, v83, v167, v83
	v_fma_f32 v168, v76, v168, v76
	v_fma_f32 v169, v77, v169, v77
	v_fma_f32 v170, v78, v170, v78
	v_fma_f32 v171, v79, v171, v79
	v_mul_f32_e32 v164, 0x3fcc422a, v164
	v_mul_f32_e32 v165, 0x3fcc422a, v165
	v_mul_f32_e32 v166, 0x3fcc422a, v166
	v_mul_f32_e32 v167, 0x3fcc422a, v167
	v_mul_f32_e32 v168, 0x3fcc422a, v168
	v_mul_f32_e32 v169, 0x3fcc422a, v169
	v_mul_f32_e32 v170, 0x3fcc422a, v170
	v_mul_f32_e32 v171, 0x3fcc422a, v171
	v_mul_f32_e32 v164, 0xbfb8aa3b, v164
	v_mul_f32_e32 v165, 0xbfb8aa3b, v165
	v_mul_f32_e32 v166, 0xbfb8aa3b, v166
	v_mul_f32_e32 v167, 0xbfb8aa3b, v167
	v_mul_f32_e32 v168, 0xbfb8aa3b, v168
	v_mul_f32_e32 v169, 0xbfb8aa3b, v169
	v_mul_f32_e32 v170, 0xbfb8aa3b, v170
	v_mul_f32_e32 v171, 0xbfb8aa3b, v171
	v_exp_f32_e32 v164, v164
	v_exp_f32_e32 v165, v165
	v_exp_f32_e32 v166, v166
	v_exp_f32_e32 v167, v167
	v_exp_f32_e32 v168, v168
	v_exp_f32_e32 v169, v169
	v_exp_f32_e32 v170, v170
	v_exp_f32_e32 v171, v171
	v_add_f32_e32 v164, 1.0, v164
	v_add_f32_e32 v165, 1.0, v165
	v_add_f32_e32 v166, 1.0, v166
	v_add_f32_e32 v167, 1.0, v167
	v_add_f32_e32 v168, 1.0, v168
	v_add_f32_e32 v169, 1.0, v169
	v_add_f32_e32 v170, 1.0, v170
	v_add_f32_e32 v171, 1.0, v171
	v_rcp_f32_e32 v164, v164
	v_rcp_f32_e32 v165, v165
	v_rcp_f32_e32 v166, v166
	v_rcp_f32_e32 v167, v167
	v_rcp_f32_e32 v168, v168
	v_rcp_f32_e32 v169, v169
	v_rcp_f32_e32 v170, v170
	v_rcp_f32_e32 v171, v171
	v_mul_f32_e32 v80, v80, v164
	v_mul_f32_e32 v81, v81, v165
	v_mul_f32_e32 v82, v82, v166
	v_mul_f32_e32 v83, v83, v167
	v_mul_f32_e32 v76, v76, v168
	v_mul_f32_e32 v77, v77, v169
	v_mul_f32_e32 v78, v78, v170
	v_mul_f32_e32 v79, v79, v171
	v_cvt_pk_bf16_f32 v80, v80, v81
	v_cvt_pk_bf16_f32 v81, v82, v83
	v_cvt_pk_bf16_f32 v82, v76, v77
	v_cvt_pk_bf16_f32 v83, v78, v79
	global_store_dwordx4 v152, v[80:83], s[44:45] nt
	v_mul_f32_e32 v164, 0x3d372713, v72
	v_mul_f32_e32 v165, 0x3d372713, v73
	v_mul_f32_e32 v166, 0x3d372713, v74
	v_mul_f32_e32 v167, 0x3d372713, v75
	v_mul_f32_e32 v168, 0x3d372713, v68
	v_mul_f32_e32 v169, 0x3d372713, v69
	v_mul_f32_e32 v170, 0x3d372713, v70
	v_mul_f32_e32 v171, 0x3d372713, v71
	v_mul_f32_e32 v164, v72, v164
	v_mul_f32_e32 v165, v73, v165
	v_mul_f32_e32 v166, v74, v166
	v_mul_f32_e32 v167, v75, v167
	v_mul_f32_e32 v168, v68, v168
	v_mul_f32_e32 v169, v69, v169
	v_mul_f32_e32 v170, v70, v170
	v_mul_f32_e32 v171, v71, v171
	v_fma_f32 v164, v72, v164, v72
	v_fma_f32 v165, v73, v165, v73
	v_fma_f32 v166, v74, v166, v74
	v_fma_f32 v167, v75, v167, v75
	v_fma_f32 v168, v68, v168, v68
	v_fma_f32 v169, v69, v169, v69
	v_fma_f32 v170, v70, v170, v70
	v_fma_f32 v171, v71, v171, v71
	v_mul_f32_e32 v164, 0x3fcc422a, v164
	v_mul_f32_e32 v165, 0x3fcc422a, v165
	v_mul_f32_e32 v166, 0x3fcc422a, v166
	v_mul_f32_e32 v167, 0x3fcc422a, v167
	v_mul_f32_e32 v168, 0x3fcc422a, v168
	v_mul_f32_e32 v169, 0x3fcc422a, v169
	v_mul_f32_e32 v170, 0x3fcc422a, v170
	v_mul_f32_e32 v171, 0x3fcc422a, v171
	v_mul_f32_e32 v164, 0xbfb8aa3b, v164
	v_mul_f32_e32 v165, 0xbfb8aa3b, v165
	v_mul_f32_e32 v166, 0xbfb8aa3b, v166
	v_mul_f32_e32 v167, 0xbfb8aa3b, v167
	v_mul_f32_e32 v168, 0xbfb8aa3b, v168
	v_mul_f32_e32 v169, 0xbfb8aa3b, v169
	v_mul_f32_e32 v170, 0xbfb8aa3b, v170
	v_mul_f32_e32 v171, 0xbfb8aa3b, v171
	v_exp_f32_e32 v164, v164
	v_exp_f32_e32 v165, v165
	v_exp_f32_e32 v166, v166
	v_exp_f32_e32 v167, v167
	v_exp_f32_e32 v168, v168
	v_exp_f32_e32 v169, v169
	v_exp_f32_e32 v170, v170
	v_exp_f32_e32 v171, v171
	v_add_f32_e32 v164, 1.0, v164
	v_add_f32_e32 v165, 1.0, v165
	v_add_f32_e32 v166, 1.0, v166
	v_add_f32_e32 v167, 1.0, v167
	v_add_f32_e32 v168, 1.0, v168
	v_add_f32_e32 v169, 1.0, v169
	v_add_f32_e32 v170, 1.0, v170
	v_add_f32_e32 v171, 1.0, v171
	v_rcp_f32_e32 v164, v164
	v_rcp_f32_e32 v165, v165
	v_rcp_f32_e32 v166, v166
	v_rcp_f32_e32 v167, v167
	v_rcp_f32_e32 v168, v168
	v_rcp_f32_e32 v169, v169
	v_rcp_f32_e32 v170, v170
	v_rcp_f32_e32 v171, v171
	v_mul_f32_e32 v72, v72, v164
	v_mul_f32_e32 v73, v73, v165
	v_mul_f32_e32 v74, v74, v166
	v_mul_f32_e32 v75, v75, v167
	v_mul_f32_e32 v68, v68, v168
	v_mul_f32_e32 v69, v69, v169
	v_mul_f32_e32 v70, v70, v170
	v_mul_f32_e32 v71, v71, v171
	v_cvt_pk_bf16_f32 v72, v72, v73
	v_cvt_pk_bf16_f32 v73, v74, v75
	v_cvt_pk_bf16_f32 v74, v68, v69
	v_cvt_pk_bf16_f32 v75, v70, v71
	global_store_dwordx4 v152, v[72:75], s[44:45] offset:256 nt
	v_add_u32_e32 v152, 0xbe000, v152
	v_mul_f32_e32 v164, 0x3d372713, v64
	v_mul_f32_e32 v165, 0x3d372713, v65
	v_mul_f32_e32 v166, 0x3d372713, v66
	v_mul_f32_e32 v167, 0x3d372713, v67
	v_mul_f32_e32 v168, 0x3d372713, v60
	v_mul_f32_e32 v169, 0x3d372713, v61
	v_mul_f32_e32 v170, 0x3d372713, v62
	v_mul_f32_e32 v171, 0x3d372713, v63
	v_mul_f32_e32 v164, v64, v164
	v_mul_f32_e32 v165, v65, v165
	v_mul_f32_e32 v166, v66, v166
	v_mul_f32_e32 v167, v67, v167
	v_mul_f32_e32 v168, v60, v168
	v_mul_f32_e32 v169, v61, v169
	v_mul_f32_e32 v170, v62, v170
	v_mul_f32_e32 v171, v63, v171
	v_fma_f32 v164, v64, v164, v64
	v_fma_f32 v165, v65, v165, v65
	v_fma_f32 v166, v66, v166, v66
	v_fma_f32 v167, v67, v167, v67
	v_fma_f32 v168, v60, v168, v60
	v_fma_f32 v169, v61, v169, v61
	v_fma_f32 v170, v62, v170, v62
	v_fma_f32 v171, v63, v171, v63
	v_mul_f32_e32 v164, 0x3fcc422a, v164
	v_mul_f32_e32 v165, 0x3fcc422a, v165
	v_mul_f32_e32 v166, 0x3fcc422a, v166
	v_mul_f32_e32 v167, 0x3fcc422a, v167
	v_mul_f32_e32 v168, 0x3fcc422a, v168
	v_mul_f32_e32 v169, 0x3fcc422a, v169
	v_mul_f32_e32 v170, 0x3fcc422a, v170
	v_mul_f32_e32 v171, 0x3fcc422a, v171
	v_mul_f32_e32 v164, 0xbfb8aa3b, v164
	v_mul_f32_e32 v165, 0xbfb8aa3b, v165
	v_mul_f32_e32 v166, 0xbfb8aa3b, v166
	v_mul_f32_e32 v167, 0xbfb8aa3b, v167
	v_mul_f32_e32 v168, 0xbfb8aa3b, v168
	v_mul_f32_e32 v169, 0xbfb8aa3b, v169
	v_mul_f32_e32 v170, 0xbfb8aa3b, v170
	v_mul_f32_e32 v171, 0xbfb8aa3b, v171
	v_exp_f32_e32 v164, v164
	v_exp_f32_e32 v165, v165
	v_exp_f32_e32 v166, v166
	v_exp_f32_e32 v167, v167
	v_exp_f32_e32 v168, v168
	v_exp_f32_e32 v169, v169
	v_exp_f32_e32 v170, v170
	v_exp_f32_e32 v171, v171
	v_add_f32_e32 v164, 1.0, v164
	v_add_f32_e32 v165, 1.0, v165
	v_add_f32_e32 v166, 1.0, v166
	v_add_f32_e32 v167, 1.0, v167
	v_add_f32_e32 v168, 1.0, v168
	v_add_f32_e32 v169, 1.0, v169
	v_add_f32_e32 v170, 1.0, v170
	v_add_f32_e32 v171, 1.0, v171
	v_rcp_f32_e32 v164, v164
	v_rcp_f32_e32 v165, v165
	v_rcp_f32_e32 v166, v166
	v_rcp_f32_e32 v167, v167
	v_rcp_f32_e32 v168, v168
	v_rcp_f32_e32 v169, v169
	v_rcp_f32_e32 v170, v170
	v_rcp_f32_e32 v171, v171
	v_mul_f32_e32 v64, v64, v164
	v_mul_f32_e32 v65, v65, v165
	v_mul_f32_e32 v66, v66, v166
	v_mul_f32_e32 v67, v67, v167
	v_mul_f32_e32 v60, v60, v168
	v_mul_f32_e32 v61, v61, v169
	v_mul_f32_e32 v62, v62, v170
	v_mul_f32_e32 v63, v63, v171
	v_cvt_pk_bf16_f32 v64, v64, v65
	v_cvt_pk_bf16_f32 v65, v66, v67
	v_cvt_pk_bf16_f32 v66, v60, v61
	v_cvt_pk_bf16_f32 v67, v62, v63
	global_store_dwordx4 v152, v[64:67], s[44:45] nt
	v_mul_f32_e32 v164, 0x3d372713, v56
	v_mul_f32_e32 v165, 0x3d372713, v57
	v_mul_f32_e32 v166, 0x3d372713, v58
	v_mul_f32_e32 v167, 0x3d372713, v59
	v_mul_f32_e32 v168, 0x3d372713, v52
	v_mul_f32_e32 v169, 0x3d372713, v53
	v_mul_f32_e32 v170, 0x3d372713, v54
	v_mul_f32_e32 v171, 0x3d372713, v55
	v_mul_f32_e32 v164, v56, v164
	v_mul_f32_e32 v165, v57, v165
	v_mul_f32_e32 v166, v58, v166
	v_mul_f32_e32 v167, v59, v167
	v_mul_f32_e32 v168, v52, v168
	v_mul_f32_e32 v169, v53, v169
	v_mul_f32_e32 v170, v54, v170
	v_mul_f32_e32 v171, v55, v171
	v_fma_f32 v164, v56, v164, v56
	v_fma_f32 v165, v57, v165, v57
	v_fma_f32 v166, v58, v166, v58
	v_fma_f32 v167, v59, v167, v59
	v_fma_f32 v168, v52, v168, v52
	v_fma_f32 v169, v53, v169, v53
	v_fma_f32 v170, v54, v170, v54
	v_fma_f32 v171, v55, v171, v55
	v_mul_f32_e32 v164, 0x3fcc422a, v164
	v_mul_f32_e32 v165, 0x3fcc422a, v165
	v_mul_f32_e32 v166, 0x3fcc422a, v166
	v_mul_f32_e32 v167, 0x3fcc422a, v167
	v_mul_f32_e32 v168, 0x3fcc422a, v168
	v_mul_f32_e32 v169, 0x3fcc422a, v169
	v_mul_f32_e32 v170, 0x3fcc422a, v170
	v_mul_f32_e32 v171, 0x3fcc422a, v171
	v_mul_f32_e32 v164, 0xbfb8aa3b, v164
	v_mul_f32_e32 v165, 0xbfb8aa3b, v165
	v_mul_f32_e32 v166, 0xbfb8aa3b, v166
	v_mul_f32_e32 v167, 0xbfb8aa3b, v167
	v_mul_f32_e32 v168, 0xbfb8aa3b, v168
	v_mul_f32_e32 v169, 0xbfb8aa3b, v169
	v_mul_f32_e32 v170, 0xbfb8aa3b, v170
	v_mul_f32_e32 v171, 0xbfb8aa3b, v171
	v_exp_f32_e32 v164, v164
	v_exp_f32_e32 v165, v165
	v_exp_f32_e32 v166, v166
	v_exp_f32_e32 v167, v167
	v_exp_f32_e32 v168, v168
	v_exp_f32_e32 v169, v169
	v_exp_f32_e32 v170, v170
	v_exp_f32_e32 v171, v171
	v_add_f32_e32 v164, 1.0, v164
	v_add_f32_e32 v165, 1.0, v165
	v_add_f32_e32 v166, 1.0, v166
	v_add_f32_e32 v167, 1.0, v167
	v_add_f32_e32 v168, 1.0, v168
	v_add_f32_e32 v169, 1.0, v169
	v_add_f32_e32 v170, 1.0, v170
	v_add_f32_e32 v171, 1.0, v171
	v_rcp_f32_e32 v164, v164
	v_rcp_f32_e32 v165, v165
	v_rcp_f32_e32 v166, v166
	v_rcp_f32_e32 v167, v167
	v_rcp_f32_e32 v168, v168
	v_rcp_f32_e32 v169, v169
	v_rcp_f32_e32 v170, v170
	v_rcp_f32_e32 v171, v171
	v_mul_f32_e32 v56, v56, v164
	v_mul_f32_e32 v57, v57, v165
	v_mul_f32_e32 v58, v58, v166
	v_mul_f32_e32 v59, v59, v167
	v_mul_f32_e32 v52, v52, v168
	v_mul_f32_e32 v53, v53, v169
	v_mul_f32_e32 v54, v54, v170
	v_mul_f32_e32 v55, v55, v171
	v_cvt_pk_bf16_f32 v56, v56, v57
	v_cvt_pk_bf16_f32 v57, v58, v59
	v_cvt_pk_bf16_f32 v58, v52, v53
	v_cvt_pk_bf16_f32 v59, v54, v55
	global_store_dwordx4 v152, v[56:59], s[44:45] offset:256 nt
	v_add_u32_e32 v152, 0x26000, v152
	v_mul_f32_e32 v164, 0x3d372713, v48
	v_mul_f32_e32 v165, 0x3d372713, v49
	v_mul_f32_e32 v166, 0x3d372713, v50
	v_mul_f32_e32 v167, 0x3d372713, v51
	v_mul_f32_e32 v168, 0x3d372713, v44
	v_mul_f32_e32 v169, 0x3d372713, v45
	v_mul_f32_e32 v170, 0x3d372713, v46
	v_mul_f32_e32 v171, 0x3d372713, v47
	v_mul_f32_e32 v164, v48, v164
	v_mul_f32_e32 v165, v49, v165
	v_mul_f32_e32 v166, v50, v166
	v_mul_f32_e32 v167, v51, v167
	v_mul_f32_e32 v168, v44, v168
	v_mul_f32_e32 v169, v45, v169
	v_mul_f32_e32 v170, v46, v170
	v_mul_f32_e32 v171, v47, v171
	v_fma_f32 v164, v48, v164, v48
	v_fma_f32 v165, v49, v165, v49
	v_fma_f32 v166, v50, v166, v50
	v_fma_f32 v167, v51, v167, v51
	v_fma_f32 v168, v44, v168, v44
	v_fma_f32 v169, v45, v169, v45
	v_fma_f32 v170, v46, v170, v46
	v_fma_f32 v171, v47, v171, v47
	v_mul_f32_e32 v164, 0x3fcc422a, v164
	v_mul_f32_e32 v165, 0x3fcc422a, v165
	v_mul_f32_e32 v166, 0x3fcc422a, v166
	v_mul_f32_e32 v167, 0x3fcc422a, v167
	v_mul_f32_e32 v168, 0x3fcc422a, v168
	v_mul_f32_e32 v169, 0x3fcc422a, v169
	v_mul_f32_e32 v170, 0x3fcc422a, v170
	v_mul_f32_e32 v171, 0x3fcc422a, v171
	v_mul_f32_e32 v164, 0xbfb8aa3b, v164
	v_mul_f32_e32 v165, 0xbfb8aa3b, v165
	v_mul_f32_e32 v166, 0xbfb8aa3b, v166
	v_mul_f32_e32 v167, 0xbfb8aa3b, v167
	v_mul_f32_e32 v168, 0xbfb8aa3b, v168
	v_mul_f32_e32 v169, 0xbfb8aa3b, v169
	v_mul_f32_e32 v170, 0xbfb8aa3b, v170
	v_mul_f32_e32 v171, 0xbfb8aa3b, v171
	v_exp_f32_e32 v164, v164
	v_exp_f32_e32 v165, v165
	v_exp_f32_e32 v166, v166
	v_exp_f32_e32 v167, v167
	v_exp_f32_e32 v168, v168
	v_exp_f32_e32 v169, v169
	v_exp_f32_e32 v170, v170
	v_exp_f32_e32 v171, v171
	v_add_f32_e32 v164, 1.0, v164
	v_add_f32_e32 v165, 1.0, v165
	v_add_f32_e32 v166, 1.0, v166
	v_add_f32_e32 v167, 1.0, v167
	v_add_f32_e32 v168, 1.0, v168
	v_add_f32_e32 v169, 1.0, v169
	v_add_f32_e32 v170, 1.0, v170
	v_add_f32_e32 v171, 1.0, v171
	v_rcp_f32_e32 v164, v164
	v_rcp_f32_e32 v165, v165
	v_rcp_f32_e32 v166, v166
	v_rcp_f32_e32 v167, v167
	v_rcp_f32_e32 v168, v168
	v_rcp_f32_e32 v169, v169
	v_rcp_f32_e32 v170, v170
	v_rcp_f32_e32 v171, v171
	v_mul_f32_e32 v48, v48, v164
	v_mul_f32_e32 v49, v49, v165
	v_mul_f32_e32 v50, v50, v166
	v_mul_f32_e32 v51, v51, v167
	v_mul_f32_e32 v44, v44, v168
	v_mul_f32_e32 v45, v45, v169
	v_mul_f32_e32 v46, v46, v170
	v_mul_f32_e32 v47, v47, v171
	v_cvt_pk_bf16_f32 v48, v48, v49
	v_cvt_pk_bf16_f32 v49, v50, v51
	v_cvt_pk_bf16_f32 v50, v44, v45
	v_cvt_pk_bf16_f32 v51, v46, v47
	global_store_dwordx4 v152, v[48:51], s[44:45] nt
	v_mul_f32_e32 v164, 0x3d372713, v40
	v_mul_f32_e32 v165, 0x3d372713, v41
	v_mul_f32_e32 v166, 0x3d372713, v42
	v_mul_f32_e32 v167, 0x3d372713, v43
	v_mul_f32_e32 v168, 0x3d372713, v36
	v_mul_f32_e32 v169, 0x3d372713, v37
	v_mul_f32_e32 v170, 0x3d372713, v38
	v_mul_f32_e32 v171, 0x3d372713, v39
	v_mul_f32_e32 v164, v40, v164
	v_mul_f32_e32 v165, v41, v165
	v_mul_f32_e32 v166, v42, v166
	v_mul_f32_e32 v167, v43, v167
	v_mul_f32_e32 v168, v36, v168
	v_mul_f32_e32 v169, v37, v169
	v_mul_f32_e32 v170, v38, v170
	v_mul_f32_e32 v171, v39, v171
	v_fma_f32 v164, v40, v164, v40
	v_fma_f32 v165, v41, v165, v41
	v_fma_f32 v166, v42, v166, v42
	v_fma_f32 v167, v43, v167, v43
	v_fma_f32 v168, v36, v168, v36
	v_fma_f32 v169, v37, v169, v37
	v_fma_f32 v170, v38, v170, v38
	v_fma_f32 v171, v39, v171, v39
	v_mul_f32_e32 v164, 0x3fcc422a, v164
	v_mul_f32_e32 v165, 0x3fcc422a, v165
	v_mul_f32_e32 v166, 0x3fcc422a, v166
	v_mul_f32_e32 v167, 0x3fcc422a, v167
	v_mul_f32_e32 v168, 0x3fcc422a, v168
	v_mul_f32_e32 v169, 0x3fcc422a, v169
	v_mul_f32_e32 v170, 0x3fcc422a, v170
	v_mul_f32_e32 v171, 0x3fcc422a, v171
	v_mul_f32_e32 v164, 0xbfb8aa3b, v164
	v_mul_f32_e32 v165, 0xbfb8aa3b, v165
	v_mul_f32_e32 v166, 0xbfb8aa3b, v166
	v_mul_f32_e32 v167, 0xbfb8aa3b, v167
	v_mul_f32_e32 v168, 0xbfb8aa3b, v168
	v_mul_f32_e32 v169, 0xbfb8aa3b, v169
	v_mul_f32_e32 v170, 0xbfb8aa3b, v170
	v_mul_f32_e32 v171, 0xbfb8aa3b, v171
	v_exp_f32_e32 v164, v164
	v_exp_f32_e32 v165, v165
	v_exp_f32_e32 v166, v166
	v_exp_f32_e32 v167, v167
	v_exp_f32_e32 v168, v168
	v_exp_f32_e32 v169, v169
	v_exp_f32_e32 v170, v170
	v_exp_f32_e32 v171, v171
	v_add_f32_e32 v164, 1.0, v164
	v_add_f32_e32 v165, 1.0, v165
	v_add_f32_e32 v166, 1.0, v166
	v_add_f32_e32 v167, 1.0, v167
	v_add_f32_e32 v168, 1.0, v168
	v_add_f32_e32 v169, 1.0, v169
	v_add_f32_e32 v170, 1.0, v170
	v_add_f32_e32 v171, 1.0, v171
	v_rcp_f32_e32 v164, v164
	v_rcp_f32_e32 v165, v165
	v_rcp_f32_e32 v166, v166
	v_rcp_f32_e32 v167, v167
	v_rcp_f32_e32 v168, v168
	v_rcp_f32_e32 v169, v169
	v_rcp_f32_e32 v170, v170
	v_rcp_f32_e32 v171, v171
	v_mul_f32_e32 v40, v40, v164
	v_mul_f32_e32 v41, v41, v165
	v_mul_f32_e32 v42, v42, v166
	v_mul_f32_e32 v43, v43, v167
	v_mul_f32_e32 v36, v36, v168
	v_mul_f32_e32 v37, v37, v169
	v_mul_f32_e32 v38, v38, v170
	v_mul_f32_e32 v39, v39, v171
	v_cvt_pk_bf16_f32 v40, v40, v41
	v_cvt_pk_bf16_f32 v41, v42, v43
	v_cvt_pk_bf16_f32 v42, v36, v37
	v_cvt_pk_bf16_f32 v43, v38, v39
	global_store_dwordx4 v152, v[40:43], s[44:45] offset:256 nt
	v_add_u32_e32 v152, 0x26000, v152
	v_mul_f32_e32 v164, 0x3d372713, v32
	v_mul_f32_e32 v165, 0x3d372713, v33
	v_mul_f32_e32 v166, 0x3d372713, v34
	v_mul_f32_e32 v167, 0x3d372713, v35
	v_mul_f32_e32 v168, 0x3d372713, v28
	v_mul_f32_e32 v169, 0x3d372713, v29
	v_mul_f32_e32 v170, 0x3d372713, v30
	v_mul_f32_e32 v171, 0x3d372713, v31
	v_mul_f32_e32 v164, v32, v164
	v_mul_f32_e32 v165, v33, v165
	v_mul_f32_e32 v166, v34, v166
	v_mul_f32_e32 v167, v35, v167
	v_mul_f32_e32 v168, v28, v168
	v_mul_f32_e32 v169, v29, v169
	v_mul_f32_e32 v170, v30, v170
	v_mul_f32_e32 v171, v31, v171
	v_fma_f32 v164, v32, v164, v32
	v_fma_f32 v165, v33, v165, v33
	v_fma_f32 v166, v34, v166, v34
	v_fma_f32 v167, v35, v167, v35
	v_fma_f32 v168, v28, v168, v28
	v_fma_f32 v169, v29, v169, v29
	v_fma_f32 v170, v30, v170, v30
	v_fma_f32 v171, v31, v171, v31
	v_mul_f32_e32 v164, 0x3fcc422a, v164
	v_mul_f32_e32 v165, 0x3fcc422a, v165
	v_mul_f32_e32 v166, 0x3fcc422a, v166
	v_mul_f32_e32 v167, 0x3fcc422a, v167
	v_mul_f32_e32 v168, 0x3fcc422a, v168
	v_mul_f32_e32 v169, 0x3fcc422a, v169
	v_mul_f32_e32 v170, 0x3fcc422a, v170
	v_mul_f32_e32 v171, 0x3fcc422a, v171
	v_mul_f32_e32 v164, 0xbfb8aa3b, v164
	v_mul_f32_e32 v165, 0xbfb8aa3b, v165
	v_mul_f32_e32 v166, 0xbfb8aa3b, v166
	v_mul_f32_e32 v167, 0xbfb8aa3b, v167
	v_mul_f32_e32 v168, 0xbfb8aa3b, v168
	v_mul_f32_e32 v169, 0xbfb8aa3b, v169
	v_mul_f32_e32 v170, 0xbfb8aa3b, v170
	v_mul_f32_e32 v171, 0xbfb8aa3b, v171
	v_exp_f32_e32 v164, v164
	v_exp_f32_e32 v165, v165
	v_exp_f32_e32 v166, v166
	v_exp_f32_e32 v167, v167
	v_exp_f32_e32 v168, v168
	v_exp_f32_e32 v169, v169
	v_exp_f32_e32 v170, v170
	v_exp_f32_e32 v171, v171
	v_add_f32_e32 v164, 1.0, v164
	v_add_f32_e32 v165, 1.0, v165
	v_add_f32_e32 v166, 1.0, v166
	v_add_f32_e32 v167, 1.0, v167
	v_add_f32_e32 v168, 1.0, v168
	v_add_f32_e32 v169, 1.0, v169
	v_add_f32_e32 v170, 1.0, v170
	v_add_f32_e32 v171, 1.0, v171
	v_rcp_f32_e32 v164, v164
	v_rcp_f32_e32 v165, v165
	v_rcp_f32_e32 v166, v166
	v_rcp_f32_e32 v167, v167
	v_rcp_f32_e32 v168, v168
	v_rcp_f32_e32 v169, v169
	v_rcp_f32_e32 v170, v170
	v_rcp_f32_e32 v171, v171
	v_mul_f32_e32 v32, v32, v164
	v_mul_f32_e32 v33, v33, v165
	v_mul_f32_e32 v34, v34, v166
	v_mul_f32_e32 v35, v35, v167
	v_mul_f32_e32 v28, v28, v168
	v_mul_f32_e32 v29, v29, v169
	v_mul_f32_e32 v30, v30, v170
	v_mul_f32_e32 v31, v31, v171
	v_cvt_pk_bf16_f32 v32, v32, v33
	v_cvt_pk_bf16_f32 v33, v34, v35
	v_cvt_pk_bf16_f32 v34, v28, v29
	v_cvt_pk_bf16_f32 v35, v30, v31
	global_store_dwordx4 v152, v[32:35], s[44:45] nt
	v_mul_f32_e32 v164, 0x3d372713, v24
	v_mul_f32_e32 v165, 0x3d372713, v25
	v_mul_f32_e32 v166, 0x3d372713, v26
	v_mul_f32_e32 v167, 0x3d372713, v27
	v_mul_f32_e32 v168, 0x3d372713, v20
	v_mul_f32_e32 v169, 0x3d372713, v21
	v_mul_f32_e32 v170, 0x3d372713, v22
	v_mul_f32_e32 v171, 0x3d372713, v23
	v_mul_f32_e32 v164, v24, v164
	v_mul_f32_e32 v165, v25, v165
	v_mul_f32_e32 v166, v26, v166
	v_mul_f32_e32 v167, v27, v167
	v_mul_f32_e32 v168, v20, v168
	v_mul_f32_e32 v169, v21, v169
	v_mul_f32_e32 v170, v22, v170
	v_mul_f32_e32 v171, v23, v171
	v_fma_f32 v164, v24, v164, v24
	v_fma_f32 v165, v25, v165, v25
	v_fma_f32 v166, v26, v166, v26
	v_fma_f32 v167, v27, v167, v27
	v_fma_f32 v168, v20, v168, v20
	v_fma_f32 v169, v21, v169, v21
	v_fma_f32 v170, v22, v170, v22
	v_fma_f32 v171, v23, v171, v23
	v_mul_f32_e32 v164, 0x3fcc422a, v164
	v_mul_f32_e32 v165, 0x3fcc422a, v165
	v_mul_f32_e32 v166, 0x3fcc422a, v166
	v_mul_f32_e32 v167, 0x3fcc422a, v167
	v_mul_f32_e32 v168, 0x3fcc422a, v168
	v_mul_f32_e32 v169, 0x3fcc422a, v169
	v_mul_f32_e32 v170, 0x3fcc422a, v170
	v_mul_f32_e32 v171, 0x3fcc422a, v171
	v_mul_f32_e32 v164, 0xbfb8aa3b, v164
	v_mul_f32_e32 v165, 0xbfb8aa3b, v165
	v_mul_f32_e32 v166, 0xbfb8aa3b, v166
	v_mul_f32_e32 v167, 0xbfb8aa3b, v167
	v_mul_f32_e32 v168, 0xbfb8aa3b, v168
	v_mul_f32_e32 v169, 0xbfb8aa3b, v169
	v_mul_f32_e32 v170, 0xbfb8aa3b, v170
	v_mul_f32_e32 v171, 0xbfb8aa3b, v171
	v_exp_f32_e32 v164, v164
	v_exp_f32_e32 v165, v165
	v_exp_f32_e32 v166, v166
	v_exp_f32_e32 v167, v167
	v_exp_f32_e32 v168, v168
	v_exp_f32_e32 v169, v169
	v_exp_f32_e32 v170, v170
	v_exp_f32_e32 v171, v171
	v_add_f32_e32 v164, 1.0, v164
	v_add_f32_e32 v165, 1.0, v165
	v_add_f32_e32 v166, 1.0, v166
	v_add_f32_e32 v167, 1.0, v167
	v_add_f32_e32 v168, 1.0, v168
	v_add_f32_e32 v169, 1.0, v169
	v_add_f32_e32 v170, 1.0, v170
	v_add_f32_e32 v171, 1.0, v171
	v_rcp_f32_e32 v164, v164
	v_rcp_f32_e32 v165, v165
	v_rcp_f32_e32 v166, v166
	v_rcp_f32_e32 v167, v167
	v_rcp_f32_e32 v168, v168
	v_rcp_f32_e32 v169, v169
	v_rcp_f32_e32 v170, v170
	v_rcp_f32_e32 v171, v171
	v_mul_f32_e32 v24, v24, v164
	v_mul_f32_e32 v25, v25, v165
	v_mul_f32_e32 v26, v26, v166
	v_mul_f32_e32 v27, v27, v167
	v_mul_f32_e32 v20, v20, v168
	v_mul_f32_e32 v21, v21, v169
	v_mul_f32_e32 v22, v22, v170
	v_mul_f32_e32 v23, v23, v171
	v_cvt_pk_bf16_f32 v24, v24, v25
	v_cvt_pk_bf16_f32 v25, v26, v27
	v_cvt_pk_bf16_f32 v26, v20, v21
	v_cvt_pk_bf16_f32 v27, v22, v23
	global_store_dwordx4 v152, v[24:27], s[44:45] offset:256 nt
	v_add_u32_e32 v152, 0x26000, v152
	v_mul_f32_e32 v164, 0x3d372713, v16
	v_mul_f32_e32 v165, 0x3d372713, v17
	v_mul_f32_e32 v166, 0x3d372713, v18
	v_mul_f32_e32 v167, 0x3d372713, v19
	v_mul_f32_e32 v168, 0x3d372713, v12
	v_mul_f32_e32 v169, 0x3d372713, v13
	v_mul_f32_e32 v170, 0x3d372713, v14
	v_mul_f32_e32 v171, 0x3d372713, v15
	v_mul_f32_e32 v164, v16, v164
	v_mul_f32_e32 v165, v17, v165
	v_mul_f32_e32 v166, v18, v166
	v_mul_f32_e32 v167, v19, v167
	v_mul_f32_e32 v168, v12, v168
	v_mul_f32_e32 v169, v13, v169
	v_mul_f32_e32 v170, v14, v170
	v_mul_f32_e32 v171, v15, v171
	v_fma_f32 v164, v16, v164, v16
	v_fma_f32 v165, v17, v165, v17
	v_fma_f32 v166, v18, v166, v18
	v_fma_f32 v167, v19, v167, v19
	v_fma_f32 v168, v12, v168, v12
	v_fma_f32 v169, v13, v169, v13
	v_fma_f32 v170, v14, v170, v14
	v_fma_f32 v171, v15, v171, v15
	v_mul_f32_e32 v164, 0x3fcc422a, v164
	v_mul_f32_e32 v165, 0x3fcc422a, v165
	v_mul_f32_e32 v166, 0x3fcc422a, v166
	v_mul_f32_e32 v167, 0x3fcc422a, v167
	v_mul_f32_e32 v168, 0x3fcc422a, v168
	v_mul_f32_e32 v169, 0x3fcc422a, v169
	v_mul_f32_e32 v170, 0x3fcc422a, v170
	v_mul_f32_e32 v171, 0x3fcc422a, v171
	v_mul_f32_e32 v164, 0xbfb8aa3b, v164
	v_mul_f32_e32 v165, 0xbfb8aa3b, v165
	v_mul_f32_e32 v166, 0xbfb8aa3b, v166
	v_mul_f32_e32 v167, 0xbfb8aa3b, v167
	v_mul_f32_e32 v168, 0xbfb8aa3b, v168
	v_mul_f32_e32 v169, 0xbfb8aa3b, v169
	v_mul_f32_e32 v170, 0xbfb8aa3b, v170
	v_mul_f32_e32 v171, 0xbfb8aa3b, v171
	v_exp_f32_e32 v164, v164
	v_exp_f32_e32 v165, v165
	v_exp_f32_e32 v166, v166
	v_exp_f32_e32 v167, v167
	v_exp_f32_e32 v168, v168
	v_exp_f32_e32 v169, v169
	v_exp_f32_e32 v170, v170
	v_exp_f32_e32 v171, v171
	v_add_f32_e32 v164, 1.0, v164
	v_add_f32_e32 v165, 1.0, v165
	v_add_f32_e32 v166, 1.0, v166
	v_add_f32_e32 v167, 1.0, v167
	v_add_f32_e32 v168, 1.0, v168
	v_add_f32_e32 v169, 1.0, v169
	v_add_f32_e32 v170, 1.0, v170
	v_add_f32_e32 v171, 1.0, v171
	v_rcp_f32_e32 v164, v164
	v_rcp_f32_e32 v165, v165
	v_rcp_f32_e32 v166, v166
	v_rcp_f32_e32 v167, v167
	v_rcp_f32_e32 v168, v168
	v_rcp_f32_e32 v169, v169
	v_rcp_f32_e32 v170, v170
	v_rcp_f32_e32 v171, v171
	v_mul_f32_e32 v16, v16, v164
	v_mul_f32_e32 v17, v17, v165
	v_mul_f32_e32 v18, v18, v166
	v_mul_f32_e32 v19, v19, v167
	v_mul_f32_e32 v12, v12, v168
	v_mul_f32_e32 v13, v13, v169
	v_mul_f32_e32 v14, v14, v170
	v_mul_f32_e32 v15, v15, v171
	v_cvt_pk_bf16_f32 v16, v16, v17
	v_cvt_pk_bf16_f32 v17, v18, v19
	v_cvt_pk_bf16_f32 v18, v12, v13
	v_cvt_pk_bf16_f32 v19, v14, v15
	global_store_dwordx4 v152, v[16:19], s[44:45] nt
	v_mul_f32_e32 v164, 0x3d372713, v8
	v_mul_f32_e32 v165, 0x3d372713, v9
	v_mul_f32_e32 v166, 0x3d372713, v10
	v_mul_f32_e32 v167, 0x3d372713, v11
	v_mul_f32_e32 v168, 0x3d372713, v4
	v_mul_f32_e32 v169, 0x3d372713, v5
	v_mul_f32_e32 v170, 0x3d372713, v6
	v_mul_f32_e32 v171, 0x3d372713, v7
	v_mul_f32_e32 v164, v8, v164
	v_mul_f32_e32 v165, v9, v165
	v_mul_f32_e32 v166, v10, v166
	v_mul_f32_e32 v167, v11, v167
	v_mul_f32_e32 v168, v4, v168
	v_mul_f32_e32 v169, v5, v169
	v_mul_f32_e32 v170, v6, v170
	v_mul_f32_e32 v171, v7, v171
	v_fma_f32 v164, v8, v164, v8
	v_fma_f32 v165, v9, v165, v9
	v_fma_f32 v166, v10, v166, v10
	v_fma_f32 v167, v11, v167, v11
	v_fma_f32 v168, v4, v168, v4
	v_fma_f32 v169, v5, v169, v5
	v_fma_f32 v170, v6, v170, v6
	v_fma_f32 v171, v7, v171, v7
	v_mul_f32_e32 v164, 0x3fcc422a, v164
	v_mul_f32_e32 v165, 0x3fcc422a, v165
	v_mul_f32_e32 v166, 0x3fcc422a, v166
	v_mul_f32_e32 v167, 0x3fcc422a, v167
	v_mul_f32_e32 v168, 0x3fcc422a, v168
	v_mul_f32_e32 v169, 0x3fcc422a, v169
	v_mul_f32_e32 v170, 0x3fcc422a, v170
	v_mul_f32_e32 v171, 0x3fcc422a, v171
	v_mul_f32_e32 v164, 0xbfb8aa3b, v164
	v_mul_f32_e32 v165, 0xbfb8aa3b, v165
	v_mul_f32_e32 v166, 0xbfb8aa3b, v166
	v_mul_f32_e32 v167, 0xbfb8aa3b, v167
	v_mul_f32_e32 v168, 0xbfb8aa3b, v168
	v_mul_f32_e32 v169, 0xbfb8aa3b, v169
	v_mul_f32_e32 v170, 0xbfb8aa3b, v170
	v_mul_f32_e32 v171, 0xbfb8aa3b, v171
	v_exp_f32_e32 v164, v164
	v_exp_f32_e32 v165, v165
	v_exp_f32_e32 v166, v166
	v_exp_f32_e32 v167, v167
	v_exp_f32_e32 v168, v168
	v_exp_f32_e32 v169, v169
	v_exp_f32_e32 v170, v170
	v_exp_f32_e32 v171, v171
	v_add_f32_e32 v164, 1.0, v164
	v_add_f32_e32 v165, 1.0, v165
	v_add_f32_e32 v166, 1.0, v166
	v_add_f32_e32 v167, 1.0, v167
	v_add_f32_e32 v168, 1.0, v168
	v_add_f32_e32 v169, 1.0, v169
	v_add_f32_e32 v170, 1.0, v170
	v_add_f32_e32 v171, 1.0, v171
	v_rcp_f32_e32 v164, v164
	v_rcp_f32_e32 v165, v165
	v_rcp_f32_e32 v166, v166
	v_rcp_f32_e32 v167, v167
	v_rcp_f32_e32 v168, v168
	v_rcp_f32_e32 v169, v169
	v_rcp_f32_e32 v170, v170
	v_rcp_f32_e32 v171, v171
	v_mul_f32_e32 v8, v8, v164
	v_mul_f32_e32 v9, v9, v165
	v_mul_f32_e32 v10, v10, v166
	v_mul_f32_e32 v11, v11, v167
	v_mul_f32_e32 v4, v4, v168
	v_mul_f32_e32 v5, v5, v169
	v_mul_f32_e32 v6, v6, v170
	v_mul_f32_e32 v7, v7, v171
	v_cvt_pk_bf16_f32 v8, v8, v9
	v_cvt_pk_bf16_f32 v9, v10, v11
	v_cvt_pk_bf16_f32 v10, v4, v5
	v_cvt_pk_bf16_f32 v11, v6, v7
	global_store_dwordx4 v152, v[8:11], s[44:45] offset:256 nt
	s_branch .LBB0_590
.Lepi_sig:
	v_mul_lo_u32 v152, v195, s30
	v_add_u32_e32 v153, s9, v191
	v_lshl_add_u32 v152, v153, 1, v152
	v_mul_f32_e32 v128, 0xbfb8aa3b, v128
	v_mul_f32_e32 v129, 0xbfb8aa3b, v129
	v_mul_f32_e32 v130, 0xbfb8aa3b, v130
	v_mul_f32_e32 v131, 0xbfb8aa3b, v131
	v_mul_f32_e32 v124, 0xbfb8aa3b, v124
	v_mul_f32_e32 v125, 0xbfb8aa3b, v125
	v_mul_f32_e32 v126, 0xbfb8aa3b, v126
	v_mul_f32_e32 v127, 0xbfb8aa3b, v127
	v_exp_f32_e32 v128, v128
	v_exp_f32_e32 v129, v129
	v_exp_f32_e32 v130, v130
	v_exp_f32_e32 v131, v131
	v_exp_f32_e32 v124, v124
	v_exp_f32_e32 v125, v125
	v_exp_f32_e32 v126, v126
	v_exp_f32_e32 v127, v127
	v_add_f32_e32 v128, 1.0, v128
	v_add_f32_e32 v129, 1.0, v129
	v_add_f32_e32 v130, 1.0, v130
	v_add_f32_e32 v131, 1.0, v131
	v_add_f32_e32 v124, 1.0, v124
	v_add_f32_e32 v125, 1.0, v125
	v_add_f32_e32 v126, 1.0, v126
	v_add_f32_e32 v127, 1.0, v127
	v_rcp_f32_e32 v128, v128
	v_rcp_f32_e32 v129, v129
	v_rcp_f32_e32 v130, v130
	v_rcp_f32_e32 v131, v131
	v_rcp_f32_e32 v124, v124
	v_rcp_f32_e32 v125, v125
	v_rcp_f32_e32 v126, v126
	v_rcp_f32_e32 v127, v127
	v_cvt_pk_bf16_f32 v128, v128, v129
	v_cvt_pk_bf16_f32 v129, v130, v131
	v_cvt_pk_bf16_f32 v130, v124, v125
	v_cvt_pk_bf16_f32 v131, v126, v127
	global_store_dwordx4 v152, v[128:131], s[44:45] nt
	v_mul_f32_e32 v120, 0xbfb8aa3b, v120
	v_mul_f32_e32 v121, 0xbfb8aa3b, v121
	v_mul_f32_e32 v122, 0xbfb8aa3b, v122
	v_mul_f32_e32 v123, 0xbfb8aa3b, v123
	v_mul_f32_e32 v116, 0xbfb8aa3b, v116
	v_mul_f32_e32 v117, 0xbfb8aa3b, v117
	v_mul_f32_e32 v118, 0xbfb8aa3b, v118
	v_mul_f32_e32 v119, 0xbfb8aa3b, v119
	v_exp_f32_e32 v120, v120
	v_exp_f32_e32 v121, v121
	v_exp_f32_e32 v122, v122
	v_exp_f32_e32 v123, v123
	v_exp_f32_e32 v116, v116
	v_exp_f32_e32 v117, v117
	v_exp_f32_e32 v118, v118
	v_exp_f32_e32 v119, v119
	v_add_f32_e32 v120, 1.0, v120
	v_add_f32_e32 v121, 1.0, v121
	v_add_f32_e32 v122, 1.0, v122
	v_add_f32_e32 v123, 1.0, v123
	v_add_f32_e32 v116, 1.0, v116
	v_add_f32_e32 v117, 1.0, v117
	v_add_f32_e32 v118, 1.0, v118
	v_add_f32_e32 v119, 1.0, v119
	v_rcp_f32_e32 v120, v120
	v_rcp_f32_e32 v121, v121
	v_rcp_f32_e32 v122, v122
	v_rcp_f32_e32 v123, v123
	v_rcp_f32_e32 v116, v116
	v_rcp_f32_e32 v117, v117
	v_rcp_f32_e32 v118, v118
	v_rcp_f32_e32 v119, v119
	v_cvt_pk_bf16_f32 v120, v120, v121
	v_cvt_pk_bf16_f32 v121, v122, v123
	v_cvt_pk_bf16_f32 v122, v116, v117
	v_cvt_pk_bf16_f32 v123, v118, v119
	global_store_dwordx4 v152, v[120:123], s[44:45] offset:256 nt
	v_add_u32_e32 v152, 0x26000, v152
	v_mul_f32_e32 v112, 0xbfb8aa3b, v112
	v_mul_f32_e32 v113, 0xbfb8aa3b, v113
	v_mul_f32_e32 v114, 0xbfb8aa3b, v114
	v_mul_f32_e32 v115, 0xbfb8aa3b, v115
	v_mul_f32_e32 v108, 0xbfb8aa3b, v108
	v_mul_f32_e32 v109, 0xbfb8aa3b, v109
	v_mul_f32_e32 v110, 0xbfb8aa3b, v110
	v_mul_f32_e32 v111, 0xbfb8aa3b, v111
	v_exp_f32_e32 v112, v112
	v_exp_f32_e32 v113, v113
	v_exp_f32_e32 v114, v114
	v_exp_f32_e32 v115, v115
	v_exp_f32_e32 v108, v108
	v_exp_f32_e32 v109, v109
	v_exp_f32_e32 v110, v110
	v_exp_f32_e32 v111, v111
	v_add_f32_e32 v112, 1.0, v112
	v_add_f32_e32 v113, 1.0, v113
	v_add_f32_e32 v114, 1.0, v114
	v_add_f32_e32 v115, 1.0, v115
	v_add_f32_e32 v108, 1.0, v108
	v_add_f32_e32 v109, 1.0, v109
	v_add_f32_e32 v110, 1.0, v110
	v_add_f32_e32 v111, 1.0, v111
	v_rcp_f32_e32 v112, v112
	v_rcp_f32_e32 v113, v113
	v_rcp_f32_e32 v114, v114
	v_rcp_f32_e32 v115, v115
	v_rcp_f32_e32 v108, v108
	v_rcp_f32_e32 v109, v109
	v_rcp_f32_e32 v110, v110
	v_rcp_f32_e32 v111, v111
	v_cvt_pk_bf16_f32 v112, v112, v113
	v_cvt_pk_bf16_f32 v113, v114, v115
	v_cvt_pk_bf16_f32 v114, v108, v109
	v_cvt_pk_bf16_f32 v115, v110, v111
	global_store_dwordx4 v152, v[112:115], s[44:45] nt
	v_mul_f32_e32 v104, 0xbfb8aa3b, v104
	v_mul_f32_e32 v105, 0xbfb8aa3b, v105
	v_mul_f32_e32 v106, 0xbfb8aa3b, v106
	v_mul_f32_e32 v107, 0xbfb8aa3b, v107
	v_mul_f32_e32 v100, 0xbfb8aa3b, v100
	v_mul_f32_e32 v101, 0xbfb8aa3b, v101
	v_mul_f32_e32 v102, 0xbfb8aa3b, v102
	v_mul_f32_e32 v103, 0xbfb8aa3b, v103
	v_exp_f32_e32 v104, v104
	v_exp_f32_e32 v105, v105
	v_exp_f32_e32 v106, v106
	v_exp_f32_e32 v107, v107
	v_exp_f32_e32 v100, v100
	v_exp_f32_e32 v101, v101
	v_exp_f32_e32 v102, v102
	v_exp_f32_e32 v103, v103
	v_add_f32_e32 v104, 1.0, v104
	v_add_f32_e32 v105, 1.0, v105
	v_add_f32_e32 v106, 1.0, v106
	v_add_f32_e32 v107, 1.0, v107
	v_add_f32_e32 v100, 1.0, v100
	v_add_f32_e32 v101, 1.0, v101
	v_add_f32_e32 v102, 1.0, v102
	v_add_f32_e32 v103, 1.0, v103
	v_rcp_f32_e32 v104, v104
	v_rcp_f32_e32 v105, v105
	v_rcp_f32_e32 v106, v106
	v_rcp_f32_e32 v107, v107
	v_rcp_f32_e32 v100, v100
	v_rcp_f32_e32 v101, v101
	v_rcp_f32_e32 v102, v102
	v_rcp_f32_e32 v103, v103
	v_cvt_pk_bf16_f32 v104, v104, v105
	v_cvt_pk_bf16_f32 v105, v106, v107
	v_cvt_pk_bf16_f32 v106, v100, v101
	v_cvt_pk_bf16_f32 v107, v102, v103
	global_store_dwordx4 v152, v[104:107], s[44:45] offset:256 nt
	v_add_u32_e32 v152, 0x26000, v152
	v_mul_f32_e32 v96, 0xbfb8aa3b, v96
	v_mul_f32_e32 v97, 0xbfb8aa3b, v97
	v_mul_f32_e32 v98, 0xbfb8aa3b, v98
	v_mul_f32_e32 v99, 0xbfb8aa3b, v99
	v_mul_f32_e32 v92, 0xbfb8aa3b, v92
	v_mul_f32_e32 v93, 0xbfb8aa3b, v93
	v_mul_f32_e32 v94, 0xbfb8aa3b, v94
	v_mul_f32_e32 v95, 0xbfb8aa3b, v95
	v_exp_f32_e32 v96, v96
	v_exp_f32_e32 v97, v97
	v_exp_f32_e32 v98, v98
	v_exp_f32_e32 v99, v99
	v_exp_f32_e32 v92, v92
	v_exp_f32_e32 v93, v93
	v_exp_f32_e32 v94, v94
	v_exp_f32_e32 v95, v95
	v_add_f32_e32 v96, 1.0, v96
	v_add_f32_e32 v97, 1.0, v97
	v_add_f32_e32 v98, 1.0, v98
	v_add_f32_e32 v99, 1.0, v99
	v_add_f32_e32 v92, 1.0, v92
	v_add_f32_e32 v93, 1.0, v93
	v_add_f32_e32 v94, 1.0, v94
	v_add_f32_e32 v95, 1.0, v95
	v_rcp_f32_e32 v96, v96
	v_rcp_f32_e32 v97, v97
	v_rcp_f32_e32 v98, v98
	v_rcp_f32_e32 v99, v99
	v_rcp_f32_e32 v92, v92
	v_rcp_f32_e32 v93, v93
	v_rcp_f32_e32 v94, v94
	v_rcp_f32_e32 v95, v95
	v_cvt_pk_bf16_f32 v96, v96, v97
	v_cvt_pk_bf16_f32 v97, v98, v99
	v_cvt_pk_bf16_f32 v98, v92, v93
	v_cvt_pk_bf16_f32 v99, v94, v95
	global_store_dwordx4 v152, v[96:99], s[44:45] nt
	v_mul_f32_e32 v88, 0xbfb8aa3b, v88
	v_mul_f32_e32 v89, 0xbfb8aa3b, v89
	v_mul_f32_e32 v90, 0xbfb8aa3b, v90
	v_mul_f32_e32 v91, 0xbfb8aa3b, v91
	v_mul_f32_e32 v84, 0xbfb8aa3b, v84
	v_mul_f32_e32 v85, 0xbfb8aa3b, v85
	v_mul_f32_e32 v86, 0xbfb8aa3b, v86
	v_mul_f32_e32 v87, 0xbfb8aa3b, v87
	v_exp_f32_e32 v88, v88
	v_exp_f32_e32 v89, v89
	v_exp_f32_e32 v90, v90
	v_exp_f32_e32 v91, v91
	v_exp_f32_e32 v84, v84
	v_exp_f32_e32 v85, v85
	v_exp_f32_e32 v86, v86
	v_exp_f32_e32 v87, v87
	v_add_f32_e32 v88, 1.0, v88
	v_add_f32_e32 v89, 1.0, v89
	v_add_f32_e32 v90, 1.0, v90
	v_add_f32_e32 v91, 1.0, v91
	v_add_f32_e32 v84, 1.0, v84
	v_add_f32_e32 v85, 1.0, v85
	v_add_f32_e32 v86, 1.0, v86
	v_add_f32_e32 v87, 1.0, v87
	v_rcp_f32_e32 v88, v88
	v_rcp_f32_e32 v89, v89
	v_rcp_f32_e32 v90, v90
	v_rcp_f32_e32 v91, v91
	v_rcp_f32_e32 v84, v84
	v_rcp_f32_e32 v85, v85
	v_rcp_f32_e32 v86, v86
	v_rcp_f32_e32 v87, v87
	v_cvt_pk_bf16_f32 v88, v88, v89
	v_cvt_pk_bf16_f32 v89, v90, v91
	v_cvt_pk_bf16_f32 v90, v84, v85
	v_cvt_pk_bf16_f32 v91, v86, v87
	global_store_dwordx4 v152, v[88:91], s[44:45] offset:256 nt
	v_add_u32_e32 v152, 0x26000, v152
	v_mul_f32_e32 v80, 0xbfb8aa3b, v80
	v_mul_f32_e32 v81, 0xbfb8aa3b, v81
	v_mul_f32_e32 v82, 0xbfb8aa3b, v82
	v_mul_f32_e32 v83, 0xbfb8aa3b, v83
	v_mul_f32_e32 v76, 0xbfb8aa3b, v76
	v_mul_f32_e32 v77, 0xbfb8aa3b, v77
	v_mul_f32_e32 v78, 0xbfb8aa3b, v78
	v_mul_f32_e32 v79, 0xbfb8aa3b, v79
	v_exp_f32_e32 v80, v80
	v_exp_f32_e32 v81, v81
	v_exp_f32_e32 v82, v82
	v_exp_f32_e32 v83, v83
	v_exp_f32_e32 v76, v76
	v_exp_f32_e32 v77, v77
	v_exp_f32_e32 v78, v78
	v_exp_f32_e32 v79, v79
	v_add_f32_e32 v80, 1.0, v80
	v_add_f32_e32 v81, 1.0, v81
	v_add_f32_e32 v82, 1.0, v82
	v_add_f32_e32 v83, 1.0, v83
	v_add_f32_e32 v76, 1.0, v76
	v_add_f32_e32 v77, 1.0, v77
	v_add_f32_e32 v78, 1.0, v78
	v_add_f32_e32 v79, 1.0, v79
	v_rcp_f32_e32 v80, v80
	v_rcp_f32_e32 v81, v81
	v_rcp_f32_e32 v82, v82
	v_rcp_f32_e32 v83, v83
	v_rcp_f32_e32 v76, v76
	v_rcp_f32_e32 v77, v77
	v_rcp_f32_e32 v78, v78
	v_rcp_f32_e32 v79, v79
	v_cvt_pk_bf16_f32 v80, v80, v81
	v_cvt_pk_bf16_f32 v81, v82, v83
	v_cvt_pk_bf16_f32 v82, v76, v77
	v_cvt_pk_bf16_f32 v83, v78, v79
	global_store_dwordx4 v152, v[80:83], s[44:45] nt
	v_mul_f32_e32 v72, 0xbfb8aa3b, v72
	v_mul_f32_e32 v73, 0xbfb8aa3b, v73
	v_mul_f32_e32 v74, 0xbfb8aa3b, v74
	v_mul_f32_e32 v75, 0xbfb8aa3b, v75
	v_mul_f32_e32 v68, 0xbfb8aa3b, v68
	v_mul_f32_e32 v69, 0xbfb8aa3b, v69
	v_mul_f32_e32 v70, 0xbfb8aa3b, v70
	v_mul_f32_e32 v71, 0xbfb8aa3b, v71
	v_exp_f32_e32 v72, v72
	v_exp_f32_e32 v73, v73
	v_exp_f32_e32 v74, v74
	v_exp_f32_e32 v75, v75
	v_exp_f32_e32 v68, v68
	v_exp_f32_e32 v69, v69
	v_exp_f32_e32 v70, v70
	v_exp_f32_e32 v71, v71
	v_add_f32_e32 v72, 1.0, v72
	v_add_f32_e32 v73, 1.0, v73
	v_add_f32_e32 v74, 1.0, v74
	v_add_f32_e32 v75, 1.0, v75
	v_add_f32_e32 v68, 1.0, v68
	v_add_f32_e32 v69, 1.0, v69
	v_add_f32_e32 v70, 1.0, v70
	v_add_f32_e32 v71, 1.0, v71
	v_rcp_f32_e32 v72, v72
	v_rcp_f32_e32 v73, v73
	v_rcp_f32_e32 v74, v74
	v_rcp_f32_e32 v75, v75
	v_rcp_f32_e32 v68, v68
	v_rcp_f32_e32 v69, v69
	v_rcp_f32_e32 v70, v70
	v_rcp_f32_e32 v71, v71
	v_cvt_pk_bf16_f32 v72, v72, v73
	v_cvt_pk_bf16_f32 v73, v74, v75
	v_cvt_pk_bf16_f32 v74, v68, v69
	v_cvt_pk_bf16_f32 v75, v70, v71
	global_store_dwordx4 v152, v[72:75], s[44:45] offset:256 nt
	v_add_u32_e32 v152, 0xbe000, v152
	v_mul_f32_e32 v64, 0xbfb8aa3b, v64
	v_mul_f32_e32 v65, 0xbfb8aa3b, v65
	v_mul_f32_e32 v66, 0xbfb8aa3b, v66
	v_mul_f32_e32 v67, 0xbfb8aa3b, v67
	v_mul_f32_e32 v60, 0xbfb8aa3b, v60
	v_mul_f32_e32 v61, 0xbfb8aa3b, v61
	v_mul_f32_e32 v62, 0xbfb8aa3b, v62
	v_mul_f32_e32 v63, 0xbfb8aa3b, v63
	v_exp_f32_e32 v64, v64
	v_exp_f32_e32 v65, v65
	v_exp_f32_e32 v66, v66
	v_exp_f32_e32 v67, v67
	v_exp_f32_e32 v60, v60
	v_exp_f32_e32 v61, v61
	v_exp_f32_e32 v62, v62
	v_exp_f32_e32 v63, v63
	v_add_f32_e32 v64, 1.0, v64
	v_add_f32_e32 v65, 1.0, v65
	v_add_f32_e32 v66, 1.0, v66
	v_add_f32_e32 v67, 1.0, v67
	v_add_f32_e32 v60, 1.0, v60
	v_add_f32_e32 v61, 1.0, v61
	v_add_f32_e32 v62, 1.0, v62
	v_add_f32_e32 v63, 1.0, v63
	v_rcp_f32_e32 v64, v64
	v_rcp_f32_e32 v65, v65
	v_rcp_f32_e32 v66, v66
	v_rcp_f32_e32 v67, v67
	v_rcp_f32_e32 v60, v60
	v_rcp_f32_e32 v61, v61
	v_rcp_f32_e32 v62, v62
	v_rcp_f32_e32 v63, v63
	v_cvt_pk_bf16_f32 v64, v64, v65
	v_cvt_pk_bf16_f32 v65, v66, v67
	v_cvt_pk_bf16_f32 v66, v60, v61
	v_cvt_pk_bf16_f32 v67, v62, v63
	global_store_dwordx4 v152, v[64:67], s[44:45] nt
	v_mul_f32_e32 v56, 0xbfb8aa3b, v56
	v_mul_f32_e32 v57, 0xbfb8aa3b, v57
	v_mul_f32_e32 v58, 0xbfb8aa3b, v58
	v_mul_f32_e32 v59, 0xbfb8aa3b, v59
	v_mul_f32_e32 v52, 0xbfb8aa3b, v52
	v_mul_f32_e32 v53, 0xbfb8aa3b, v53
	v_mul_f32_e32 v54, 0xbfb8aa3b, v54
	v_mul_f32_e32 v55, 0xbfb8aa3b, v55
	v_exp_f32_e32 v56, v56
	v_exp_f32_e32 v57, v57
	v_exp_f32_e32 v58, v58
	v_exp_f32_e32 v59, v59
	v_exp_f32_e32 v52, v52
	v_exp_f32_e32 v53, v53
	v_exp_f32_e32 v54, v54
	v_exp_f32_e32 v55, v55
	v_add_f32_e32 v56, 1.0, v56
	v_add_f32_e32 v57, 1.0, v57
	v_add_f32_e32 v58, 1.0, v58
	v_add_f32_e32 v59, 1.0, v59
	v_add_f32_e32 v52, 1.0, v52
	v_add_f32_e32 v53, 1.0, v53
	v_add_f32_e32 v54, 1.0, v54
	v_add_f32_e32 v55, 1.0, v55
	v_rcp_f32_e32 v56, v56
	v_rcp_f32_e32 v57, v57
	v_rcp_f32_e32 v58, v58
	v_rcp_f32_e32 v59, v59
	v_rcp_f32_e32 v52, v52
	v_rcp_f32_e32 v53, v53
	v_rcp_f32_e32 v54, v54
	v_rcp_f32_e32 v55, v55
	v_cvt_pk_bf16_f32 v56, v56, v57
	v_cvt_pk_bf16_f32 v57, v58, v59
	v_cvt_pk_bf16_f32 v58, v52, v53
	v_cvt_pk_bf16_f32 v59, v54, v55
	global_store_dwordx4 v152, v[56:59], s[44:45] offset:256 nt
	v_add_u32_e32 v152, 0x26000, v152
	v_mul_f32_e32 v48, 0xbfb8aa3b, v48
	v_mul_f32_e32 v49, 0xbfb8aa3b, v49
	v_mul_f32_e32 v50, 0xbfb8aa3b, v50
	v_mul_f32_e32 v51, 0xbfb8aa3b, v51
	v_mul_f32_e32 v44, 0xbfb8aa3b, v44
	v_mul_f32_e32 v45, 0xbfb8aa3b, v45
	v_mul_f32_e32 v46, 0xbfb8aa3b, v46
	v_mul_f32_e32 v47, 0xbfb8aa3b, v47
	v_exp_f32_e32 v48, v48
	v_exp_f32_e32 v49, v49
	v_exp_f32_e32 v50, v50
	v_exp_f32_e32 v51, v51
	v_exp_f32_e32 v44, v44
	v_exp_f32_e32 v45, v45
	v_exp_f32_e32 v46, v46
	v_exp_f32_e32 v47, v47
	v_add_f32_e32 v48, 1.0, v48
	v_add_f32_e32 v49, 1.0, v49
	v_add_f32_e32 v50, 1.0, v50
	v_add_f32_e32 v51, 1.0, v51
	v_add_f32_e32 v44, 1.0, v44
	v_add_f32_e32 v45, 1.0, v45
	v_add_f32_e32 v46, 1.0, v46
	v_add_f32_e32 v47, 1.0, v47
	v_rcp_f32_e32 v48, v48
	v_rcp_f32_e32 v49, v49
	v_rcp_f32_e32 v50, v50
	v_rcp_f32_e32 v51, v51
	v_rcp_f32_e32 v44, v44
	v_rcp_f32_e32 v45, v45
	v_rcp_f32_e32 v46, v46
	v_rcp_f32_e32 v47, v47
	v_cvt_pk_bf16_f32 v48, v48, v49
	v_cvt_pk_bf16_f32 v49, v50, v51
	v_cvt_pk_bf16_f32 v50, v44, v45
	v_cvt_pk_bf16_f32 v51, v46, v47
	global_store_dwordx4 v152, v[48:51], s[44:45] nt
	v_mul_f32_e32 v40, 0xbfb8aa3b, v40
	v_mul_f32_e32 v41, 0xbfb8aa3b, v41
	v_mul_f32_e32 v42, 0xbfb8aa3b, v42
	v_mul_f32_e32 v43, 0xbfb8aa3b, v43
	v_mul_f32_e32 v36, 0xbfb8aa3b, v36
	v_mul_f32_e32 v37, 0xbfb8aa3b, v37
	v_mul_f32_e32 v38, 0xbfb8aa3b, v38
	v_mul_f32_e32 v39, 0xbfb8aa3b, v39
	v_exp_f32_e32 v40, v40
	v_exp_f32_e32 v41, v41
	v_exp_f32_e32 v42, v42
	v_exp_f32_e32 v43, v43
	v_exp_f32_e32 v36, v36
	v_exp_f32_e32 v37, v37
	v_exp_f32_e32 v38, v38
	v_exp_f32_e32 v39, v39
	v_add_f32_e32 v40, 1.0, v40
	v_add_f32_e32 v41, 1.0, v41
	v_add_f32_e32 v42, 1.0, v42
	v_add_f32_e32 v43, 1.0, v43
	v_add_f32_e32 v36, 1.0, v36
	v_add_f32_e32 v37, 1.0, v37
	v_add_f32_e32 v38, 1.0, v38
	v_add_f32_e32 v39, 1.0, v39
	v_rcp_f32_e32 v40, v40
	v_rcp_f32_e32 v41, v41
	v_rcp_f32_e32 v42, v42
	v_rcp_f32_e32 v43, v43
	v_rcp_f32_e32 v36, v36
	v_rcp_f32_e32 v37, v37
	v_rcp_f32_e32 v38, v38
	v_rcp_f32_e32 v39, v39
	v_cvt_pk_bf16_f32 v40, v40, v41
	v_cvt_pk_bf16_f32 v41, v42, v43
	v_cvt_pk_bf16_f32 v42, v36, v37
	v_cvt_pk_bf16_f32 v43, v38, v39
	global_store_dwordx4 v152, v[40:43], s[44:45] offset:256 nt
	v_add_u32_e32 v152, 0x26000, v152
	v_mul_f32_e32 v32, 0xbfb8aa3b, v32
	v_mul_f32_e32 v33, 0xbfb8aa3b, v33
	v_mul_f32_e32 v34, 0xbfb8aa3b, v34
	v_mul_f32_e32 v35, 0xbfb8aa3b, v35
	v_mul_f32_e32 v28, 0xbfb8aa3b, v28
	v_mul_f32_e32 v29, 0xbfb8aa3b, v29
	v_mul_f32_e32 v30, 0xbfb8aa3b, v30
	v_mul_f32_e32 v31, 0xbfb8aa3b, v31
	v_exp_f32_e32 v32, v32
	v_exp_f32_e32 v33, v33
	v_exp_f32_e32 v34, v34
	v_exp_f32_e32 v35, v35
	v_exp_f32_e32 v28, v28
	v_exp_f32_e32 v29, v29
	v_exp_f32_e32 v30, v30
	v_exp_f32_e32 v31, v31
	v_add_f32_e32 v32, 1.0, v32
	v_add_f32_e32 v33, 1.0, v33
	v_add_f32_e32 v34, 1.0, v34
	v_add_f32_e32 v35, 1.0, v35
	v_add_f32_e32 v28, 1.0, v28
	v_add_f32_e32 v29, 1.0, v29
	v_add_f32_e32 v30, 1.0, v30
	v_add_f32_e32 v31, 1.0, v31
	v_rcp_f32_e32 v32, v32
	v_rcp_f32_e32 v33, v33
	v_rcp_f32_e32 v34, v34
	v_rcp_f32_e32 v35, v35
	v_rcp_f32_e32 v28, v28
	v_rcp_f32_e32 v29, v29
	v_rcp_f32_e32 v30, v30
	v_rcp_f32_e32 v31, v31
	v_cvt_pk_bf16_f32 v32, v32, v33
	v_cvt_pk_bf16_f32 v33, v34, v35
	v_cvt_pk_bf16_f32 v34, v28, v29
	v_cvt_pk_bf16_f32 v35, v30, v31
	global_store_dwordx4 v152, v[32:35], s[44:45] nt
	v_mul_f32_e32 v24, 0xbfb8aa3b, v24
	v_mul_f32_e32 v25, 0xbfb8aa3b, v25
	v_mul_f32_e32 v26, 0xbfb8aa3b, v26
	v_mul_f32_e32 v27, 0xbfb8aa3b, v27
	v_mul_f32_e32 v20, 0xbfb8aa3b, v20
	v_mul_f32_e32 v21, 0xbfb8aa3b, v21
	v_mul_f32_e32 v22, 0xbfb8aa3b, v22
	v_mul_f32_e32 v23, 0xbfb8aa3b, v23
	v_exp_f32_e32 v24, v24
	v_exp_f32_e32 v25, v25
	v_exp_f32_e32 v26, v26
	v_exp_f32_e32 v27, v27
	v_exp_f32_e32 v20, v20
	v_exp_f32_e32 v21, v21
	v_exp_f32_e32 v22, v22
	v_exp_f32_e32 v23, v23
	v_add_f32_e32 v24, 1.0, v24
	v_add_f32_e32 v25, 1.0, v25
	v_add_f32_e32 v26, 1.0, v26
	v_add_f32_e32 v27, 1.0, v27
	v_add_f32_e32 v20, 1.0, v20
	v_add_f32_e32 v21, 1.0, v21
	v_add_f32_e32 v22, 1.0, v22
	v_add_f32_e32 v23, 1.0, v23
	v_rcp_f32_e32 v24, v24
	v_rcp_f32_e32 v25, v25
	v_rcp_f32_e32 v26, v26
	v_rcp_f32_e32 v27, v27
	v_rcp_f32_e32 v20, v20
	v_rcp_f32_e32 v21, v21
	v_rcp_f32_e32 v22, v22
	v_rcp_f32_e32 v23, v23
	v_cvt_pk_bf16_f32 v24, v24, v25
	v_cvt_pk_bf16_f32 v25, v26, v27
	v_cvt_pk_bf16_f32 v26, v20, v21
	v_cvt_pk_bf16_f32 v27, v22, v23
	global_store_dwordx4 v152, v[24:27], s[44:45] offset:256 nt
	v_add_u32_e32 v152, 0x26000, v152
	v_mul_f32_e32 v16, 0xbfb8aa3b, v16
	v_mul_f32_e32 v17, 0xbfb8aa3b, v17
	v_mul_f32_e32 v18, 0xbfb8aa3b, v18
	v_mul_f32_e32 v19, 0xbfb8aa3b, v19
	v_mul_f32_e32 v12, 0xbfb8aa3b, v12
	v_mul_f32_e32 v13, 0xbfb8aa3b, v13
	v_mul_f32_e32 v14, 0xbfb8aa3b, v14
	v_mul_f32_e32 v15, 0xbfb8aa3b, v15
	v_exp_f32_e32 v16, v16
	v_exp_f32_e32 v17, v17
	v_exp_f32_e32 v18, v18
	v_exp_f32_e32 v19, v19
	v_exp_f32_e32 v12, v12
	v_exp_f32_e32 v13, v13
	v_exp_f32_e32 v14, v14
	v_exp_f32_e32 v15, v15
	v_add_f32_e32 v16, 1.0, v16
	v_add_f32_e32 v17, 1.0, v17
	v_add_f32_e32 v18, 1.0, v18
	v_add_f32_e32 v19, 1.0, v19
	v_add_f32_e32 v12, 1.0, v12
	v_add_f32_e32 v13, 1.0, v13
	v_add_f32_e32 v14, 1.0, v14
	v_add_f32_e32 v15, 1.0, v15
	v_rcp_f32_e32 v16, v16
	v_rcp_f32_e32 v17, v17
	v_rcp_f32_e32 v18, v18
	v_rcp_f32_e32 v19, v19
	v_rcp_f32_e32 v12, v12
	v_rcp_f32_e32 v13, v13
	v_rcp_f32_e32 v14, v14
	v_rcp_f32_e32 v15, v15
	v_cvt_pk_bf16_f32 v16, v16, v17
	v_cvt_pk_bf16_f32 v17, v18, v19
	v_cvt_pk_bf16_f32 v18, v12, v13
	v_cvt_pk_bf16_f32 v19, v14, v15
	global_store_dwordx4 v152, v[16:19], s[44:45] nt
	v_mul_f32_e32 v8, 0xbfb8aa3b, v8
	v_mul_f32_e32 v9, 0xbfb8aa3b, v9
	v_mul_f32_e32 v10, 0xbfb8aa3b, v10
	v_mul_f32_e32 v11, 0xbfb8aa3b, v11
	v_mul_f32_e32 v4, 0xbfb8aa3b, v4
	v_mul_f32_e32 v5, 0xbfb8aa3b, v5
	v_mul_f32_e32 v6, 0xbfb8aa3b, v6
	v_mul_f32_e32 v7, 0xbfb8aa3b, v7
	v_exp_f32_e32 v8, v8
	v_exp_f32_e32 v9, v9
	v_exp_f32_e32 v10, v10
	v_exp_f32_e32 v11, v11
	v_exp_f32_e32 v4, v4
	v_exp_f32_e32 v5, v5
	v_exp_f32_e32 v6, v6
	v_exp_f32_e32 v7, v7
	v_add_f32_e32 v8, 1.0, v8
	v_add_f32_e32 v9, 1.0, v9
	v_add_f32_e32 v10, 1.0, v10
	v_add_f32_e32 v11, 1.0, v11
	v_add_f32_e32 v4, 1.0, v4
	v_add_f32_e32 v5, 1.0, v5
	v_add_f32_e32 v6, 1.0, v6
	v_add_f32_e32 v7, 1.0, v7
	v_rcp_f32_e32 v8, v8
	v_rcp_f32_e32 v9, v9
	v_rcp_f32_e32 v10, v10
	v_rcp_f32_e32 v11, v11
	v_rcp_f32_e32 v4, v4
	v_rcp_f32_e32 v5, v5
	v_rcp_f32_e32 v6, v6
	v_rcp_f32_e32 v7, v7
	v_cvt_pk_bf16_f32 v8, v8, v9
	v_cvt_pk_bf16_f32 v9, v10, v11
	v_cvt_pk_bf16_f32 v10, v4, v5
	v_cvt_pk_bf16_f32 v11, v6, v7
	global_store_dwordx4 v152, v[8:11], s[44:45] offset:256 nt
	s_branch .LBB0_590

.LBB0_592:
	v_mul_lo_u32 v152, v195, s96
	v_lshl_or_b32 v153, s50, 9, v193
	v_add_u32_e32 v152, v152, v153
	v_mul_f32_e32 v164, 0xbfb8aa3b, v128
	v_mul_f32_e32 v165, 0xbfb8aa3b, v129
	v_mul_f32_e32 v166, 0xbfb8aa3b, v130
	v_mul_f32_e32 v167, 0xbfb8aa3b, v131
	v_mul_f32_e32 v168, 0xbfb8aa3b, v124
	v_mul_f32_e32 v169, 0xbfb8aa3b, v125
	v_mul_f32_e32 v170, 0xbfb8aa3b, v126
	v_mul_f32_e32 v171, 0xbfb8aa3b, v127
	v_exp_f32_e32 v164, v164
	v_exp_f32_e32 v165, v165
	v_exp_f32_e32 v166, v166
	v_exp_f32_e32 v167, v167
	v_exp_f32_e32 v168, v168
	v_exp_f32_e32 v169, v169
	v_exp_f32_e32 v170, v170
	v_exp_f32_e32 v171, v171
	v_add_f32_e32 v164, 1.0, v164
	v_add_f32_e32 v165, 1.0, v165
	v_add_f32_e32 v166, 1.0, v166
	v_add_f32_e32 v167, 1.0, v167
	v_add_f32_e32 v168, 1.0, v168
	v_add_f32_e32 v169, 1.0, v169
	v_add_f32_e32 v170, 1.0, v170
	v_add_f32_e32 v171, 1.0, v171
	v_rcp_f32_e32 v164, v164
	v_rcp_f32_e32 v165, v165
	v_rcp_f32_e32 v166, v166
	v_rcp_f32_e32 v167, v167
	v_rcp_f32_e32 v168, v168
	v_rcp_f32_e32 v169, v169
	v_rcp_f32_e32 v170, v170
	v_rcp_f32_e32 v171, v171
	v_mul_f32_e32 v128, v128, v164
	v_mul_f32_e32 v129, v129, v165
	v_mul_f32_e32 v130, v130, v166
	v_mul_f32_e32 v131, v131, v167
	v_mul_f32_e32 v124, v124, v168
	v_mul_f32_e32 v125, v125, v169
	v_mul_f32_e32 v126, v126, v170
	v_mul_f32_e32 v127, v127, v171
	v_cvt_pk_bf16_f32 v128, v128, v129
	v_cvt_pk_bf16_f32 v129, v130, v131
	v_cvt_pk_bf16_f32 v130, v124, v125
	v_cvt_pk_bf16_f32 v131, v126, v127
	global_store_dwordx4 v152, v[128:131], s[42:43] offset:2048 nt
	v_mul_f32_e32 v164, 0xbfb8aa3b, v120
	v_mul_f32_e32 v165, 0xbfb8aa3b, v121
	v_mul_f32_e32 v166, 0xbfb8aa3b, v122
	v_mul_f32_e32 v167, 0xbfb8aa3b, v123
	v_mul_f32_e32 v168, 0xbfb8aa3b, v116
	v_mul_f32_e32 v169, 0xbfb8aa3b, v117
	v_mul_f32_e32 v170, 0xbfb8aa3b, v118
	v_mul_f32_e32 v171, 0xbfb8aa3b, v119
	v_exp_f32_e32 v164, v164
	v_exp_f32_e32 v165, v165
	v_exp_f32_e32 v166, v166
	v_exp_f32_e32 v167, v167
	v_exp_f32_e32 v168, v168
	v_exp_f32_e32 v169, v169
	v_exp_f32_e32 v170, v170
	v_exp_f32_e32 v171, v171
	v_add_f32_e32 v164, 1.0, v164
	v_add_f32_e32 v165, 1.0, v165
	v_add_f32_e32 v166, 1.0, v166
	v_add_f32_e32 v167, 1.0, v167
	v_add_f32_e32 v168, 1.0, v168
	v_add_f32_e32 v169, 1.0, v169
	v_add_f32_e32 v170, 1.0, v170
	v_add_f32_e32 v171, 1.0, v171
	v_rcp_f32_e32 v164, v164
	v_rcp_f32_e32 v165, v165
	v_rcp_f32_e32 v166, v166
	v_rcp_f32_e32 v167, v167
	v_rcp_f32_e32 v168, v168
	v_rcp_f32_e32 v169, v169
	v_rcp_f32_e32 v170, v170
	v_rcp_f32_e32 v171, v171
	v_mul_f32_e32 v120, v120, v164
	v_mul_f32_e32 v121, v121, v165
	v_mul_f32_e32 v122, v122, v166
	v_mul_f32_e32 v123, v123, v167
	v_mul_f32_e32 v116, v116, v168
	v_mul_f32_e32 v117, v117, v169
	v_mul_f32_e32 v118, v118, v170
	v_mul_f32_e32 v119, v119, v171
	v_cvt_pk_bf16_f32 v120, v120, v121
	v_cvt_pk_bf16_f32 v121, v122, v123
	v_cvt_pk_bf16_f32 v122, v116, v117
	v_cvt_pk_bf16_f32 v123, v118, v119
	global_store_dwordx4 v152, v[120:123], s[42:43] offset:2304 nt
	v_add_u32_e32 v152, 0xc000, v152
	v_mul_f32_e32 v164, 0xbfb8aa3b, v112
	v_mul_f32_e32 v165, 0xbfb8aa3b, v113
	v_mul_f32_e32 v166, 0xbfb8aa3b, v114
	v_mul_f32_e32 v167, 0xbfb8aa3b, v115
	v_mul_f32_e32 v168, 0xbfb8aa3b, v108
	v_mul_f32_e32 v169, 0xbfb8aa3b, v109
	v_mul_f32_e32 v170, 0xbfb8aa3b, v110
	v_mul_f32_e32 v171, 0xbfb8aa3b, v111
	v_exp_f32_e32 v164, v164
	v_exp_f32_e32 v165, v165
	v_exp_f32_e32 v166, v166
	v_exp_f32_e32 v167, v167
	v_exp_f32_e32 v168, v168
	v_exp_f32_e32 v169, v169
	v_exp_f32_e32 v170, v170
	v_exp_f32_e32 v171, v171
	v_add_f32_e32 v164, 1.0, v164
	v_add_f32_e32 v165, 1.0, v165
	v_add_f32_e32 v166, 1.0, v166
	v_add_f32_e32 v167, 1.0, v167
	v_add_f32_e32 v168, 1.0, v168
	v_add_f32_e32 v169, 1.0, v169
	v_add_f32_e32 v170, 1.0, v170
	v_add_f32_e32 v171, 1.0, v171
	v_rcp_f32_e32 v164, v164
	v_rcp_f32_e32 v165, v165
	v_rcp_f32_e32 v166, v166
	v_rcp_f32_e32 v167, v167
	v_rcp_f32_e32 v168, v168
	v_rcp_f32_e32 v169, v169
	v_rcp_f32_e32 v170, v170
	v_rcp_f32_e32 v171, v171
	v_mul_f32_e32 v112, v112, v164
	v_mul_f32_e32 v113, v113, v165
	v_mul_f32_e32 v114, v114, v166
	v_mul_f32_e32 v115, v115, v167
	v_mul_f32_e32 v108, v108, v168
	v_mul_f32_e32 v109, v109, v169
	v_mul_f32_e32 v110, v110, v170
	v_mul_f32_e32 v111, v111, v171
	v_cvt_pk_bf16_f32 v112, v112, v113
	v_cvt_pk_bf16_f32 v113, v114, v115
	v_cvt_pk_bf16_f32 v114, v108, v109
	v_cvt_pk_bf16_f32 v115, v110, v111
	global_store_dwordx4 v152, v[112:115], s[42:43] offset:2048 nt
	v_mul_f32_e32 v164, 0xbfb8aa3b, v104
	v_mul_f32_e32 v165, 0xbfb8aa3b, v105
	v_mul_f32_e32 v166, 0xbfb8aa3b, v106
	v_mul_f32_e32 v167, 0xbfb8aa3b, v107
	v_mul_f32_e32 v168, 0xbfb8aa3b, v100
	v_mul_f32_e32 v169, 0xbfb8aa3b, v101
	v_mul_f32_e32 v170, 0xbfb8aa3b, v102
	v_mul_f32_e32 v171, 0xbfb8aa3b, v103
	v_exp_f32_e32 v164, v164
	v_exp_f32_e32 v165, v165
	v_exp_f32_e32 v166, v166
	v_exp_f32_e32 v167, v167
	v_exp_f32_e32 v168, v168
	v_exp_f32_e32 v169, v169
	v_exp_f32_e32 v170, v170
	v_exp_f32_e32 v171, v171
	v_add_f32_e32 v164, 1.0, v164
	v_add_f32_e32 v165, 1.0, v165
	v_add_f32_e32 v166, 1.0, v166
	v_add_f32_e32 v167, 1.0, v167
	v_add_f32_e32 v168, 1.0, v168
	v_add_f32_e32 v169, 1.0, v169
	v_add_f32_e32 v170, 1.0, v170
	v_add_f32_e32 v171, 1.0, v171
	v_rcp_f32_e32 v164, v164
	v_rcp_f32_e32 v165, v165
	v_rcp_f32_e32 v166, v166
	v_rcp_f32_e32 v167, v167
	v_rcp_f32_e32 v168, v168
	v_rcp_f32_e32 v169, v169
	v_rcp_f32_e32 v170, v170
	v_rcp_f32_e32 v171, v171
	v_mul_f32_e32 v104, v104, v164
	v_mul_f32_e32 v105, v105, v165
	v_mul_f32_e32 v106, v106, v166
	v_mul_f32_e32 v107, v107, v167
	v_mul_f32_e32 v100, v100, v168
	v_mul_f32_e32 v101, v101, v169
	v_mul_f32_e32 v102, v102, v170
	v_mul_f32_e32 v103, v103, v171
	v_cvt_pk_bf16_f32 v104, v104, v105
	v_cvt_pk_bf16_f32 v105, v106, v107
	v_cvt_pk_bf16_f32 v106, v100, v101
	v_cvt_pk_bf16_f32 v107, v102, v103
	global_store_dwordx4 v152, v[104:107], s[42:43] offset:2304 nt
	v_add_u32_e32 v152, 0xc000, v152
	v_mul_f32_e32 v164, 0xbfb8aa3b, v96
	v_mul_f32_e32 v165, 0xbfb8aa3b, v97
	v_mul_f32_e32 v166, 0xbfb8aa3b, v98
	v_mul_f32_e32 v167, 0xbfb8aa3b, v99
	v_mul_f32_e32 v168, 0xbfb8aa3b, v92
	v_mul_f32_e32 v169, 0xbfb8aa3b, v93
	v_mul_f32_e32 v170, 0xbfb8aa3b, v94
	v_mul_f32_e32 v171, 0xbfb8aa3b, v95
	v_exp_f32_e32 v164, v164
	v_exp_f32_e32 v165, v165
	v_exp_f32_e32 v166, v166
	v_exp_f32_e32 v167, v167
	v_exp_f32_e32 v168, v168
	v_exp_f32_e32 v169, v169
	v_exp_f32_e32 v170, v170
	v_exp_f32_e32 v171, v171
	v_add_f32_e32 v164, 1.0, v164
	v_add_f32_e32 v165, 1.0, v165
	v_add_f32_e32 v166, 1.0, v166
	v_add_f32_e32 v167, 1.0, v167
	v_add_f32_e32 v168, 1.0, v168
	v_add_f32_e32 v169, 1.0, v169
	v_add_f32_e32 v170, 1.0, v170
	v_add_f32_e32 v171, 1.0, v171
	v_rcp_f32_e32 v164, v164
	v_rcp_f32_e32 v165, v165
	v_rcp_f32_e32 v166, v166
	v_rcp_f32_e32 v167, v167
	v_rcp_f32_e32 v168, v168
	v_rcp_f32_e32 v169, v169
	v_rcp_f32_e32 v170, v170
	v_rcp_f32_e32 v171, v171
	v_mul_f32_e32 v96, v96, v164
	v_mul_f32_e32 v97, v97, v165
	v_mul_f32_e32 v98, v98, v166
	v_mul_f32_e32 v99, v99, v167
	v_mul_f32_e32 v92, v92, v168
	v_mul_f32_e32 v93, v93, v169
	v_mul_f32_e32 v94, v94, v170
	v_mul_f32_e32 v95, v95, v171
	v_cvt_pk_bf16_f32 v96, v96, v97
	v_cvt_pk_bf16_f32 v97, v98, v99
	v_cvt_pk_bf16_f32 v98, v92, v93
	v_cvt_pk_bf16_f32 v99, v94, v95
	global_store_dwordx4 v152, v[96:99], s[42:43] offset:2048 nt
	v_mul_f32_e32 v164, 0xbfb8aa3b, v88
	v_mul_f32_e32 v165, 0xbfb8aa3b, v89
	v_mul_f32_e32 v166, 0xbfb8aa3b, v90
	v_mul_f32_e32 v167, 0xbfb8aa3b, v91
	v_mul_f32_e32 v168, 0xbfb8aa3b, v84
	v_mul_f32_e32 v169, 0xbfb8aa3b, v85
	v_mul_f32_e32 v170, 0xbfb8aa3b, v86
	v_mul_f32_e32 v171, 0xbfb8aa3b, v87
	v_exp_f32_e32 v164, v164
	v_exp_f32_e32 v165, v165
	v_exp_f32_e32 v166, v166
	v_exp_f32_e32 v167, v167
	v_exp_f32_e32 v168, v168
	v_exp_f32_e32 v169, v169
	v_exp_f32_e32 v170, v170
	v_exp_f32_e32 v171, v171
	v_add_f32_e32 v164, 1.0, v164
	v_add_f32_e32 v165, 1.0, v165
	v_add_f32_e32 v166, 1.0, v166
	v_add_f32_e32 v167, 1.0, v167
	v_add_f32_e32 v168, 1.0, v168
	v_add_f32_e32 v169, 1.0, v169
	v_add_f32_e32 v170, 1.0, v170
	v_add_f32_e32 v171, 1.0, v171
	v_rcp_f32_e32 v164, v164
	v_rcp_f32_e32 v165, v165
	v_rcp_f32_e32 v166, v166
	v_rcp_f32_e32 v167, v167
	v_rcp_f32_e32 v168, v168
	v_rcp_f32_e32 v169, v169
	v_rcp_f32_e32 v170, v170
	v_rcp_f32_e32 v171, v171
	v_mul_f32_e32 v88, v88, v164
	v_mul_f32_e32 v89, v89, v165
	v_mul_f32_e32 v90, v90, v166
	v_mul_f32_e32 v91, v91, v167
	v_mul_f32_e32 v84, v84, v168
	v_mul_f32_e32 v85, v85, v169
	v_mul_f32_e32 v86, v86, v170
	v_mul_f32_e32 v87, v87, v171
	v_cvt_pk_bf16_f32 v88, v88, v89
	v_cvt_pk_bf16_f32 v89, v90, v91
	v_cvt_pk_bf16_f32 v90, v84, v85
	v_cvt_pk_bf16_f32 v91, v86, v87
	global_store_dwordx4 v152, v[88:91], s[42:43] offset:2304 nt
	v_add_u32_e32 v152, 0xc000, v152
	v_mul_f32_e32 v164, 0xbfb8aa3b, v80
	v_mul_f32_e32 v165, 0xbfb8aa3b, v81
	v_mul_f32_e32 v166, 0xbfb8aa3b, v82
	v_mul_f32_e32 v167, 0xbfb8aa3b, v83
	v_mul_f32_e32 v168, 0xbfb8aa3b, v76
	v_mul_f32_e32 v169, 0xbfb8aa3b, v77
	v_mul_f32_e32 v170, 0xbfb8aa3b, v78
	v_mul_f32_e32 v171, 0xbfb8aa3b, v79
	v_exp_f32_e32 v164, v164
	v_exp_f32_e32 v165, v165
	v_exp_f32_e32 v166, v166
	v_exp_f32_e32 v167, v167
	v_exp_f32_e32 v168, v168
	v_exp_f32_e32 v169, v169
	v_exp_f32_e32 v170, v170
	v_exp_f32_e32 v171, v171
	v_add_f32_e32 v164, 1.0, v164
	v_add_f32_e32 v165, 1.0, v165
	v_add_f32_e32 v166, 1.0, v166
	v_add_f32_e32 v167, 1.0, v167
	v_add_f32_e32 v168, 1.0, v168
	v_add_f32_e32 v169, 1.0, v169
	v_add_f32_e32 v170, 1.0, v170
	v_add_f32_e32 v171, 1.0, v171
	v_rcp_f32_e32 v164, v164
	v_rcp_f32_e32 v165, v165
	v_rcp_f32_e32 v166, v166
	v_rcp_f32_e32 v167, v167
	v_rcp_f32_e32 v168, v168
	v_rcp_f32_e32 v169, v169
	v_rcp_f32_e32 v170, v170
	v_rcp_f32_e32 v171, v171
	v_mul_f32_e32 v80, v80, v164
	v_mul_f32_e32 v81, v81, v165
	v_mul_f32_e32 v82, v82, v166
	v_mul_f32_e32 v83, v83, v167
	v_mul_f32_e32 v76, v76, v168
	v_mul_f32_e32 v77, v77, v169
	v_mul_f32_e32 v78, v78, v170
	v_mul_f32_e32 v79, v79, v171
	v_cvt_pk_bf16_f32 v80, v80, v81
	v_cvt_pk_bf16_f32 v81, v82, v83
	v_cvt_pk_bf16_f32 v82, v76, v77
	v_cvt_pk_bf16_f32 v83, v78, v79
	global_store_dwordx4 v152, v[80:83], s[42:43] offset:2048 nt
	v_mul_f32_e32 v164, 0xbfb8aa3b, v72
	v_mul_f32_e32 v165, 0xbfb8aa3b, v73
	v_mul_f32_e32 v166, 0xbfb8aa3b, v74
	v_mul_f32_e32 v167, 0xbfb8aa3b, v75
	v_mul_f32_e32 v168, 0xbfb8aa3b, v68
	v_mul_f32_e32 v169, 0xbfb8aa3b, v69
	v_mul_f32_e32 v170, 0xbfb8aa3b, v70
	v_mul_f32_e32 v171, 0xbfb8aa3b, v71
	v_exp_f32_e32 v164, v164
	v_exp_f32_e32 v165, v165
	v_exp_f32_e32 v166, v166
	v_exp_f32_e32 v167, v167
	v_exp_f32_e32 v168, v168
	v_exp_f32_e32 v169, v169
	v_exp_f32_e32 v170, v170
	v_exp_f32_e32 v171, v171
	v_add_f32_e32 v164, 1.0, v164
	v_add_f32_e32 v165, 1.0, v165
	v_add_f32_e32 v166, 1.0, v166
	v_add_f32_e32 v167, 1.0, v167
	v_add_f32_e32 v168, 1.0, v168
	v_add_f32_e32 v169, 1.0, v169
	v_add_f32_e32 v170, 1.0, v170
	v_add_f32_e32 v171, 1.0, v171
	v_rcp_f32_e32 v164, v164
	v_rcp_f32_e32 v165, v165
	v_rcp_f32_e32 v166, v166
	v_rcp_f32_e32 v167, v167
	v_rcp_f32_e32 v168, v168
	v_rcp_f32_e32 v169, v169
	v_rcp_f32_e32 v170, v170
	v_rcp_f32_e32 v171, v171
	v_mul_f32_e32 v72, v72, v164
	v_mul_f32_e32 v73, v73, v165
	v_mul_f32_e32 v74, v74, v166
	v_mul_f32_e32 v75, v75, v167
	v_mul_f32_e32 v68, v68, v168
	v_mul_f32_e32 v69, v69, v169
	v_mul_f32_e32 v70, v70, v170
	v_mul_f32_e32 v71, v71, v171
	v_cvt_pk_bf16_f32 v72, v72, v73
	v_cvt_pk_bf16_f32 v73, v74, v75
	v_cvt_pk_bf16_f32 v74, v68, v69
	v_cvt_pk_bf16_f32 v75, v70, v71
	global_store_dwordx4 v152, v[72:75], s[42:43] offset:2304 nt
	v_add_u32_e32 v152, 0x3c000, v152
	v_mul_f32_e32 v164, 0xbfb8aa3b, v64
	v_mul_f32_e32 v165, 0xbfb8aa3b, v65
	v_mul_f32_e32 v166, 0xbfb8aa3b, v66
	v_mul_f32_e32 v167, 0xbfb8aa3b, v67
	v_mul_f32_e32 v168, 0xbfb8aa3b, v60
	v_mul_f32_e32 v169, 0xbfb8aa3b, v61
	v_mul_f32_e32 v170, 0xbfb8aa3b, v62
	v_mul_f32_e32 v171, 0xbfb8aa3b, v63
	v_exp_f32_e32 v164, v164
	v_exp_f32_e32 v165, v165
	v_exp_f32_e32 v166, v166
	v_exp_f32_e32 v167, v167
	v_exp_f32_e32 v168, v168
	v_exp_f32_e32 v169, v169
	v_exp_f32_e32 v170, v170
	v_exp_f32_e32 v171, v171
	v_add_f32_e32 v164, 1.0, v164
	v_add_f32_e32 v165, 1.0, v165
	v_add_f32_e32 v166, 1.0, v166
	v_add_f32_e32 v167, 1.0, v167
	v_add_f32_e32 v168, 1.0, v168
	v_add_f32_e32 v169, 1.0, v169
	v_add_f32_e32 v170, 1.0, v170
	v_add_f32_e32 v171, 1.0, v171
	v_rcp_f32_e32 v164, v164
	v_rcp_f32_e32 v165, v165
	v_rcp_f32_e32 v166, v166
	v_rcp_f32_e32 v167, v167
	v_rcp_f32_e32 v168, v168
	v_rcp_f32_e32 v169, v169
	v_rcp_f32_e32 v170, v170
	v_rcp_f32_e32 v171, v171
	v_mul_f32_e32 v64, v64, v164
	v_mul_f32_e32 v65, v65, v165
	v_mul_f32_e32 v66, v66, v166
	v_mul_f32_e32 v67, v67, v167
	v_mul_f32_e32 v60, v60, v168
	v_mul_f32_e32 v61, v61, v169
	v_mul_f32_e32 v62, v62, v170
	v_mul_f32_e32 v63, v63, v171
	v_cvt_pk_bf16_f32 v64, v64, v65
	v_cvt_pk_bf16_f32 v65, v66, v67
	v_cvt_pk_bf16_f32 v66, v60, v61
	v_cvt_pk_bf16_f32 v67, v62, v63
	global_store_dwordx4 v152, v[64:67], s[42:43] offset:2048 nt
	v_mul_f32_e32 v164, 0xbfb8aa3b, v56
	v_mul_f32_e32 v165, 0xbfb8aa3b, v57
	v_mul_f32_e32 v166, 0xbfb8aa3b, v58
	v_mul_f32_e32 v167, 0xbfb8aa3b, v59
	v_mul_f32_e32 v168, 0xbfb8aa3b, v52
	v_mul_f32_e32 v169, 0xbfb8aa3b, v53
	v_mul_f32_e32 v170, 0xbfb8aa3b, v54
	v_mul_f32_e32 v171, 0xbfb8aa3b, v55
	v_exp_f32_e32 v164, v164
	v_exp_f32_e32 v165, v165
	v_exp_f32_e32 v166, v166
	v_exp_f32_e32 v167, v167
	v_exp_f32_e32 v168, v168
	v_exp_f32_e32 v169, v169
	v_exp_f32_e32 v170, v170
	v_exp_f32_e32 v171, v171
	v_add_f32_e32 v164, 1.0, v164
	v_add_f32_e32 v165, 1.0, v165
	v_add_f32_e32 v166, 1.0, v166
	v_add_f32_e32 v167, 1.0, v167
	v_add_f32_e32 v168, 1.0, v168
	v_add_f32_e32 v169, 1.0, v169
	v_add_f32_e32 v170, 1.0, v170
	v_add_f32_e32 v171, 1.0, v171
	v_rcp_f32_e32 v164, v164
	v_rcp_f32_e32 v165, v165
	v_rcp_f32_e32 v166, v166
	v_rcp_f32_e32 v167, v167
	v_rcp_f32_e32 v168, v168
	v_rcp_f32_e32 v169, v169
	v_rcp_f32_e32 v170, v170
	v_rcp_f32_e32 v171, v171
	v_mul_f32_e32 v56, v56, v164
	v_mul_f32_e32 v57, v57, v165
	v_mul_f32_e32 v58, v58, v166
	v_mul_f32_e32 v59, v59, v167
	v_mul_f32_e32 v52, v52, v168
	v_mul_f32_e32 v53, v53, v169
	v_mul_f32_e32 v54, v54, v170
	v_mul_f32_e32 v55, v55, v171
	v_cvt_pk_bf16_f32 v56, v56, v57
	v_cvt_pk_bf16_f32 v57, v58, v59
	v_cvt_pk_bf16_f32 v58, v52, v53
	v_cvt_pk_bf16_f32 v59, v54, v55
	global_store_dwordx4 v152, v[56:59], s[42:43] offset:2304 nt
	v_add_u32_e32 v152, 0xc000, v152
	v_mul_f32_e32 v164, 0xbfb8aa3b, v48
	v_mul_f32_e32 v165, 0xbfb8aa3b, v49
	v_mul_f32_e32 v166, 0xbfb8aa3b, v50
	v_mul_f32_e32 v167, 0xbfb8aa3b, v51
	v_mul_f32_e32 v168, 0xbfb8aa3b, v44
	v_mul_f32_e32 v169, 0xbfb8aa3b, v45
	v_mul_f32_e32 v170, 0xbfb8aa3b, v46
	v_mul_f32_e32 v171, 0xbfb8aa3b, v47
	v_exp_f32_e32 v164, v164
	v_exp_f32_e32 v165, v165
	v_exp_f32_e32 v166, v166
	v_exp_f32_e32 v167, v167
	v_exp_f32_e32 v168, v168
	v_exp_f32_e32 v169, v169
	v_exp_f32_e32 v170, v170
	v_exp_f32_e32 v171, v171
	v_add_f32_e32 v164, 1.0, v164
	v_add_f32_e32 v165, 1.0, v165
	v_add_f32_e32 v166, 1.0, v166
	v_add_f32_e32 v167, 1.0, v167
	v_add_f32_e32 v168, 1.0, v168
	v_add_f32_e32 v169, 1.0, v169
	v_add_f32_e32 v170, 1.0, v170
	v_add_f32_e32 v171, 1.0, v171
	v_rcp_f32_e32 v164, v164
	v_rcp_f32_e32 v165, v165
	v_rcp_f32_e32 v166, v166
	v_rcp_f32_e32 v167, v167
	v_rcp_f32_e32 v168, v168
	v_rcp_f32_e32 v169, v169
	v_rcp_f32_e32 v170, v170
	v_rcp_f32_e32 v171, v171
	v_mul_f32_e32 v48, v48, v164
	v_mul_f32_e32 v49, v49, v165
	v_mul_f32_e32 v50, v50, v166
	v_mul_f32_e32 v51, v51, v167
	v_mul_f32_e32 v44, v44, v168
	v_mul_f32_e32 v45, v45, v169
	v_mul_f32_e32 v46, v46, v170
	v_mul_f32_e32 v47, v47, v171
	v_cvt_pk_bf16_f32 v48, v48, v49
	v_cvt_pk_bf16_f32 v49, v50, v51
	v_cvt_pk_bf16_f32 v50, v44, v45
	v_cvt_pk_bf16_f32 v51, v46, v47
	global_store_dwordx4 v152, v[48:51], s[42:43] offset:2048 nt
	v_mul_f32_e32 v164, 0xbfb8aa3b, v40
	v_mul_f32_e32 v165, 0xbfb8aa3b, v41
	v_mul_f32_e32 v166, 0xbfb8aa3b, v42
	v_mul_f32_e32 v167, 0xbfb8aa3b, v43
	v_mul_f32_e32 v168, 0xbfb8aa3b, v36
	v_mul_f32_e32 v169, 0xbfb8aa3b, v37
	v_mul_f32_e32 v170, 0xbfb8aa3b, v38
	v_mul_f32_e32 v171, 0xbfb8aa3b, v39
	v_exp_f32_e32 v164, v164
	v_exp_f32_e32 v165, v165
	v_exp_f32_e32 v166, v166
	v_exp_f32_e32 v167, v167
	v_exp_f32_e32 v168, v168
	v_exp_f32_e32 v169, v169
	v_exp_f32_e32 v170, v170
	v_exp_f32_e32 v171, v171
	v_add_f32_e32 v164, 1.0, v164
	v_add_f32_e32 v165, 1.0, v165
	v_add_f32_e32 v166, 1.0, v166
	v_add_f32_e32 v167, 1.0, v167
	v_add_f32_e32 v168, 1.0, v168
	v_add_f32_e32 v169, 1.0, v169
	v_add_f32_e32 v170, 1.0, v170
	v_add_f32_e32 v171, 1.0, v171
	v_rcp_f32_e32 v164, v164
	v_rcp_f32_e32 v165, v165
	v_rcp_f32_e32 v166, v166
	v_rcp_f32_e32 v167, v167
	v_rcp_f32_e32 v168, v168
	v_rcp_f32_e32 v169, v169
	v_rcp_f32_e32 v170, v170
	v_rcp_f32_e32 v171, v171
	v_mul_f32_e32 v40, v40, v164
	v_mul_f32_e32 v41, v41, v165
	v_mul_f32_e32 v42, v42, v166
	v_mul_f32_e32 v43, v43, v167
	v_mul_f32_e32 v36, v36, v168
	v_mul_f32_e32 v37, v37, v169
	v_mul_f32_e32 v38, v38, v170
	v_mul_f32_e32 v39, v39, v171
	v_cvt_pk_bf16_f32 v40, v40, v41
	v_cvt_pk_bf16_f32 v41, v42, v43
	v_cvt_pk_bf16_f32 v42, v36, v37
	v_cvt_pk_bf16_f32 v43, v38, v39
	global_store_dwordx4 v152, v[40:43], s[42:43] offset:2304 nt
	v_add_u32_e32 v152, 0xc000, v152
	v_mul_f32_e32 v164, 0xbfb8aa3b, v32
	v_mul_f32_e32 v165, 0xbfb8aa3b, v33
	v_mul_f32_e32 v166, 0xbfb8aa3b, v34
	v_mul_f32_e32 v167, 0xbfb8aa3b, v35
	v_mul_f32_e32 v168, 0xbfb8aa3b, v28
	v_mul_f32_e32 v169, 0xbfb8aa3b, v29
	v_mul_f32_e32 v170, 0xbfb8aa3b, v30
	v_mul_f32_e32 v171, 0xbfb8aa3b, v31
	v_exp_f32_e32 v164, v164
	v_exp_f32_e32 v165, v165
	v_exp_f32_e32 v166, v166
	v_exp_f32_e32 v167, v167
	v_exp_f32_e32 v168, v168
	v_exp_f32_e32 v169, v169
	v_exp_f32_e32 v170, v170
	v_exp_f32_e32 v171, v171
	v_add_f32_e32 v164, 1.0, v164
	v_add_f32_e32 v165, 1.0, v165
	v_add_f32_e32 v166, 1.0, v166
	v_add_f32_e32 v167, 1.0, v167
	v_add_f32_e32 v168, 1.0, v168
	v_add_f32_e32 v169, 1.0, v169
	v_add_f32_e32 v170, 1.0, v170
	v_add_f32_e32 v171, 1.0, v171
	v_rcp_f32_e32 v164, v164
	v_rcp_f32_e32 v165, v165
	v_rcp_f32_e32 v166, v166
	v_rcp_f32_e32 v167, v167
	v_rcp_f32_e32 v168, v168
	v_rcp_f32_e32 v169, v169
	v_rcp_f32_e32 v170, v170
	v_rcp_f32_e32 v171, v171
	v_mul_f32_e32 v32, v32, v164
	v_mul_f32_e32 v33, v33, v165
	v_mul_f32_e32 v34, v34, v166
	v_mul_f32_e32 v35, v35, v167
	v_mul_f32_e32 v28, v28, v168
	v_mul_f32_e32 v29, v29, v169
	v_mul_f32_e32 v30, v30, v170
	v_mul_f32_e32 v31, v31, v171
	v_cvt_pk_bf16_f32 v32, v32, v33
	v_cvt_pk_bf16_f32 v33, v34, v35
	v_cvt_pk_bf16_f32 v34, v28, v29
	v_cvt_pk_bf16_f32 v35, v30, v31
	global_store_dwordx4 v152, v[32:35], s[42:43] offset:2048 nt
	v_mul_f32_e32 v164, 0xbfb8aa3b, v24
	v_mul_f32_e32 v165, 0xbfb8aa3b, v25
	v_mul_f32_e32 v166, 0xbfb8aa3b, v26
	v_mul_f32_e32 v167, 0xbfb8aa3b, v27
	v_mul_f32_e32 v168, 0xbfb8aa3b, v20
	v_mul_f32_e32 v169, 0xbfb8aa3b, v21
	v_mul_f32_e32 v170, 0xbfb8aa3b, v22
	v_mul_f32_e32 v171, 0xbfb8aa3b, v23
	v_exp_f32_e32 v164, v164
	v_exp_f32_e32 v165, v165
	v_exp_f32_e32 v166, v166
	v_exp_f32_e32 v167, v167
	v_exp_f32_e32 v168, v168
	v_exp_f32_e32 v169, v169
	v_exp_f32_e32 v170, v170
	v_exp_f32_e32 v171, v171
	v_add_f32_e32 v164, 1.0, v164
	v_add_f32_e32 v165, 1.0, v165
	v_add_f32_e32 v166, 1.0, v166
	v_add_f32_e32 v167, 1.0, v167
	v_add_f32_e32 v168, 1.0, v168
	v_add_f32_e32 v169, 1.0, v169
	v_add_f32_e32 v170, 1.0, v170
	v_add_f32_e32 v171, 1.0, v171
	v_rcp_f32_e32 v164, v164
	v_rcp_f32_e32 v165, v165
	v_rcp_f32_e32 v166, v166
	v_rcp_f32_e32 v167, v167
	v_rcp_f32_e32 v168, v168
	v_rcp_f32_e32 v169, v169
	v_rcp_f32_e32 v170, v170
	v_rcp_f32_e32 v171, v171
	v_mul_f32_e32 v24, v24, v164
	v_mul_f32_e32 v25, v25, v165
	v_mul_f32_e32 v26, v26, v166
	v_mul_f32_e32 v27, v27, v167
	v_mul_f32_e32 v20, v20, v168
	v_mul_f32_e32 v21, v21, v169
	v_mul_f32_e32 v22, v22, v170
	v_mul_f32_e32 v23, v23, v171
	v_cvt_pk_bf16_f32 v24, v24, v25
	v_cvt_pk_bf16_f32 v25, v26, v27
	v_cvt_pk_bf16_f32 v26, v20, v21
	v_cvt_pk_bf16_f32 v27, v22, v23
	global_store_dwordx4 v152, v[24:27], s[42:43] offset:2304 nt
	v_add_u32_e32 v152, 0xc000, v152
	v_mul_f32_e32 v164, 0xbfb8aa3b, v16
	v_mul_f32_e32 v165, 0xbfb8aa3b, v17
	v_mul_f32_e32 v166, 0xbfb8aa3b, v18
	v_mul_f32_e32 v167, 0xbfb8aa3b, v19
	v_mul_f32_e32 v168, 0xbfb8aa3b, v12
	v_mul_f32_e32 v169, 0xbfb8aa3b, v13
	v_mul_f32_e32 v170, 0xbfb8aa3b, v14
	v_mul_f32_e32 v171, 0xbfb8aa3b, v15
	v_exp_f32_e32 v164, v164
	v_exp_f32_e32 v165, v165
	v_exp_f32_e32 v166, v166
	v_exp_f32_e32 v167, v167
	v_exp_f32_e32 v168, v168
	v_exp_f32_e32 v169, v169
	v_exp_f32_e32 v170, v170
	v_exp_f32_e32 v171, v171
	v_add_f32_e32 v164, 1.0, v164
	v_add_f32_e32 v165, 1.0, v165
	v_add_f32_e32 v166, 1.0, v166
	v_add_f32_e32 v167, 1.0, v167
	v_add_f32_e32 v168, 1.0, v168
	v_add_f32_e32 v169, 1.0, v169
	v_add_f32_e32 v170, 1.0, v170
	v_add_f32_e32 v171, 1.0, v171
	v_rcp_f32_e32 v164, v164
	v_rcp_f32_e32 v165, v165
	v_rcp_f32_e32 v166, v166
	v_rcp_f32_e32 v167, v167
	v_rcp_f32_e32 v168, v168
	v_rcp_f32_e32 v169, v169
	v_rcp_f32_e32 v170, v170
	v_rcp_f32_e32 v171, v171
	v_mul_f32_e32 v16, v16, v164
	v_mul_f32_e32 v17, v17, v165
	v_mul_f32_e32 v18, v18, v166
	v_mul_f32_e32 v19, v19, v167
	v_mul_f32_e32 v12, v12, v168
	v_mul_f32_e32 v13, v13, v169
	v_mul_f32_e32 v14, v14, v170
	v_mul_f32_e32 v15, v15, v171
	v_cvt_pk_bf16_f32 v16, v16, v17
	v_cvt_pk_bf16_f32 v17, v18, v19
	v_cvt_pk_bf16_f32 v18, v12, v13
	v_cvt_pk_bf16_f32 v19, v14, v15
	global_store_dwordx4 v152, v[16:19], s[42:43] offset:2048 nt
	v_mul_f32_e32 v164, 0xbfb8aa3b, v8
	v_mul_f32_e32 v165, 0xbfb8aa3b, v9
	v_mul_f32_e32 v166, 0xbfb8aa3b, v10
	v_mul_f32_e32 v167, 0xbfb8aa3b, v11
	v_mul_f32_e32 v168, 0xbfb8aa3b, v4
	v_mul_f32_e32 v169, 0xbfb8aa3b, v5
	v_mul_f32_e32 v170, 0xbfb8aa3b, v6
	v_mul_f32_e32 v171, 0xbfb8aa3b, v7
	v_exp_f32_e32 v164, v164
	v_exp_f32_e32 v165, v165
	v_exp_f32_e32 v166, v166
	v_exp_f32_e32 v167, v167
	v_exp_f32_e32 v168, v168
	v_exp_f32_e32 v169, v169
	v_exp_f32_e32 v170, v170
	v_exp_f32_e32 v171, v171
	v_add_f32_e32 v164, 1.0, v164
	v_add_f32_e32 v165, 1.0, v165
	v_add_f32_e32 v166, 1.0, v166
	v_add_f32_e32 v167, 1.0, v167
	v_add_f32_e32 v168, 1.0, v168
	v_add_f32_e32 v169, 1.0, v169
	v_add_f32_e32 v170, 1.0, v170
	v_add_f32_e32 v171, 1.0, v171
	v_rcp_f32_e32 v164, v164
	v_rcp_f32_e32 v165, v165
	v_rcp_f32_e32 v166, v166
	v_rcp_f32_e32 v167, v167
	v_rcp_f32_e32 v168, v168
	v_rcp_f32_e32 v169, v169
	v_rcp_f32_e32 v170, v170
	v_rcp_f32_e32 v171, v171
	v_mul_f32_e32 v8, v8, v164
	v_mul_f32_e32 v9, v9, v165
	v_mul_f32_e32 v10, v10, v166
	v_mul_f32_e32 v11, v11, v167
	v_mul_f32_e32 v4, v4, v168
	v_mul_f32_e32 v5, v5, v169
	v_mul_f32_e32 v6, v6, v170
	v_mul_f32_e32 v7, v7, v171
	v_cvt_pk_bf16_f32 v8, v8, v9
	v_cvt_pk_bf16_f32 v9, v10, v11
	v_cvt_pk_bf16_f32 v10, v4, v5
	v_cvt_pk_bf16_f32 v11, v6, v7
	global_store_dwordx4 v152, v[8:11], s[42:43] offset:2304 nt
	s_andn2_b64 vcc, exec, s[38:39]
	s_mov_b64 s[2:3], -1
	s_cbranch_vccnz .LBB0_430

.LBB0_679:
	v_lshl_add_u32 v168, s22, 8, v3
	v_lshl_or_b32 v166, s28, 8, v171
	s_ashr_i32 s10, s22, 3
	v_ashrrev_i32_e32 v167, 31, v166
	s_mul_hi_i32 s11, s10, 0x18000
	s_mul_i32 s10, s10, 0x18000
	s_add_u32 s10, s2, s10
	s_addc_u32 s11, s3, s11
	v_lshl_add_u64 v[128:129], v[166:167], 2, s[10:11]
	v_lshl_add_u32 v173, v168, 10, v166
	v_lshlrev_b32_e32 v173, 2, v173
	v_mov_b32_e32 v174, v173
	global_load_dwordx4 v[144:147], v[128:129], off
	global_load_dwordx4 v[136:139], v[128:129], off offset:64
	global_load_dwordx4 v[132:135], v[128:129], off offset:512
	s_nop 0
	global_load_dwordx4 v[128:131], v[128:129], off offset:576
	s_and_b64 vcc, exec, s[38:39]
	s_mov_b32 s23, 0xffff
	global_load_dwordx4 v[190:193], v173, s[42:43]
	global_load_dwordx4 v[194:197], v173, s[42:43] offset:64
	global_load_dwordx4 v[198:201], v173, s[42:43] offset:512
	global_load_dwordx4 v[202:205], v173, s[42:43] offset:576
	v_add_u32_e32 v173, 0x10000, v173
	global_load_dwordx4 v[206:209], v173, s[42:43]
	global_load_dwordx4 v[210:213], v173, s[42:43] offset:64
	global_load_dwordx4 v[214:217], v173, s[42:43] offset:512
	global_load_dwordx4 v[218:221], v173, s[42:43] offset:576
	v_add_u32_e32 v173, 0x10000, v173
	global_load_dwordx4 v[222:225], v173, s[42:43]
	global_load_dwordx4 v[226:229], v173, s[42:43] offset:64
	global_load_dwordx4 v[230:233], v173, s[42:43] offset:512
	global_load_dwordx4 v[234:237], v173, s[42:43] offset:576
	v_add_u32_e32 v173, 0x10000, v173
	global_load_dwordx4 v[238:241], v173, s[42:43]
	global_load_dwordx4 v[242:245], v173, s[42:43] offset:64
	global_load_dwordx4 v[246:249], v173, s[42:43] offset:512
	global_load_dwordx4 v[164:167], v173, s[42:43] offset:576
	s_waitcnt vmcnt(15)
	v_pk_fma_f32 v[142:143], v[142:143], v[146:147], v[192:193]
	v_pk_fma_f32 v[140:141], v[140:141], v[144:145], v[190:191]
	global_store_dwordx4 v174, v[140:143], s[60:61] nt
	v_add_u32_e32 v173, 0x50000, v173
	global_load_dwordx4 v[190:193], v173, s[42:43]
	s_waitcnt vmcnt(16)
	v_pk_fma_f32 v[126:127], v[126:127], v[138:139], v[196:197]
	v_pk_fma_f32 v[124:125], v[124:125], v[136:137], v[194:195]
	global_store_dwordx4 v174, v[124:127], s[60:61] offset:64 nt
	global_load_dwordx4 v[194:197], v173, s[42:43] offset:64
	s_waitcnt vmcnt(17)
	v_pk_fma_f32 v[122:123], v[122:123], v[134:135], v[200:201]
	v_pk_fma_f32 v[120:121], v[120:121], v[132:133], v[198:199]
	global_store_dwordx4 v174, v[120:123], s[60:61] offset:512 nt
	global_load_dwordx4 v[198:201], v173, s[42:43] offset:512
	s_waitcnt vmcnt(18)
	v_pk_fma_f32 v[118:119], v[118:119], v[130:131], v[204:205]
	v_pk_fma_f32 v[116:117], v[116:117], v[128:129], v[202:203]
	global_store_dwordx4 v174, v[116:119], s[60:61] offset:576 nt
	global_load_dwordx4 v[202:205], v173, s[42:43] offset:576
	v_add_u32_e32 v174, 0x10000, v174
	s_waitcnt vmcnt(19)
	v_pk_fma_f32 v[114:115], v[114:115], v[146:147], v[208:209]
	v_pk_fma_f32 v[112:113], v[112:113], v[144:145], v[206:207]
	global_store_dwordx4 v174, v[112:115], s[60:61] nt
	v_add_u32_e32 v173, 0x10000, v173
	global_load_dwordx4 v[206:209], v173, s[42:43]
	s_waitcnt vmcnt(20)
	v_pk_fma_f32 v[110:111], v[110:111], v[138:139], v[212:213]
	v_pk_fma_f32 v[108:109], v[108:109], v[136:137], v[210:211]
	global_store_dwordx4 v174, v[108:111], s[60:61] offset:64 nt
	global_load_dwordx4 v[210:213], v173, s[42:43] offset:64
	s_waitcnt vmcnt(21)
	v_pk_fma_f32 v[106:107], v[106:107], v[134:135], v[216:217]
	v_pk_fma_f32 v[104:105], v[104:105], v[132:133], v[214:215]
	global_store_dwordx4 v174, v[104:107], s[60:61] offset:512 nt
	global_load_dwordx4 v[214:217], v173, s[42:43] offset:512
	s_waitcnt vmcnt(22)
	v_pk_fma_f32 v[102:103], v[102:103], v[130:131], v[220:221]
	v_pk_fma_f32 v[100:101], v[100:101], v[128:129], v[218:219]
	global_store_dwordx4 v174, v[100:103], s[60:61] offset:576 nt
	global_load_dwordx4 v[218:221], v173, s[42:43] offset:576
	v_add_u32_e32 v174, 0x10000, v174
	s_waitcnt vmcnt(23)
	v_pk_fma_f32 v[98:99], v[98:99], v[146:147], v[224:225]
	v_pk_fma_f32 v[96:97], v[96:97], v[144:145], v[222:223]
	global_store_dwordx4 v174, v[96:99], s[60:61] nt
	v_add_u32_e32 v173, 0x10000, v173
	global_load_dwordx4 v[222:225], v173, s[42:43]
	s_waitcnt vmcnt(24)
	v_pk_fma_f32 v[94:95], v[94:95], v[138:139], v[228:229]
	v_pk_fma_f32 v[92:93], v[92:93], v[136:137], v[226:227]
	global_store_dwordx4 v174, v[92:95], s[60:61] offset:64 nt
	global_load_dwordx4 v[226:229], v173, s[42:43] offset:64
	s_waitcnt vmcnt(25)
	v_pk_fma_f32 v[90:91], v[90:91], v[134:135], v[232:233]
	v_pk_fma_f32 v[88:89], v[88:89], v[132:133], v[230:231]
	global_store_dwordx4 v174, v[88:91], s[60:61] offset:512 nt
	global_load_dwordx4 v[230:233], v173, s[42:43] offset:512
	s_waitcnt vmcnt(26)
	v_pk_fma_f32 v[86:87], v[86:87], v[130:131], v[236:237]
	v_pk_fma_f32 v[84:85], v[84:85], v[128:129], v[234:235]
	global_store_dwordx4 v174, v[84:87], s[60:61] offset:576 nt
	global_load_dwordx4 v[234:237], v173, s[42:43] offset:576
	v_add_u32_e32 v174, 0x10000, v174
	s_waitcnt vmcnt(27)
	v_pk_fma_f32 v[82:83], v[82:83], v[146:147], v[240:241]
	v_pk_fma_f32 v[80:81], v[80:81], v[144:145], v[238:239]
	global_store_dwordx4 v174, v[80:83], s[60:61] nt
	v_add_u32_e32 v173, 0x10000, v173
	global_load_dwordx4 v[238:241], v173, s[42:43]
	s_waitcnt vmcnt(28)
	v_pk_fma_f32 v[78:79], v[78:79], v[138:139], v[244:245]
	v_pk_fma_f32 v[76:77], v[76:77], v[136:137], v[242:243]
	global_store_dwordx4 v174, v[76:79], s[60:61] offset:64 nt
	global_load_dwordx4 v[242:245], v173, s[42:43] offset:64
	s_waitcnt vmcnt(29)
	v_pk_fma_f32 v[74:75], v[74:75], v[134:135], v[248:249]
	v_pk_fma_f32 v[72:73], v[72:73], v[132:133], v[246:247]
	global_store_dwordx4 v174, v[72:75], s[60:61] offset:512 nt
	global_load_dwordx4 v[246:249], v173, s[42:43] offset:512
	s_waitcnt vmcnt(30)
	v_pk_fma_f32 v[70:71], v[70:71], v[130:131], v[166:167]
	v_pk_fma_f32 v[68:69], v[68:69], v[128:129], v[164:165]
	global_store_dwordx4 v174, v[68:71], s[60:61] offset:576 nt
	global_load_dwordx4 v[164:167], v173, s[42:43] offset:576
	v_add_u32_e32 v174, 0x50000, v174
	s_waitcnt vmcnt(30)
	v_pk_fma_f32 v[66:67], v[66:67], v[146:147], v[192:193]
	v_pk_fma_f32 v[64:65], v[64:65], v[144:145], v[190:191]
	global_store_dwordx4 v174, v[64:67], s[60:61] nt
	s_waitcnt vmcnt(29)
	v_pk_fma_f32 v[62:63], v[62:63], v[138:139], v[196:197]
	v_pk_fma_f32 v[60:61], v[60:61], v[136:137], v[194:195]
	global_store_dwordx4 v174, v[60:63], s[60:61] offset:64 nt
	s_waitcnt vmcnt(28)
	v_pk_fma_f32 v[58:59], v[58:59], v[134:135], v[200:201]
	v_pk_fma_f32 v[56:57], v[56:57], v[132:133], v[198:199]
	global_store_dwordx4 v174, v[56:59], s[60:61] offset:512 nt
	s_waitcnt vmcnt(27)
	v_pk_fma_f32 v[54:55], v[54:55], v[130:131], v[204:205]
	v_pk_fma_f32 v[52:53], v[52:53], v[128:129], v[202:203]
	global_store_dwordx4 v174, v[52:55], s[60:61] offset:576 nt
	v_add_u32_e32 v174, 0x10000, v174
	s_waitcnt vmcnt(26)
	v_pk_fma_f32 v[50:51], v[50:51], v[146:147], v[208:209]
	v_pk_fma_f32 v[48:49], v[48:49], v[144:145], v[206:207]
	global_store_dwordx4 v174, v[48:51], s[60:61] nt
	s_waitcnt vmcnt(25)
	v_pk_fma_f32 v[46:47], v[46:47], v[138:139], v[212:213]
	v_pk_fma_f32 v[44:45], v[44:45], v[136:137], v[210:211]
	global_store_dwordx4 v174, v[44:47], s[60:61] offset:64 nt
	s_waitcnt vmcnt(24)
	v_pk_fma_f32 v[42:43], v[42:43], v[134:135], v[216:217]
	v_pk_fma_f32 v[40:41], v[40:41], v[132:133], v[214:215]
	global_store_dwordx4 v174, v[40:43], s[60:61] offset:512 nt
	s_waitcnt vmcnt(23)
	v_pk_fma_f32 v[38:39], v[38:39], v[130:131], v[220:221]
	v_pk_fma_f32 v[36:37], v[36:37], v[128:129], v[218:219]
	global_store_dwordx4 v174, v[36:39], s[60:61] offset:576 nt
	v_add_u32_e32 v174, 0x10000, v174
	s_waitcnt vmcnt(22)
	v_pk_fma_f32 v[34:35], v[34:35], v[146:147], v[224:225]
	v_pk_fma_f32 v[32:33], v[32:33], v[144:145], v[222:223]
	global_store_dwordx4 v174, v[32:35], s[60:61] nt
	s_waitcnt vmcnt(21)
	v_pk_fma_f32 v[30:31], v[30:31], v[138:139], v[228:229]
	v_pk_fma_f32 v[28:29], v[28:29], v[136:137], v[226:227]
	global_store_dwordx4 v174, v[28:31], s[60:61] offset:64 nt
	s_waitcnt vmcnt(20)
	v_pk_fma_f32 v[26:27], v[26:27], v[134:135], v[232:233]
	v_pk_fma_f32 v[24:25], v[24:25], v[132:133], v[230:231]
	global_store_dwordx4 v174, v[24:27], s[60:61] offset:512 nt
	s_waitcnt vmcnt(19)
	v_pk_fma_f32 v[22:23], v[22:23], v[130:131], v[236:237]
	v_pk_fma_f32 v[20:21], v[20:21], v[128:129], v[234:235]
	global_store_dwordx4 v174, v[20:23], s[60:61] offset:576 nt
	v_add_u32_e32 v174, 0x10000, v174
	s_waitcnt vmcnt(18)
	v_pk_fma_f32 v[18:19], v[18:19], v[146:147], v[240:241]
	v_pk_fma_f32 v[16:17], v[16:17], v[144:145], v[238:239]
	global_store_dwordx4 v174, v[16:19], s[60:61] nt
	s_waitcnt vmcnt(17)
	v_pk_fma_f32 v[14:15], v[14:15], v[138:139], v[244:245]
	v_pk_fma_f32 v[12:13], v[12:13], v[136:137], v[242:243]
	global_store_dwordx4 v174, v[12:15], s[60:61] offset:64 nt
	s_waitcnt vmcnt(16)
	v_pk_fma_f32 v[10:11], v[10:11], v[134:135], v[248:249]
	v_pk_fma_f32 v[8:9], v[8:9], v[132:133], v[246:247]
	global_store_dwordx4 v174, v[8:11], s[60:61] offset:512 nt
	s_waitcnt vmcnt(15)
	v_pk_fma_f32 v[6:7], v[6:7], v[130:131], v[166:167]
	v_pk_fma_f32 v[4:5], v[4:5], v[128:129], v[164:165]
	global_store_dwordx4 v174, v[4:7], s[60:61] offset:576 nt
	s_mov_b64 s[10:11], -1
	s_cbranch_vccnz .LBB0_664
	s_andn2_b64 vcc, exec, s[44:45]
	s_cbranch_vccnz .LBB0_663
	s_barrier
	s_branch .LBB0_663
